# GEMM main loops: per-segment s_setprio 1/0 toggles removed; the one static priority raise of waves 4-7 set in attention now persists through the GEMM phases
# baseline (speedup 1.0000x reference)
; #define PG8_STAGE(bufoff, gbase, voff) do { _Pragma("unroll") for (int _i = 0; _i < 2; ++_i) \
;         __builtin_amdgcn_global_load_lds((const unsigned*)((const char*)(gbase) + (voff)[_i]), (LAS unsigned*)(lds + (bufoff) + ldsw + _i * 8192), 16, 0, 0); } while (0)
; #define PG8_LDA(dst, b, h) do { _Pragma("unroll") for (int m = 0; m < 4; ++m) _Pragma("unroll") for (int k = 0; k < 2; ++k) dst[m][k] = *(const LAS bf16x8*)(lds + PG8_SA(b, h) + aoff + m * 2048 + k * 1024); } while (0)
; #define PG8_LDB(dst, b, h) do { _Pragma("unroll") for (int n = 0; n < 2; ++n) _Pragma("unroll") for (int k = 0; k < 2; ++k) dst[n][k] = *(const LAS bf16x8*)(lds + PG8_SB(b, h) + boff + n * 2048 + k * 1024); } while (0)
; #define PG8_MMA(ai, bj, At, Bt) do { __builtin_amdgcn_s_setprio(1); _Pragma("unroll") for (int m = 0; m < 4; ++m) _Pragma("unroll") for (int n = 0; n < 2; ++n) _Pragma("unroll") for (int k = 0; k < 2; ++k) \
;         acc[ai][bj][m][n] = __builtin_amdgcn_mfma_f32_16x16x32_bf16(Bt[n][k], At[m][k], acc[ai][bj][m][n], 0, 0, 0); __builtin_amdgcn_s_setprio(0); } while (0)
; #define PG8_WAIT_V(n) asm volatile("s_waitcnt vmcnt(" #n ")" ::: "memory")
; template <class Epi>
; __device__ __forceinline__ void gemm_phase(LAS unsigned char* lds, const Gemm g, const StaticOrder& S, const Epi& E) {
;     ...
;             const bool last = (t == nt - 2);
;             const char* a1 = cA + (size_t)(t + 1) * kstep;
;             const char* a2 = last ? nA : cA + (size_t)(t + 2) * kstep; const char* b2 = last ? nB : cB + (size_t)(t + 2) * kstep;
;             const char* a3 = a2 + kstep; const char* b3 = b2 + kstep;
;             PG8_LDB(B0, 0, 0); PG8_LDB(B1, 0, 1); PG8_SCHED; PG8_LDA(At, 0, 0); PG8_STAGE(PG8_SA(1, 1), a1 + hstepA, voffA);
;             PG8_WAIT_V(8); PG8_WAIT_L(0); PG8_BAR; PG8_MMA(0, 0, At, B0); PG8_MMA(0, 1, At, B1); PG8_BAR; PG8_SCHED;
;             PG8_LDA(At, 0, 1); PG8_STAGE(PG8_SB(0, 0), b2, voffB); PG8_STAGE(PG8_SB(0, 1), b2 + hstepB, voffB); PG8_STAGE(PG8_SA(0, 0), a2, voffA);
;             PG8_WAIT_V(8); PG8_WAIT_L(0); PG8_BAR; PG8_MMA(1, 0, At, B0); PG8_MMA(1, 1, At, B1); PG8_BAR; PG8_SCHED;
;             PG8_LDB(B0, 1, 0); PG8_LDB(B1, 1, 1); PG8_SCHED; PG8_LDA(At, 1, 0); PG8_STAGE(PG8_SA(0, 1), a2 + hstepA, voffA);
;             PG8_WAIT_V(8); PG8_WAIT_L(0); PG8_BAR; PG8_MMA(0, 0, At, B0); PG8_MMA(0, 1, At, B1); PG8_BAR; PG8_SCHED;
.LBB0_325:
	s_add_u32 s48, s30, 0xfff80080
	s_addc_u32 s49, s31, -1
	s_add_i32 s85, 0, 0x10000
	s_cmp_eq_u32 s84, 28
	s_cselect_b32 s81, s0, s49
	s_cselect_b32 s80, s23, s48
	v_add_u32_e32 v0, s85, v141
	s_cselect_b32 s79, s21, s83
	s_cselect_b32 s78, s36, s82
	s_add_i32 s87, 0, 0x14000
	ds_read_b128 v[152:155], v0
	ds_read_b128 v[156:159], v0 offset:1024
	ds_read_b128 v[162:165], v0 offset:2048
	ds_read_b128 v[166:169], v0 offset:3072
	v_add_u32_e32 v0, s87, v141
	ds_read_b128 v[170:173], v0
	ds_read_b128 v[174:177], v0 offset:1024
	ds_read_b128 v[178:181], v0 offset:2048
	ds_read_b128 v[182:185], v0 offset:3072
	v_lshl_add_u64 v[196:197], s[30:31], 0, v[148:149]
	s_add_i32 m0, s39, 0xc000
	ds_read_b128 v[186:189], v160
	ds_read_b128 v[190:193], v160 offset:1024
	ds_read_b128 v[200:203], v160 offset:2048
	ds_read_b128 v[204:207], v160 offset:3072
	ds_read_b128 v[208:211], v160 offset:4096
	ds_read_b128 v[212:215], v160 offset:5120
	ds_read_b128 v[216:219], v160 offset:6144
	ds_read_b128 v[220:223], v160 offset:7168
	global_load_lds_dwordx4 v[196:197], off
	v_lshl_add_u64 v[196:197], s[30:31], 0, v[150:151]
	s_add_i32 m0, s39, 0xe000
	s_nop 0
	global_load_lds_dwordx4 v[196:197], off
	s_waitcnt vmcnt(8)
	s_waitcnt lgkmcnt(0)
	s_barrier
	s_nop 0
	s_waitcnt lgkmcnt(0)
	v_mfma_f32_16x16x32_bf16 v[126:129], v[152:155], v[186:189], v[126:129]
	v_mfma_f32_16x16x32_bf16 v[122:125], v[162:165], v[186:189], v[122:125]
	v_mfma_f32_16x16x32_bf16 v[110:113], v[152:155], v[200:203], v[110:113]
	v_mfma_f32_16x16x32_bf16 v[106:109], v[162:165], v[200:203], v[106:109]
	v_mfma_f32_16x16x32_bf16 v[94:97], v[152:155], v[208:211], v[94:97]
	v_mfma_f32_16x16x32_bf16 v[90:93], v[162:165], v[208:211], v[90:93]
	v_mfma_f32_16x16x32_bf16 v[78:81], v[152:155], v[216:219], v[78:81]
	v_mfma_f32_16x16x32_bf16 v[74:77], v[162:165], v[216:219], v[74:77]
	v_mfma_f32_16x16x32_bf16 v[126:129], v[156:159], v[190:193], v[126:129]
	v_mfma_f32_16x16x32_bf16 v[122:125], v[166:169], v[190:193], v[122:125]
	v_mfma_f32_16x16x32_bf16 v[110:113], v[156:159], v[204:207], v[110:113]
	v_mfma_f32_16x16x32_bf16 v[106:109], v[166:169], v[204:207], v[106:109]
	v_mfma_f32_16x16x32_bf16 v[94:97], v[156:159], v[212:215], v[94:97]
	v_mfma_f32_16x16x32_bf16 v[90:93], v[166:169], v[212:215], v[90:93]
	v_mfma_f32_16x16x32_bf16 v[78:81], v[156:159], v[220:223], v[78:81]
	v_mfma_f32_16x16x32_bf16 v[74:77], v[166:169], v[220:223], v[74:77]
	s_nop 0
	s_nop 0
	v_mfma_f32_16x16x32_bf16 v[118:121], v[170:173], v[186:189], v[118:121]
	v_mfma_f32_16x16x32_bf16 v[114:117], v[178:181], v[186:189], v[114:117]
	v_mfma_f32_16x16x32_bf16 v[102:105], v[170:173], v[200:203], v[102:105]
	v_mfma_f32_16x16x32_bf16 v[98:101], v[178:181], v[200:203], v[98:101]
	v_mfma_f32_16x16x32_bf16 v[86:89], v[170:173], v[208:211], v[86:89]
	v_mfma_f32_16x16x32_bf16 v[82:85], v[178:181], v[208:211], v[82:85]
	v_mfma_f32_16x16x32_bf16 v[70:73], v[170:173], v[216:219], v[70:73]
	v_mfma_f32_16x16x32_bf16 v[66:69], v[178:181], v[216:219], v[66:69]
	v_mfma_f32_16x16x32_bf16 v[118:121], v[174:177], v[190:193], v[118:121]
	v_mfma_f32_16x16x32_bf16 v[114:117], v[182:185], v[190:193], v[114:117]
	v_mfma_f32_16x16x32_bf16 v[102:105], v[174:177], v[204:207], v[102:105]
	v_mfma_f32_16x16x32_bf16 v[98:101], v[182:185], v[204:207], v[98:101]
	v_mfma_f32_16x16x32_bf16 v[86:89], v[174:177], v[212:215], v[86:89]
	v_mfma_f32_16x16x32_bf16 v[82:85], v[182:185], v[212:215], v[82:85]
	v_mfma_f32_16x16x32_bf16 v[70:73], v[174:177], v[220:223], v[70:73]
	v_mfma_f32_16x16x32_bf16 v[66:69], v[182:185], v[220:223], v[66:69]
	s_nop 0
	s_barrier
	s_add_i32 s48, s85, s38
	v_lshl_add_u64 v[196:197], s[78:79], 0, v[132:133]
	s_mov_b32 m0, s48
	ds_read_b128 v[186:189], v160 offset:16384
	ds_read_b128 v[190:193], v160 offset:17408
	ds_read_b128 v[200:203], v160 offset:18432
	ds_read_b128 v[204:207], v160 offset:19456
	ds_read_b128 v[208:211], v160 offset:20480
	ds_read_b128 v[212:215], v160 offset:21504
	ds_read_b128 v[216:219], v160 offset:22528
	ds_read_b128 v[220:223], v160 offset:23552
	global_load_lds_dwordx4 v[196:197], off
	s_add_i32 m0, s48, 0x2000
	s_add_u32 s48, s78, 0x80000
	v_lshl_add_u64 v[198:199], s[78:79], 0, v[136:137]
	s_addc_u32 s49, s79, 0
	s_add_i32 s85, s87, s38
	global_load_lds_dwordx4 v[198:199], off
	v_lshl_add_u64 v[224:225], s[48:49], 0, v[132:133]
	s_mov_b32 m0, s85
	v_lshl_add_u64 v[230:231], s[80:81], 0, v[134:135]
	global_load_lds_dwordx4 v[224:225], off
	v_lshl_add_u64 v[224:225], s[48:49], 0, v[136:137]
	s_add_i32 m0, s85, 0x2000
	s_nop 0
	global_load_lds_dwordx4 v[224:225], off
	v_lshl_add_u64 v[224:225], s[80:81], 0, v[130:131]
	s_mov_b32 m0, s39
	s_nop 0
	global_load_lds_dwordx4 v[224:225], off
	s_mov_b32 m0, s43
	s_nop 0
	global_load_lds_dwordx4 v[230:231], off
	s_waitcnt vmcnt(8)
	s_waitcnt lgkmcnt(0)
	s_barrier
; #define PG8_STAGE(bufoff, gbase, voff) do { _Pragma("unroll") for (int _i = 0; _i < 2; ++_i) \
;         __builtin_amdgcn_global_load_lds((const unsigned*)((const char*)(gbase) + (voff)[_i]), (LAS unsigned*)(lds + (bufoff) + ldsw + _i * 8192), 16, 0, 0); } while (0)
; #define PG8_LDA(dst, b, h) do { _Pragma("unroll") for (int m = 0; m < 4; ++m) _Pragma("unroll") for (int k = 0; k < 2; ++k) dst[m][k] = *(const LAS bf16x8*)(lds + PG8_SA(b, h) + aoff + m * 2048 + k * 1024); } while (0)
; #define PG8_LDB(dst, b, h) do { _Pragma("unroll") for (int n = 0; n < 2; ++n) _Pragma("unroll") for (int k = 0; k < 2; ++k) dst[n][k] = *(const LAS bf16x8*)(lds + PG8_SB(b, h) + boff + n * 2048 + k * 1024); } while (0)
; #define PG8_MMA(ai, bj, At, Bt) do { __builtin_amdgcn_s_setprio(1); _Pragma("unroll") for (int m = 0; m < 4; ++m) _Pragma("unroll") for (int n = 0; n < 2; ++n) _Pragma("unroll") for (int k = 0; k < 2; ++k) \
;         acc[ai][bj][m][n] = __builtin_amdgcn_mfma_f32_16x16x32_bf16(Bt[n][k], At[m][k], acc[ai][bj][m][n], 0, 0, 0); __builtin_amdgcn_s_setprio(0); } while (0)
; #define PG8_WAIT_V(n) asm volatile("s_waitcnt vmcnt(" #n ")" ::: "memory")
; #define PG8_WAIT_L(n) asm volatile("s_waitcnt lgkmcnt(" #n ")" ::: "memory")
; #define PG8_BAR __builtin_amdgcn_s_barrier()
; #define PG8_SCHED __builtin_amdgcn_sched_barrier(0)
; template <class Epi>
; __device__ __forceinline__ void gemm_phase(LAS unsigned char* lds, const Gemm g, const StaticOrder& S, const Epi& E) {
;     ...
;             PG8_WAIT_V(8); PG8_WAIT_L(0); PG8_BAR; PG8_MMA(0, 0, At, B0); PG8_MMA(0, 1, At, B1); PG8_BAR; PG8_SCHED;
;             PG8_LDA(At, 0, 1); PG8_STAGE(PG8_SB(0, 0), b2, voffB); PG8_STAGE(PG8_SB(0, 1), b2 + hstepB, voffB); PG8_STAGE(PG8_SA(0, 0), a2, voffA);
;             PG8_WAIT_V(8); PG8_WAIT_L(0); PG8_BAR; PG8_MMA(1, 0, At, B0); PG8_MMA(1, 1, At, B1); PG8_BAR; PG8_SCHED;
;             PG8_LDB(B0, 1, 0); PG8_LDB(B1, 1, 1); PG8_SCHED; PG8_LDA(At, 1, 0); PG8_STAGE(PG8_SA(0, 1), a2 + hstepA, voffA);
;             PG8_WAIT_V(8); PG8_WAIT_L(0); PG8_BAR; PG8_MMA(0, 0, At, B0); PG8_MMA(0, 1, At, B1); PG8_BAR; PG8_SCHED;
;             PG8_LDA(At, 1, 1); PG8_STAGE(PG8_SB(1, 0), b3, voffB); PG8_STAGE(PG8_SB(1, 1), b3 + hstepB, voffB); PG8_STAGE(PG8_SA(1, 0), a3, voffA);
	s_nop 0
	s_waitcnt lgkmcnt(0)
	v_mfma_f32_16x16x32_bf16 v[62:65], v[152:155], v[186:189], v[62:65]
	v_mfma_f32_16x16x32_bf16 v[58:61], v[162:165], v[186:189], v[58:61]
	v_mfma_f32_16x16x32_bf16 v[46:49], v[152:155], v[200:203], v[46:49]
	v_mfma_f32_16x16x32_bf16 v[42:45], v[162:165], v[200:203], v[42:45]
	v_mfma_f32_16x16x32_bf16 v[30:33], v[152:155], v[208:211], v[30:33]
	v_mfma_f32_16x16x32_bf16 v[26:29], v[162:165], v[208:211], v[26:29]
	v_mfma_f32_16x16x32_bf16 v[14:17], v[152:155], v[216:219], v[14:17]
	v_mfma_f32_16x16x32_bf16 v[10:13], v[162:165], v[216:219], v[10:13]
	v_mfma_f32_16x16x32_bf16 v[62:65], v[156:159], v[190:193], v[62:65]
	v_mfma_f32_16x16x32_bf16 v[58:61], v[166:169], v[190:193], v[58:61]
	v_mfma_f32_16x16x32_bf16 v[46:49], v[156:159], v[204:207], v[46:49]
	v_mfma_f32_16x16x32_bf16 v[42:45], v[166:169], v[204:207], v[42:45]
	v_mfma_f32_16x16x32_bf16 v[30:33], v[156:159], v[212:215], v[30:33]
	v_mfma_f32_16x16x32_bf16 v[26:29], v[166:169], v[212:215], v[26:29]
	v_mfma_f32_16x16x32_bf16 v[14:17], v[156:159], v[220:223], v[14:17]
	v_mfma_f32_16x16x32_bf16 v[10:13], v[166:169], v[220:223], v[10:13]
	s_nop 0
	s_nop 0
	v_mfma_f32_16x16x32_bf16 v[54:57], v[170:173], v[186:189], v[54:57]
	v_mfma_f32_16x16x32_bf16 v[50:53], v[178:181], v[186:189], v[50:53]
	v_mfma_f32_16x16x32_bf16 v[38:41], v[170:173], v[200:203], v[38:41]
	v_mfma_f32_16x16x32_bf16 v[34:37], v[178:181], v[200:203], v[34:37]
	v_mfma_f32_16x16x32_bf16 v[22:25], v[170:173], v[208:211], v[22:25]
	v_mfma_f32_16x16x32_bf16 v[18:21], v[178:181], v[208:211], v[18:21]
	v_mfma_f32_16x16x32_bf16 v[6:9], v[170:173], v[216:219], v[6:9]
	v_mfma_f32_16x16x32_bf16 v[2:5], v[178:181], v[216:219], v[2:5]
	v_mfma_f32_16x16x32_bf16 v[54:57], v[174:177], v[190:193], v[54:57]
	v_mfma_f32_16x16x32_bf16 v[50:53], v[182:185], v[190:193], v[50:53]
	v_mfma_f32_16x16x32_bf16 v[38:41], v[174:177], v[204:207], v[38:41]
	v_mfma_f32_16x16x32_bf16 v[34:37], v[182:185], v[204:207], v[34:37]
	v_mfma_f32_16x16x32_bf16 v[22:25], v[174:177], v[212:215], v[22:25]
	v_mfma_f32_16x16x32_bf16 v[18:21], v[182:185], v[212:215], v[18:21]
	v_mfma_f32_16x16x32_bf16 v[6:9], v[174:177], v[220:223], v[6:9]
	v_mfma_f32_16x16x32_bf16 v[2:5], v[182:185], v[220:223], v[2:5]
	s_nop 0
	s_barrier
	s_add_i32 s85, 0, 0x18000
	v_add_u32_e32 v0, s85, v141
	s_add_i32 s87, 0, 0x1c000
	ds_read_b128 v[152:155], v0
	ds_read_b128 v[156:159], v0 offset:1024
	ds_read_b128 v[162:165], v0 offset:2048
	ds_read_b128 v[166:169], v0 offset:3072
	v_add_u32_e32 v0, s87, v141
	ds_read_b128 v[170:173], v0
	ds_read_b128 v[174:177], v0 offset:1024
	ds_read_b128 v[178:181], v0 offset:2048
	ds_read_b128 v[182:185], v0 offset:3072
	s_add_u32 s48, s80, 0x80000
	s_addc_u32 s49, s81, 0
	s_mov_b32 m0, s60
	v_lshl_add_u64 v[232:233], s[48:49], 0, v[130:131]
	ds_read_b128 v[186:189], v160 offset:32768
	ds_read_b128 v[190:193], v160 offset:33792
	ds_read_b128 v[200:203], v160 offset:34816
	ds_read_b128 v[204:207], v160 offset:35840
	ds_read_b128 v[208:211], v160 offset:36864
	ds_read_b128 v[212:215], v160 offset:37888
	ds_read_b128 v[216:219], v160 offset:38912
	ds_read_b128 v[220:223], v160 offset:39936
	global_load_lds_dwordx4 v[232:233], off
	v_lshl_add_u64 v[232:233], s[48:49], 0, v[134:135]
	s_mov_b32 m0, s61
	s_nop 0
	global_load_lds_dwordx4 v[232:233], off
	s_waitcnt vmcnt(8)
	s_waitcnt lgkmcnt(0)
	s_barrier
	s_nop 0
	s_waitcnt lgkmcnt(0)
	v_mfma_f32_16x16x32_bf16 v[126:129], v[152:155], v[186:189], v[126:129]
	v_mfma_f32_16x16x32_bf16 v[122:125], v[162:165], v[186:189], v[122:125]
	v_mfma_f32_16x16x32_bf16 v[110:113], v[152:155], v[200:203], v[110:113]
	v_mfma_f32_16x16x32_bf16 v[106:109], v[162:165], v[200:203], v[106:109]
	v_mfma_f32_16x16x32_bf16 v[94:97], v[152:155], v[208:211], v[94:97]
	v_mfma_f32_16x16x32_bf16 v[90:93], v[162:165], v[208:211], v[90:93]
	v_mfma_f32_16x16x32_bf16 v[78:81], v[152:155], v[216:219], v[78:81]
	v_mfma_f32_16x16x32_bf16 v[74:77], v[162:165], v[216:219], v[74:77]
	v_mfma_f32_16x16x32_bf16 v[126:129], v[156:159], v[190:193], v[126:129]
	v_mfma_f32_16x16x32_bf16 v[122:125], v[166:169], v[190:193], v[122:125]
	v_mfma_f32_16x16x32_bf16 v[110:113], v[156:159], v[204:207], v[110:113]
	v_mfma_f32_16x16x32_bf16 v[106:109], v[166:169], v[204:207], v[106:109]
	v_mfma_f32_16x16x32_bf16 v[94:97], v[156:159], v[212:215], v[94:97]
	v_mfma_f32_16x16x32_bf16 v[90:93], v[166:169], v[212:215], v[90:93]
	v_mfma_f32_16x16x32_bf16 v[78:81], v[156:159], v[220:223], v[78:81]
	v_mfma_f32_16x16x32_bf16 v[74:77], v[166:169], v[220:223], v[74:77]
	s_nop 0
	s_nop 0
	v_mfma_f32_16x16x32_bf16 v[118:121], v[170:173], v[186:189], v[118:121]
	v_mfma_f32_16x16x32_bf16 v[114:117], v[178:181], v[186:189], v[114:117]
	v_mfma_f32_16x16x32_bf16 v[102:105], v[170:173], v[200:203], v[102:105]
	v_mfma_f32_16x16x32_bf16 v[98:101], v[178:181], v[200:203], v[98:101]
	v_mfma_f32_16x16x32_bf16 v[86:89], v[170:173], v[208:211], v[86:89]
	v_mfma_f32_16x16x32_bf16 v[82:85], v[178:181], v[208:211], v[82:85]
	v_mfma_f32_16x16x32_bf16 v[70:73], v[170:173], v[216:219], v[70:73]
	v_mfma_f32_16x16x32_bf16 v[66:69], v[178:181], v[216:219], v[66:69]
	v_mfma_f32_16x16x32_bf16 v[118:121], v[174:177], v[190:193], v[118:121]
	v_mfma_f32_16x16x32_bf16 v[114:117], v[182:185], v[190:193], v[114:117]
	v_mfma_f32_16x16x32_bf16 v[102:105], v[174:177], v[204:207], v[102:105]
	v_mfma_f32_16x16x32_bf16 v[98:101], v[182:185], v[204:207], v[98:101]
	v_mfma_f32_16x16x32_bf16 v[86:89], v[174:177], v[212:215], v[86:89]
	v_mfma_f32_16x16x32_bf16 v[82:85], v[182:185], v[212:215], v[82:85]
	v_mfma_f32_16x16x32_bf16 v[70:73], v[174:177], v[220:223], v[70:73]
	v_mfma_f32_16x16x32_bf16 v[66:69], v[182:185], v[220:223], v[66:69]
	s_nop 0
	s_barrier
; #define PG8_STAGE(bufoff, gbase, voff) do { _Pragma("unroll") for (int _i = 0; _i < 2; ++_i) \
;         __builtin_amdgcn_global_load_lds((const unsigned*)((const char*)(gbase) + (voff)[_i]), (LAS unsigned*)(lds + (bufoff) + ldsw + _i * 8192), 16, 0, 0); } while (0)
; #define PG8_LDA(dst, b, h) do { _Pragma("unroll") for (int m = 0; m < 4; ++m) _Pragma("unroll") for (int k = 0; k < 2; ++k) dst[m][k] = *(const LAS bf16x8*)(lds + PG8_SA(b, h) + aoff + m * 2048 + k * 1024); } while (0)
; #define PG8_MMA(ai, bj, At, Bt) do { __builtin_amdgcn_s_setprio(1); _Pragma("unroll") for (int m = 0; m < 4; ++m) _Pragma("unroll") for (int n = 0; n < 2; ++n) _Pragma("unroll") for (int k = 0; k < 2; ++k) \
;         acc[ai][bj][m][n] = __builtin_amdgcn_mfma_f32_16x16x32_bf16(Bt[n][k], At[m][k], acc[ai][bj][m][n], 0, 0, 0); __builtin_amdgcn_s_setprio(0); } while (0)
; #define PG8_WAIT_V(n) asm volatile("s_waitcnt vmcnt(" #n ")" ::: "memory")
; #define PG8_WAIT_L(n) asm volatile("s_waitcnt lgkmcnt(" #n ")" ::: "memory")
; #define PG8_BAR __builtin_amdgcn_s_barrier()
; #define PG8_SCHED __builtin_amdgcn_sched_barrier(0)
; template <class Epi>
; __device__ __forceinline__ void gemm_phase(LAS unsigned char* lds, const Gemm g, const StaticOrder& S, const Epi& E) {
;     ...
;             PG8_WAIT_V(8); PG8_WAIT_L(0); PG8_BAR; PG8_MMA(0, 0, At, B0); PG8_MMA(0, 1, At, B1); PG8_BAR; PG8_SCHED;
;             PG8_LDA(At, 1, 1); PG8_STAGE(PG8_SB(1, 0), b3, voffB); PG8_STAGE(PG8_SB(1, 1), b3 + hstepB, voffB); PG8_STAGE(PG8_SA(1, 0), a3, voffA);
;             PG8_WAIT_V(8); PG8_WAIT_L(0); PG8_BAR; PG8_MMA(1, 0, At, B0); PG8_MMA(1, 1, At, B1); PG8_BAR; PG8_SCHED;
;         }
;         if (wr == 0) PG8_BAR;
;         E(acc, cur, wr, wc, fr, fq);
;         if (!has_next) break;
	s_add_i32 s48, s85, s38
	v_lshl_add_u64 v[196:197], v[196:197], 0, s[64:65]
	s_mov_b32 m0, s48
	ds_read_b128 v[186:189], v160 offset:49152
	ds_read_b128 v[190:193], v160 offset:50176
	ds_read_b128 v[200:203], v160 offset:51200
	ds_read_b128 v[204:207], v160 offset:52224
	ds_read_b128 v[208:211], v160 offset:53248
	ds_read_b128 v[212:215], v160 offset:54272
	ds_read_b128 v[216:219], v160 offset:55296
	ds_read_b128 v[220:223], v160 offset:56320
	global_load_lds_dwordx4 v[196:197], off
	s_add_i32 m0, s48, 0x2000
	s_add_u32 s48, s78, 0x80080
	v_lshl_add_u64 v[196:197], v[198:199], 0, s[64:65]
	s_addc_u32 s49, s79, 0
	s_add_i32 s78, s87, s38
	global_load_lds_dwordx4 v[196:197], off
	v_lshl_add_u64 v[196:197], s[48:49], 0, v[132:133]
	s_mov_b32 m0, s78
	s_nop 0
	global_load_lds_dwordx4 v[196:197], off
	v_lshl_add_u64 v[196:197], s[48:49], 0, v[136:137]
	s_add_i32 m0, s78, 0x2000
	s_nop 0
	global_load_lds_dwordx4 v[196:197], off
	v_lshl_add_u64 v[196:197], v[224:225], 0, s[64:65]
	s_mov_b32 m0, s91
	s_nop 0
	global_load_lds_dwordx4 v[196:197], off
	v_lshl_add_u64 v[196:197], v[230:231], 0, s[64:65]
	s_mov_b32 m0, s95
	s_nop 0
	global_load_lds_dwordx4 v[196:197], off
	s_waitcnt vmcnt(8)
	s_waitcnt lgkmcnt(0)
	s_barrier
	s_nop 0
	s_waitcnt lgkmcnt(0)
	v_mfma_f32_16x16x32_bf16 v[62:65], v[152:155], v[186:189], v[62:65]
	v_mfma_f32_16x16x32_bf16 v[58:61], v[162:165], v[186:189], v[58:61]
	v_mfma_f32_16x16x32_bf16 v[46:49], v[152:155], v[200:203], v[46:49]
	v_mfma_f32_16x16x32_bf16 v[42:45], v[162:165], v[200:203], v[42:45]
	v_mfma_f32_16x16x32_bf16 v[30:33], v[152:155], v[208:211], v[30:33]
	v_mfma_f32_16x16x32_bf16 v[26:29], v[162:165], v[208:211], v[26:29]
	v_mfma_f32_16x16x32_bf16 v[14:17], v[152:155], v[216:219], v[14:17]
	v_mfma_f32_16x16x32_bf16 v[10:13], v[162:165], v[216:219], v[10:13]
	v_mfma_f32_16x16x32_bf16 v[62:65], v[156:159], v[190:193], v[62:65]
	v_mfma_f32_16x16x32_bf16 v[58:61], v[166:169], v[190:193], v[58:61]
	v_mfma_f32_16x16x32_bf16 v[46:49], v[156:159], v[204:207], v[46:49]
	v_mfma_f32_16x16x32_bf16 v[42:45], v[166:169], v[204:207], v[42:45]
	v_mfma_f32_16x16x32_bf16 v[30:33], v[156:159], v[212:215], v[30:33]
	v_mfma_f32_16x16x32_bf16 v[26:29], v[166:169], v[212:215], v[26:29]
	v_mfma_f32_16x16x32_bf16 v[14:17], v[156:159], v[220:223], v[14:17]
	v_mfma_f32_16x16x32_bf16 v[10:13], v[166:169], v[220:223], v[10:13]
	s_nop 0
	s_nop 0
	v_mfma_f32_16x16x32_bf16 v[54:57], v[170:173], v[186:189], v[54:57]
	v_mfma_f32_16x16x32_bf16 v[50:53], v[178:181], v[186:189], v[50:53]
	v_mfma_f32_16x16x32_bf16 v[38:41], v[170:173], v[200:203], v[38:41]
	v_mfma_f32_16x16x32_bf16 v[34:37], v[178:181], v[200:203], v[34:37]
	v_mfma_f32_16x16x32_bf16 v[22:25], v[170:173], v[208:211], v[22:25]
	v_mfma_f32_16x16x32_bf16 v[18:21], v[178:181], v[208:211], v[18:21]
	v_mfma_f32_16x16x32_bf16 v[6:9], v[170:173], v[216:219], v[6:9]
	v_mfma_f32_16x16x32_bf16 v[2:5], v[178:181], v[216:219], v[2:5]
	v_mfma_f32_16x16x32_bf16 v[54:57], v[174:177], v[190:193], v[54:57]
	v_mfma_f32_16x16x32_bf16 v[50:53], v[182:185], v[190:193], v[50:53]
	v_mfma_f32_16x16x32_bf16 v[38:41], v[174:177], v[204:207], v[38:41]
	v_mfma_f32_16x16x32_bf16 v[34:37], v[182:185], v[204:207], v[34:37]
	v_mfma_f32_16x16x32_bf16 v[22:25], v[174:177], v[212:215], v[22:25]
	v_mfma_f32_16x16x32_bf16 v[18:21], v[182:185], v[212:215], v[18:21]
	v_mfma_f32_16x16x32_bf16 v[6:9], v[174:177], v[220:223], v[6:9]
	v_mfma_f32_16x16x32_bf16 v[2:5], v[182:185], v[220:223], v[2:5]
	s_nop 0
	s_barrier
	s_add_i32 s84, s84, 2
	s_add_u32 s30, s30, 0x100
	s_addc_u32 s31, s31, 0
	s_add_u32 s82, s82, 0x100
	s_addc_u32 s83, s83, 0
	s_cmp_gt_u32 s84, 29
	s_cbranch_scc0 .LBB0_325
	s_and_b64 vcc, exec, s[18:19]
	s_cbranch_vccz .LBB0_328
	s_barrier

; #define PG8_STAGE(bufoff, gbase, voff) do { _Pragma("unroll") for (int _i = 0; _i < 2; ++_i) \
;         __builtin_amdgcn_global_load_lds((const unsigned*)((const char*)(gbase) + (voff)[_i]), (LAS unsigned*)(lds + (bufoff) + ldsw + _i * 8192), 16, 0, 0); } while (0)
; #define PG8_LDA(dst, b, h) do { _Pragma("unroll") for (int m = 0; m < 4; ++m) _Pragma("unroll") for (int k = 0; k < 2; ++k) dst[m][k] = *(const LAS bf16x8*)(lds + PG8_SA(b, h) + aoff + m * 2048 + k * 1024); } while (0)
; #define PG8_LDB(dst, b, h) do { _Pragma("unroll") for (int n = 0; n < 2; ++n) _Pragma("unroll") for (int k = 0; k < 2; ++k) dst[n][k] = *(const LAS bf16x8*)(lds + PG8_SB(b, h) + boff + n * 2048 + k * 1024); } while (0)
; #define PG8_MMA(ai, bj, At, Bt) do { __builtin_amdgcn_s_setprio(1); _Pragma("unroll") for (int m = 0; m < 4; ++m) _Pragma("unroll") for (int n = 0; n < 2; ++n) _Pragma("unroll") for (int k = 0; k < 2; ++k) \
;         acc[ai][bj][m][n] = __builtin_amdgcn_mfma_f32_16x16x32_bf16(Bt[n][k], At[m][k], acc[ai][bj][m][n], 0, 0, 0); __builtin_amdgcn_s_setprio(0); } while (0)
; #define PG8_WAIT_V(n) asm volatile("s_waitcnt vmcnt(" #n ")" ::: "memory")
; #define PG8_WAIT_L(n) asm volatile("s_waitcnt lgkmcnt(" #n ")" ::: "memory")
; #define PG8_BAR __builtin_amdgcn_s_barrier()
; #define PG8_SCHED __builtin_amdgcn_sched_barrier(0)
; template <class Epi>
; __device__ __forceinline__ void gemm_phase(LAS unsigned char* lds, const Gemm g, const StaticOrder& S, const Epi& E) {
;     ...
;             const bool last = (t == nt - 2);
;             const char* a1 = cA + (size_t)(t + 1) * kstep;
;             const char* a2 = last ? nA : cA + (size_t)(t + 2) * kstep; const char* b2 = last ? nB : cB + (size_t)(t + 2) * kstep;
;             const char* a3 = a2 + kstep; const char* b3 = b2 + kstep;
;             PG8_LDB(B0, 0, 0); PG8_LDB(B1, 0, 1); PG8_SCHED; PG8_LDA(At, 0, 0); PG8_STAGE(PG8_SA(1, 1), a1 + hstepA, voffA);
;             PG8_WAIT_V(8); PG8_WAIT_L(0); PG8_BAR; PG8_MMA(0, 0, At, B0); PG8_MMA(0, 1, At, B1); PG8_BAR; PG8_SCHED;
;             PG8_LDA(At, 0, 1); PG8_STAGE(PG8_SB(0, 0), b2, voffB); PG8_STAGE(PG8_SB(0, 1), b2 + hstepB, voffB); PG8_STAGE(PG8_SA(0, 0), a2, voffA);
;             PG8_WAIT_V(8); PG8_WAIT_L(0); PG8_BAR; PG8_MMA(1, 0, At, B0); PG8_MMA(1, 1, At, B1); PG8_BAR; PG8_SCHED;
.LBB0_557:
	s_add_u32 s16, s63, s14
	s_addc_u32 s17, s72, s15
	s_add_u32 s16, s16, 0x4000100
	s_addc_u32 s17, s17, 0
	s_add_u32 s48, s73, s14
	s_addc_u32 s49, s74, s15
	s_add_i32 s78, 0, 0x10000
	s_cmpk_eq_i32 s14, 0x300
	s_cselect_b32 s19, s11, s17
	s_cselect_b32 s18, s10, s16
	s_cselect_b32 s17, s13, s49
	s_cselect_b32 s16, s12, s48
	s_add_i32 s79, 0, 0x14000
	v_add_u32_e32 v156, s78, v142
	v_add_u32_e32 v172, s79, v142
	ds_read_b128 v[144:147], v156
	ds_read_b128 v[148:151], v156 offset:1024
	ds_read_b128 v[152:155], v156 offset:2048
	ds_read_b128 v[156:159], v156 offset:3072
	ds_read_b128 v[160:163], v172
	ds_read_b128 v[164:167], v172 offset:1024
	ds_read_b128 v[168:171], v172 offset:2048
	ds_read_b128 v[172:175], v172 offset:3072
	v_lshl_add_u64 v[192:193], v[138:139], 0, s[14:15]
	s_add_i32 m0, s36, 0xc000
	ds_read_b128 v[176:179], v143
	ds_read_b128 v[180:183], v143 offset:1024
	ds_read_b128 v[184:187], v143 offset:2048
	ds_read_b128 v[188:191], v143 offset:3072
	ds_read_b128 v[200:203], v143 offset:4096
	ds_read_b128 v[204:207], v143 offset:5120
	ds_read_b128 v[208:211], v143 offset:6144
	ds_read_b128 v[212:215], v143 offset:7168
	global_load_lds_dwordx4 v[192:193], off
	v_lshl_add_u64 v[192:193], v[140:141], 0, s[14:15]
	s_add_i32 m0, s36, 0xe000
	s_nop 0
	global_load_lds_dwordx4 v[192:193], off
	s_waitcnt vmcnt(8)
	s_waitcnt lgkmcnt(0)
	s_barrier
	s_nop 0
	s_waitcnt lgkmcnt(0)
	v_mfma_f32_16x16x32_bf16 v[126:129], v[144:147], v[176:179], v[126:129]
	v_mfma_f32_16x16x32_bf16 v[122:125], v[152:155], v[176:179], v[122:125]
	v_mfma_f32_16x16x32_bf16 v[118:121], v[144:147], v[184:187], v[118:121]
	v_mfma_f32_16x16x32_bf16 v[114:117], v[152:155], v[184:187], v[114:117]
	v_mfma_f32_16x16x32_bf16 v[102:105], v[144:147], v[200:203], v[102:105]
	v_mfma_f32_16x16x32_bf16 v[98:101], v[152:155], v[200:203], v[98:101]
	v_mfma_f32_16x16x32_bf16 v[86:89], v[144:147], v[208:211], v[86:89]
	v_mfma_f32_16x16x32_bf16 v[82:85], v[152:155], v[208:211], v[82:85]
	v_mfma_f32_16x16x32_bf16 v[126:129], v[148:151], v[180:183], v[126:129]
	v_mfma_f32_16x16x32_bf16 v[122:125], v[156:159], v[180:183], v[122:125]
	v_mfma_f32_16x16x32_bf16 v[118:121], v[148:151], v[188:191], v[118:121]
	v_mfma_f32_16x16x32_bf16 v[114:117], v[156:159], v[188:191], v[114:117]
	v_mfma_f32_16x16x32_bf16 v[102:105], v[148:151], v[204:207], v[102:105]
	v_mfma_f32_16x16x32_bf16 v[98:101], v[156:159], v[204:207], v[98:101]
	v_mfma_f32_16x16x32_bf16 v[86:89], v[148:151], v[212:215], v[86:89]
	v_mfma_f32_16x16x32_bf16 v[82:85], v[156:159], v[212:215], v[82:85]
	s_nop 0
	s_nop 0
	v_mfma_f32_16x16x32_bf16 v[110:113], v[160:163], v[176:179], v[110:113]
	v_mfma_f32_16x16x32_bf16 v[106:109], v[168:171], v[176:179], v[106:109]
	v_mfma_f32_16x16x32_bf16 v[94:97], v[160:163], v[184:187], v[94:97]
	v_mfma_f32_16x16x32_bf16 v[90:93], v[168:171], v[184:187], v[90:93]
	v_mfma_f32_16x16x32_bf16 v[78:81], v[160:163], v[200:203], v[78:81]
	v_mfma_f32_16x16x32_bf16 v[74:77], v[168:171], v[200:203], v[74:77]
	v_mfma_f32_16x16x32_bf16 v[70:73], v[160:163], v[208:211], v[70:73]
	v_mfma_f32_16x16x32_bf16 v[66:69], v[168:171], v[208:211], v[66:69]
	v_mfma_f32_16x16x32_bf16 v[110:113], v[164:167], v[180:183], v[110:113]
	v_mfma_f32_16x16x32_bf16 v[106:109], v[172:175], v[180:183], v[106:109]
	v_mfma_f32_16x16x32_bf16 v[94:97], v[164:167], v[188:191], v[94:97]
	v_mfma_f32_16x16x32_bf16 v[90:93], v[172:175], v[188:191], v[90:93]
	v_mfma_f32_16x16x32_bf16 v[78:81], v[164:167], v[204:207], v[78:81]
	v_mfma_f32_16x16x32_bf16 v[74:77], v[172:175], v[204:207], v[74:77]
	v_mfma_f32_16x16x32_bf16 v[70:73], v[164:167], v[212:215], v[70:73]
	v_mfma_f32_16x16x32_bf16 v[66:69], v[172:175], v[212:215], v[66:69]
	s_nop 0
	s_barrier
	s_add_i32 s48, s78, s34
	v_lshl_add_u64 v[192:193], s[16:17], 0, v[0:1]
	s_mov_b32 m0, s48
	ds_read_b128 v[176:179], v143 offset:16384
	ds_read_b128 v[180:183], v143 offset:17408
	ds_read_b128 v[184:187], v143 offset:18432
	ds_read_b128 v[188:191], v143 offset:19456
	ds_read_b128 v[200:203], v143 offset:20480
	ds_read_b128 v[204:207], v143 offset:21504
	ds_read_b128 v[208:211], v143 offset:22528
	ds_read_b128 v[212:215], v143 offset:23552
	global_load_lds_dwordx4 v[192:193], off
	s_add_i32 m0, s48, 0x2000
	s_add_u32 s48, s16, 0x100000
	v_lshl_add_u64 v[196:197], s[16:17], 0, v[136:137]
	s_addc_u32 s49, s17, 0
	s_add_i32 s78, s79, s34
	global_load_lds_dwordx4 v[196:197], off
	v_lshl_add_u64 v[198:199], s[48:49], 0, v[0:1]
	s_mov_b32 m0, s78
	v_lshl_add_u64 v[216:217], s[18:19], 0, v[134:135]
	global_load_lds_dwordx4 v[198:199], off
	v_lshl_add_u64 v[198:199], s[48:49], 0, v[136:137]
	s_add_i32 m0, s78, 0x2000
	s_nop 0
	global_load_lds_dwordx4 v[198:199], off
	v_lshl_add_u64 v[198:199], s[18:19], 0, v[132:133]
	s_mov_b32 m0, s36
	s_nop 0
	global_load_lds_dwordx4 v[198:199], off
	s_mov_b32 m0, s38
	s_nop 0
	global_load_lds_dwordx4 v[216:217], off
	s_waitcnt vmcnt(8)
	s_waitcnt lgkmcnt(0)
	s_barrier
; #define PG8_STAGE(bufoff, gbase, voff) do { _Pragma("unroll") for (int _i = 0; _i < 2; ++_i) \
;         __builtin_amdgcn_global_load_lds((const unsigned*)((const char*)(gbase) + (voff)[_i]), (LAS unsigned*)(lds + (bufoff) + ldsw + _i * 8192), 16, 0, 0); } while (0)
; #define PG8_LDA(dst, b, h) do { _Pragma("unroll") for (int m = 0; m < 4; ++m) _Pragma("unroll") for (int k = 0; k < 2; ++k) dst[m][k] = *(const LAS bf16x8*)(lds + PG8_SA(b, h) + aoff + m * 2048 + k * 1024); } while (0)
; #define PG8_LDB(dst, b, h) do { _Pragma("unroll") for (int n = 0; n < 2; ++n) _Pragma("unroll") for (int k = 0; k < 2; ++k) dst[n][k] = *(const LAS bf16x8*)(lds + PG8_SB(b, h) + boff + n * 2048 + k * 1024); } while (0)
; #define PG8_MMA(ai, bj, At, Bt) do { __builtin_amdgcn_s_setprio(1); _Pragma("unroll") for (int m = 0; m < 4; ++m) _Pragma("unroll") for (int n = 0; n < 2; ++n) _Pragma("unroll") for (int k = 0; k < 2; ++k) \
;         acc[ai][bj][m][n] = __builtin_amdgcn_mfma_f32_16x16x32_bf16(Bt[n][k], At[m][k], acc[ai][bj][m][n], 0, 0, 0); __builtin_amdgcn_s_setprio(0); } while (0)
; #define PG8_WAIT_V(n) asm volatile("s_waitcnt vmcnt(" #n ")" ::: "memory")
; #define PG8_WAIT_L(n) asm volatile("s_waitcnt lgkmcnt(" #n ")" ::: "memory")
; #define PG8_BAR __builtin_amdgcn_s_barrier()
; #define PG8_SCHED __builtin_amdgcn_sched_barrier(0)
; template <class Epi>
; __device__ __forceinline__ void gemm_phase(LAS unsigned char* lds, const Gemm g, const StaticOrder& S, const Epi& E) {
;     ...
;             PG8_WAIT_V(8); PG8_WAIT_L(0); PG8_BAR; PG8_MMA(0, 0, At, B0); PG8_MMA(0, 1, At, B1); PG8_BAR; PG8_SCHED;
;             PG8_LDA(At, 0, 1); PG8_STAGE(PG8_SB(0, 0), b2, voffB); PG8_STAGE(PG8_SB(0, 1), b2 + hstepB, voffB); PG8_STAGE(PG8_SA(0, 0), a2, voffA);
;             PG8_WAIT_V(8); PG8_WAIT_L(0); PG8_BAR; PG8_MMA(1, 0, At, B0); PG8_MMA(1, 1, At, B1); PG8_BAR; PG8_SCHED;
;             PG8_LDB(B0, 1, 0); PG8_LDB(B1, 1, 1); PG8_SCHED; PG8_LDA(At, 1, 0); PG8_STAGE(PG8_SA(0, 1), a2 + hstepA, voffA);
;             PG8_WAIT_V(8); PG8_WAIT_L(0); PG8_BAR; PG8_MMA(0, 0, At, B0); PG8_MMA(0, 1, At, B1); PG8_BAR; PG8_SCHED;
;             PG8_LDA(At, 1, 1); PG8_STAGE(PG8_SB(1, 0), b3, voffB); PG8_STAGE(PG8_SB(1, 1), b3 + hstepB, voffB); PG8_STAGE(PG8_SA(1, 0), a3, voffA);
	s_nop 0
	s_waitcnt lgkmcnt(0)
	v_mfma_f32_16x16x32_bf16 v[62:65], v[144:147], v[176:179], v[62:65]
	v_mfma_f32_16x16x32_bf16 v[58:61], v[152:155], v[176:179], v[58:61]
	v_mfma_f32_16x16x32_bf16 v[54:57], v[144:147], v[184:187], v[54:57]
	v_mfma_f32_16x16x32_bf16 v[50:53], v[152:155], v[184:187], v[50:53]
	v_mfma_f32_16x16x32_bf16 v[38:41], v[144:147], v[200:203], v[38:41]
	v_mfma_f32_16x16x32_bf16 v[34:37], v[152:155], v[200:203], v[34:37]
	v_mfma_f32_16x16x32_bf16 v[22:25], v[144:147], v[208:211], v[22:25]
	v_mfma_f32_16x16x32_bf16 v[18:21], v[152:155], v[208:211], v[18:21]
	v_mfma_f32_16x16x32_bf16 v[62:65], v[148:151], v[180:183], v[62:65]
	v_mfma_f32_16x16x32_bf16 v[58:61], v[156:159], v[180:183], v[58:61]
	v_mfma_f32_16x16x32_bf16 v[54:57], v[148:151], v[188:191], v[54:57]
	v_mfma_f32_16x16x32_bf16 v[50:53], v[156:159], v[188:191], v[50:53]
	v_mfma_f32_16x16x32_bf16 v[38:41], v[148:151], v[204:207], v[38:41]
	v_mfma_f32_16x16x32_bf16 v[34:37], v[156:159], v[204:207], v[34:37]
	v_mfma_f32_16x16x32_bf16 v[22:25], v[148:151], v[212:215], v[22:25]
	v_mfma_f32_16x16x32_bf16 v[18:21], v[156:159], v[212:215], v[18:21]
	s_nop 0
	s_nop 0
	v_mfma_f32_16x16x32_bf16 v[46:49], v[160:163], v[176:179], v[46:49]
	v_mfma_f32_16x16x32_bf16 v[42:45], v[168:171], v[176:179], v[42:45]
	v_mfma_f32_16x16x32_bf16 v[30:33], v[160:163], v[184:187], v[30:33]
	v_mfma_f32_16x16x32_bf16 v[26:29], v[168:171], v[184:187], v[26:29]
	v_mfma_f32_16x16x32_bf16 v[14:17], v[160:163], v[200:203], v[14:17]
	v_mfma_f32_16x16x32_bf16 v[10:13], v[168:171], v[200:203], v[10:13]
	v_mfma_f32_16x16x32_bf16 v[6:9], v[160:163], v[208:211], v[6:9]
	v_mfma_f32_16x16x32_bf16 v[2:5], v[168:171], v[208:211], v[2:5]
	v_mfma_f32_16x16x32_bf16 v[46:49], v[164:167], v[180:183], v[46:49]
	v_mfma_f32_16x16x32_bf16 v[42:45], v[172:175], v[180:183], v[42:45]
	v_mfma_f32_16x16x32_bf16 v[30:33], v[164:167], v[188:191], v[30:33]
	v_mfma_f32_16x16x32_bf16 v[26:29], v[172:175], v[188:191], v[26:29]
	v_mfma_f32_16x16x32_bf16 v[14:17], v[164:167], v[204:207], v[14:17]
	v_mfma_f32_16x16x32_bf16 v[10:13], v[172:175], v[204:207], v[10:13]
	v_mfma_f32_16x16x32_bf16 v[6:9], v[164:167], v[212:215], v[6:9]
	v_mfma_f32_16x16x32_bf16 v[2:5], v[172:175], v[212:215], v[2:5]
	s_nop 0
	s_barrier
	s_add_i32 s48, 0, 0x18000
	s_add_i32 s49, 0, 0x1c000
	v_add_u32_e32 v156, s48, v142
	v_add_u32_e32 v172, s49, v142
	ds_read_b128 v[144:147], v156
	ds_read_b128 v[148:151], v156 offset:1024
	ds_read_b128 v[152:155], v156 offset:2048
	ds_read_b128 v[156:159], v156 offset:3072
	ds_read_b128 v[160:163], v172
	ds_read_b128 v[164:167], v172 offset:1024
	ds_read_b128 v[168:171], v172 offset:2048
	ds_read_b128 v[172:175], v172 offset:3072
	s_add_u32 s18, s18, 0x80000
	s_addc_u32 s19, s19, 0
	s_mov_b32 m0, s39
	v_lshl_add_u64 v[218:219], s[18:19], 0, v[132:133]
	ds_read_b128 v[176:179], v143 offset:32768
	ds_read_b128 v[180:183], v143 offset:33792
	ds_read_b128 v[184:187], v143 offset:34816
	ds_read_b128 v[188:191], v143 offset:35840
	ds_read_b128 v[200:203], v143 offset:36864
	ds_read_b128 v[204:207], v143 offset:37888
	ds_read_b128 v[208:211], v143 offset:38912
	ds_read_b128 v[212:215], v143 offset:39936
	global_load_lds_dwordx4 v[218:219], off
	v_lshl_add_u64 v[218:219], s[18:19], 0, v[134:135]
	s_mov_b32 m0, s43
	s_nop 0
	global_load_lds_dwordx4 v[218:219], off
	s_waitcnt vmcnt(8)
	s_waitcnt lgkmcnt(0)
	s_barrier
	s_nop 0
	s_waitcnt lgkmcnt(0)
	v_mfma_f32_16x16x32_bf16 v[126:129], v[144:147], v[176:179], v[126:129]
	v_mfma_f32_16x16x32_bf16 v[122:125], v[152:155], v[176:179], v[122:125]
	v_mfma_f32_16x16x32_bf16 v[118:121], v[144:147], v[184:187], v[118:121]
	v_mfma_f32_16x16x32_bf16 v[114:117], v[152:155], v[184:187], v[114:117]
	v_mfma_f32_16x16x32_bf16 v[102:105], v[144:147], v[200:203], v[102:105]
	v_mfma_f32_16x16x32_bf16 v[98:101], v[152:155], v[200:203], v[98:101]
	v_mfma_f32_16x16x32_bf16 v[86:89], v[144:147], v[208:211], v[86:89]
	v_mfma_f32_16x16x32_bf16 v[82:85], v[152:155], v[208:211], v[82:85]
	v_mfma_f32_16x16x32_bf16 v[126:129], v[148:151], v[180:183], v[126:129]
	v_mfma_f32_16x16x32_bf16 v[122:125], v[156:159], v[180:183], v[122:125]
	v_mfma_f32_16x16x32_bf16 v[118:121], v[148:151], v[188:191], v[118:121]
	v_mfma_f32_16x16x32_bf16 v[114:117], v[156:159], v[188:191], v[114:117]
	v_mfma_f32_16x16x32_bf16 v[102:105], v[148:151], v[204:207], v[102:105]
	v_mfma_f32_16x16x32_bf16 v[98:101], v[156:159], v[204:207], v[98:101]
	v_mfma_f32_16x16x32_bf16 v[86:89], v[148:151], v[212:215], v[86:89]
	v_mfma_f32_16x16x32_bf16 v[82:85], v[156:159], v[212:215], v[82:85]
	s_nop 0
	s_nop 0
	v_mfma_f32_16x16x32_bf16 v[110:113], v[160:163], v[176:179], v[110:113]
	v_mfma_f32_16x16x32_bf16 v[106:109], v[168:171], v[176:179], v[106:109]
	v_mfma_f32_16x16x32_bf16 v[94:97], v[160:163], v[184:187], v[94:97]
	v_mfma_f32_16x16x32_bf16 v[90:93], v[168:171], v[184:187], v[90:93]
	v_mfma_f32_16x16x32_bf16 v[78:81], v[160:163], v[200:203], v[78:81]
	v_mfma_f32_16x16x32_bf16 v[74:77], v[168:171], v[200:203], v[74:77]
	v_mfma_f32_16x16x32_bf16 v[70:73], v[160:163], v[208:211], v[70:73]
	v_mfma_f32_16x16x32_bf16 v[66:69], v[168:171], v[208:211], v[66:69]
	v_mfma_f32_16x16x32_bf16 v[110:113], v[164:167], v[180:183], v[110:113]
	v_mfma_f32_16x16x32_bf16 v[106:109], v[172:175], v[180:183], v[106:109]
	v_mfma_f32_16x16x32_bf16 v[94:97], v[164:167], v[188:191], v[94:97]
	v_mfma_f32_16x16x32_bf16 v[90:93], v[172:175], v[188:191], v[90:93]
	v_mfma_f32_16x16x32_bf16 v[78:81], v[164:167], v[204:207], v[78:81]
	v_mfma_f32_16x16x32_bf16 v[74:77], v[172:175], v[204:207], v[74:77]
	v_mfma_f32_16x16x32_bf16 v[70:73], v[164:167], v[212:215], v[70:73]
	v_mfma_f32_16x16x32_bf16 v[66:69], v[172:175], v[212:215], v[66:69]
	s_nop 0
	s_barrier
; #define PG8_STAGE(bufoff, gbase, voff) do { _Pragma("unroll") for (int _i = 0; _i < 2; ++_i) \
;         __builtin_amdgcn_global_load_lds((const unsigned*)((const char*)(gbase) + (voff)[_i]), (LAS unsigned*)(lds + (bufoff) + ldsw + _i * 8192), 16, 0, 0); } while (0)
; #define PG8_LDA(dst, b, h) do { _Pragma("unroll") for (int m = 0; m < 4; ++m) _Pragma("unroll") for (int k = 0; k < 2; ++k) dst[m][k] = *(const LAS bf16x8*)(lds + PG8_SA(b, h) + aoff + m * 2048 + k * 1024); } while (0)
; #define PG8_MMA(ai, bj, At, Bt) do { __builtin_amdgcn_s_setprio(1); _Pragma("unroll") for (int m = 0; m < 4; ++m) _Pragma("unroll") for (int n = 0; n < 2; ++n) _Pragma("unroll") for (int k = 0; k < 2; ++k) \
;         acc[ai][bj][m][n] = __builtin_amdgcn_mfma_f32_16x16x32_bf16(Bt[n][k], At[m][k], acc[ai][bj][m][n], 0, 0, 0); __builtin_amdgcn_s_setprio(0); } while (0)
; #define PG8_WAIT_V(n) asm volatile("s_waitcnt vmcnt(" #n ")" ::: "memory")
; #define PG8_WAIT_L(n) asm volatile("s_waitcnt lgkmcnt(" #n ")" ::: "memory")
; #define PG8_BAR __builtin_amdgcn_s_barrier()
; #define PG8_SCHED __builtin_amdgcn_sched_barrier(0)
; template <class Epi>
; __device__ __forceinline__ void gemm_phase(LAS unsigned char* lds, const Gemm g, const StaticOrder& S, const Epi& E) {
;     ...
;             PG8_WAIT_V(8); PG8_WAIT_L(0); PG8_BAR; PG8_MMA(0, 0, At, B0); PG8_MMA(0, 1, At, B1); PG8_BAR; PG8_SCHED;
;             PG8_LDA(At, 1, 1); PG8_STAGE(PG8_SB(1, 0), b3, voffB); PG8_STAGE(PG8_SB(1, 1), b3 + hstepB, voffB); PG8_STAGE(PG8_SA(1, 0), a3, voffA);
;             PG8_WAIT_V(8); PG8_WAIT_L(0); PG8_BAR; PG8_MMA(1, 0, At, B0); PG8_MMA(1, 1, At, B1); PG8_BAR; PG8_SCHED;
;         }
; __global__ void __launch_bounds__(512, 2) nsa_fwd(Params P_unused) {
;     ...
;             for (int u = bid; u < 256; u += G) {
;                 const int kv = u >> 7, pm = (u >> 3) & 15, ks = u & 7;
;                 pg8::Gemm gm{WSP(const bf16_t, WS_KV) + (size_t)kv * KVJ + (size_t)pm * 256 * 2048 + ks * 512, WSP(const bf16_t, WS_CW1) + (size_t)(L * 2 + kv) * 256 * 4096 + ks * 512, 256, 256, 512, 2048, 4096};
;                 pg8::StaticOrder S; S.init(256, 256, 1, 0);
;                 EpiC1S E{WSP(float, WS_XB) + (size_t)ks * 4096 * 512, pm * 256, kv * 256};
;                 pg8::gemm_phase<EpiC1S>(lds, gm, S, E);
;             }
	s_add_i32 s18, s48, s34
	v_lshl_add_u64 v[192:193], v[192:193], 0, s[64:65]
	s_mov_b32 m0, s18
	ds_read_b128 v[176:179], v143 offset:49152
	ds_read_b128 v[180:183], v143 offset:50176
	ds_read_b128 v[184:187], v143 offset:51200
	ds_read_b128 v[188:191], v143 offset:52224
	ds_read_b128 v[200:203], v143 offset:53248
	ds_read_b128 v[204:207], v143 offset:54272
	ds_read_b128 v[208:211], v143 offset:55296
	ds_read_b128 v[212:215], v143 offset:56320
	global_load_lds_dwordx4 v[192:193], off
	s_add_i32 m0, s18, 0x2000
	s_add_u32 s16, s16, 0x100080
	v_lshl_add_u64 v[192:193], v[196:197], 0, s[64:65]
	s_addc_u32 s17, s17, 0
	s_add_i32 s18, s49, s34
	global_load_lds_dwordx4 v[192:193], off
	v_lshl_add_u64 v[192:193], s[16:17], 0, v[0:1]
	s_mov_b32 m0, s18
	s_nop 0
	global_load_lds_dwordx4 v[192:193], off
	v_lshl_add_u64 v[192:193], s[16:17], 0, v[136:137]
	s_add_i32 m0, s18, 0x2000
	s_nop 0
	global_load_lds_dwordx4 v[192:193], off
	v_lshl_add_u64 v[192:193], v[198:199], 0, s[64:65]
	s_mov_b32 m0, s61
	s_nop 0
	global_load_lds_dwordx4 v[192:193], off
	v_lshl_add_u64 v[192:193], v[216:217], 0, s[64:65]
	s_mov_b32 m0, s62
	s_nop 0
	global_load_lds_dwordx4 v[192:193], off
	s_waitcnt vmcnt(8)
	s_waitcnt lgkmcnt(0)
	s_barrier
	s_nop 0
	s_waitcnt lgkmcnt(0)
	v_mfma_f32_16x16x32_bf16 v[62:65], v[144:147], v[176:179], v[62:65]
	v_mfma_f32_16x16x32_bf16 v[58:61], v[152:155], v[176:179], v[58:61]
	v_mfma_f32_16x16x32_bf16 v[54:57], v[144:147], v[184:187], v[54:57]
	v_mfma_f32_16x16x32_bf16 v[50:53], v[152:155], v[184:187], v[50:53]
	v_mfma_f32_16x16x32_bf16 v[38:41], v[144:147], v[200:203], v[38:41]
	v_mfma_f32_16x16x32_bf16 v[34:37], v[152:155], v[200:203], v[34:37]
	v_mfma_f32_16x16x32_bf16 v[22:25], v[144:147], v[208:211], v[22:25]
	v_mfma_f32_16x16x32_bf16 v[18:21], v[152:155], v[208:211], v[18:21]
	v_mfma_f32_16x16x32_bf16 v[62:65], v[148:151], v[180:183], v[62:65]
	v_mfma_f32_16x16x32_bf16 v[58:61], v[156:159], v[180:183], v[58:61]
	v_mfma_f32_16x16x32_bf16 v[54:57], v[148:151], v[188:191], v[54:57]
	v_mfma_f32_16x16x32_bf16 v[50:53], v[156:159], v[188:191], v[50:53]
	v_mfma_f32_16x16x32_bf16 v[38:41], v[148:151], v[204:207], v[38:41]
	v_mfma_f32_16x16x32_bf16 v[34:37], v[156:159], v[204:207], v[34:37]
	v_mfma_f32_16x16x32_bf16 v[22:25], v[148:151], v[212:215], v[22:25]
	v_mfma_f32_16x16x32_bf16 v[18:21], v[156:159], v[212:215], v[18:21]
	s_nop 0
	s_nop 0
	v_mfma_f32_16x16x32_bf16 v[46:49], v[160:163], v[176:179], v[46:49]
	v_mfma_f32_16x16x32_bf16 v[42:45], v[168:171], v[176:179], v[42:45]
	v_mfma_f32_16x16x32_bf16 v[30:33], v[160:163], v[184:187], v[30:33]
	v_mfma_f32_16x16x32_bf16 v[26:29], v[168:171], v[184:187], v[26:29]
	v_mfma_f32_16x16x32_bf16 v[14:17], v[160:163], v[200:203], v[14:17]
	v_mfma_f32_16x16x32_bf16 v[10:13], v[168:171], v[200:203], v[10:13]
	v_mfma_f32_16x16x32_bf16 v[6:9], v[160:163], v[208:211], v[6:9]
	v_mfma_f32_16x16x32_bf16 v[2:5], v[168:171], v[208:211], v[2:5]
	v_mfma_f32_16x16x32_bf16 v[46:49], v[164:167], v[180:183], v[46:49]
	v_mfma_f32_16x16x32_bf16 v[42:45], v[172:175], v[180:183], v[42:45]
	v_mfma_f32_16x16x32_bf16 v[30:33], v[164:167], v[188:191], v[30:33]
	v_mfma_f32_16x16x32_bf16 v[26:29], v[172:175], v[188:191], v[26:29]
	v_mfma_f32_16x16x32_bf16 v[14:17], v[164:167], v[204:207], v[14:17]
	v_mfma_f32_16x16x32_bf16 v[10:13], v[172:175], v[204:207], v[10:13]
	v_mfma_f32_16x16x32_bf16 v[6:9], v[164:167], v[212:215], v[6:9]
	v_mfma_f32_16x16x32_bf16 v[2:5], v[172:175], v[212:215], v[2:5]
	s_nop 0
	s_barrier
	s_add_i32 s75, s75, 2
	s_add_u32 s14, s14, 0x100
	s_addc_u32 s15, s15, 0
	s_cmp_gt_u32 s75, 5
	s_cbranch_scc0 .LBB0_557
	s_cmpk_lt_u32 s9, 0x100
	s_cbranch_scc0 .LBB0_553
	s_barrier
	s_branch .LBB0_553

; #define PG8_STAGE(bufoff, gbase, voff) do { _Pragma("unroll") for (int _i = 0; _i < 2; ++_i) \
;         __builtin_amdgcn_global_load_lds((const unsigned*)((const char*)(gbase) + (voff)[_i]), (LAS unsigned*)(lds + (bufoff) + ldsw + _i * 8192), 16, 0, 0); } while (0)
; #define PG8_LDA(dst, b, h) do { _Pragma("unroll") for (int m = 0; m < 4; ++m) _Pragma("unroll") for (int k = 0; k < 2; ++k) dst[m][k] = *(const LAS bf16x8*)(lds + PG8_SA(b, h) + aoff + m * 2048 + k * 1024); } while (0)
; #define PG8_LDB(dst, b, h) do { _Pragma("unroll") for (int n = 0; n < 2; ++n) _Pragma("unroll") for (int k = 0; k < 2; ++k) dst[n][k] = *(const LAS bf16x8*)(lds + PG8_SB(b, h) + boff + n * 2048 + k * 1024); } while (0)
; #define PG8_MMA(ai, bj, At, Bt) do { __builtin_amdgcn_s_setprio(1); _Pragma("unroll") for (int m = 0; m < 4; ++m) _Pragma("unroll") for (int n = 0; n < 2; ++n) _Pragma("unroll") for (int k = 0; k < 2; ++k) \
;         acc[ai][bj][m][n] = __builtin_amdgcn_mfma_f32_16x16x32_bf16(Bt[n][k], At[m][k], acc[ai][bj][m][n], 0, 0, 0); __builtin_amdgcn_s_setprio(0); } while (0)
; #define PG8_WAIT_V(n) asm volatile("s_waitcnt vmcnt(" #n ")" ::: "memory")
; #define PG8_WAIT_L(n) asm volatile("s_waitcnt lgkmcnt(" #n ")" ::: "memory")
; #define PG8_BAR __builtin_amdgcn_s_barrier()
; #define PG8_SCHED __builtin_amdgcn_sched_barrier(0)
; template <class Epi>
; __device__ __forceinline__ void gemm_phase(LAS unsigned char* lds, const Gemm g, const StaticOrder& S, const Epi& E) {
;     ...
;             const bool last = (t == nt - 2);
;             const char* a1 = cA + (size_t)(t + 1) * kstep;
;             const char* a2 = last ? nA : cA + (size_t)(t + 2) * kstep; const char* b2 = last ? nB : cB + (size_t)(t + 2) * kstep;
;             const char* a3 = a2 + kstep; const char* b3 = b2 + kstep;
;             PG8_LDB(B0, 0, 0); PG8_LDB(B1, 0, 1); PG8_SCHED; PG8_LDA(At, 0, 0); PG8_STAGE(PG8_SA(1, 1), a1 + hstepA, voffA);
;             PG8_WAIT_V(8); PG8_WAIT_L(0); PG8_BAR; PG8_MMA(0, 0, At, B0); PG8_MMA(0, 1, At, B1); PG8_BAR; PG8_SCHED;
;             PG8_LDA(At, 0, 1); PG8_STAGE(PG8_SB(0, 0), b2, voffB); PG8_STAGE(PG8_SB(0, 1), b2 + hstepB, voffB); PG8_STAGE(PG8_SA(0, 0), a2, voffA);
;             PG8_WAIT_V(8); PG8_WAIT_L(0); PG8_BAR; PG8_MMA(1, 0, At, B0); PG8_MMA(1, 1, At, B1); PG8_BAR; PG8_SCHED;
.LBB0_711:
	s_add_u32 s48, s80, 0xfffe0080
	s_addc_u32 s49, s81, -1
	s_add_i32 s74, 0, 0x10000
	s_cmp_eq_u32 s73, 4
	s_cselect_b32 s85, s19, s49
	s_cselect_b32 s84, s27, s48
	s_cselect_b32 s83, s25, s72
	s_cselect_b32 s82, s62, s63
	s_add_i32 s75, 0, 0x14000
	v_add_u32_e32 v154, s74, v140
	v_add_u32_e32 v170, s75, v140
	ds_read_b128 v[142:145], v154
	ds_read_b128 v[146:149], v154 offset:1024
	ds_read_b128 v[150:153], v154 offset:2048
	ds_read_b128 v[154:157], v154 offset:3072
	ds_read_b128 v[158:161], v170
	ds_read_b128 v[162:165], v170 offset:1024
	ds_read_b128 v[166:169], v170 offset:2048
	ds_read_b128 v[170:173], v170 offset:3072
	v_lshl_add_u64 v[196:197], s[80:81], 0, v[134:135]
	s_add_i32 m0, s34, 0xc000
	ds_read_b128 v[174:177], v141
	ds_read_b128 v[178:181], v141 offset:1024
	ds_read_b128 v[182:185], v141 offset:2048
	ds_read_b128 v[186:189], v141 offset:3072
	ds_read_b128 v[190:193], v141 offset:4096
	ds_read_b128 v[200:203], v141 offset:5120
	ds_read_b128 v[204:207], v141 offset:6144
	ds_read_b128 v[208:211], v141 offset:7168
	global_load_lds_dwordx4 v[196:197], off
	v_lshl_add_u64 v[196:197], s[80:81], 0, v[136:137]
	s_add_i32 m0, s34, 0xe000
	s_nop 0
	global_load_lds_dwordx4 v[196:197], off
	s_waitcnt vmcnt(8)
	s_waitcnt lgkmcnt(0)
	s_barrier
	s_nop 0
	s_waitcnt lgkmcnt(0)
	v_mfma_f32_16x16x32_bf16 v[126:129], v[142:145], v[174:177], v[126:129]
	v_mfma_f32_16x16x32_bf16 v[122:125], v[150:153], v[174:177], v[122:125]
	v_mfma_f32_16x16x32_bf16 v[118:121], v[142:145], v[182:185], v[118:121]
	v_mfma_f32_16x16x32_bf16 v[114:117], v[150:153], v[182:185], v[114:117]
	v_mfma_f32_16x16x32_bf16 v[106:109], v[142:145], v[190:193], v[106:109]
	v_mfma_f32_16x16x32_bf16 v[98:101], v[150:153], v[190:193], v[98:101]
	v_mfma_f32_16x16x32_bf16 v[90:93], v[142:145], v[204:207], v[90:93]
	v_mfma_f32_16x16x32_bf16 v[82:85], v[150:153], v[204:207], v[82:85]
	v_mfma_f32_16x16x32_bf16 v[126:129], v[146:149], v[178:181], v[126:129]
	v_mfma_f32_16x16x32_bf16 v[122:125], v[154:157], v[178:181], v[122:125]
	v_mfma_f32_16x16x32_bf16 v[118:121], v[146:149], v[186:189], v[118:121]
	v_mfma_f32_16x16x32_bf16 v[114:117], v[154:157], v[186:189], v[114:117]
	v_mfma_f32_16x16x32_bf16 v[106:109], v[146:149], v[200:203], v[106:109]
	v_mfma_f32_16x16x32_bf16 v[98:101], v[154:157], v[200:203], v[98:101]
	v_mfma_f32_16x16x32_bf16 v[90:93], v[146:149], v[208:211], v[90:93]
	v_mfma_f32_16x16x32_bf16 v[82:85], v[154:157], v[208:211], v[82:85]
	s_nop 0
	s_nop 0
	v_mfma_f32_16x16x32_bf16 v[110:113], v[158:161], v[174:177], v[110:113]
	v_mfma_f32_16x16x32_bf16 v[102:105], v[166:169], v[174:177], v[102:105]
	v_mfma_f32_16x16x32_bf16 v[94:97], v[158:161], v[182:185], v[94:97]
	v_mfma_f32_16x16x32_bf16 v[86:89], v[166:169], v[182:185], v[86:89]
	v_mfma_f32_16x16x32_bf16 v[78:81], v[158:161], v[190:193], v[78:81]
	v_mfma_f32_16x16x32_bf16 v[74:77], v[166:169], v[190:193], v[74:77]
	v_mfma_f32_16x16x32_bf16 v[70:73], v[158:161], v[204:207], v[70:73]
	v_mfma_f32_16x16x32_bf16 v[66:69], v[166:169], v[204:207], v[66:69]
	v_mfma_f32_16x16x32_bf16 v[110:113], v[162:165], v[178:181], v[110:113]
	v_mfma_f32_16x16x32_bf16 v[102:105], v[170:173], v[178:181], v[102:105]
	v_mfma_f32_16x16x32_bf16 v[94:97], v[162:165], v[186:189], v[94:97]
	v_mfma_f32_16x16x32_bf16 v[86:89], v[170:173], v[186:189], v[86:89]
	v_mfma_f32_16x16x32_bf16 v[78:81], v[162:165], v[200:203], v[78:81]
	v_mfma_f32_16x16x32_bf16 v[74:77], v[170:173], v[200:203], v[74:77]
	v_mfma_f32_16x16x32_bf16 v[70:73], v[162:165], v[208:211], v[70:73]
	v_mfma_f32_16x16x32_bf16 v[66:69], v[170:173], v[208:211], v[66:69]
	s_nop 0
	s_barrier
	s_add_i32 s48, s74, s29
	v_lshl_add_u64 v[196:197], s[82:83], 0, v[0:1]
	s_mov_b32 m0, s48
	ds_read_b128 v[174:177], v141 offset:16384
	ds_read_b128 v[178:181], v141 offset:17408
	ds_read_b128 v[182:185], v141 offset:18432
	ds_read_b128 v[186:189], v141 offset:19456
	ds_read_b128 v[190:193], v141 offset:20480
	ds_read_b128 v[200:203], v141 offset:21504
	ds_read_b128 v[204:207], v141 offset:22528
	ds_read_b128 v[208:211], v141 offset:23552
	global_load_lds_dwordx4 v[196:197], off
	s_add_i32 m0, s48, 0x2000
	s_add_u32 s48, s82, 0x20000
	v_lshl_add_u64 v[198:199], s[82:83], 0, v[130:131]
	s_addc_u32 s49, s83, 0
	s_add_i32 s74, s75, s29
	global_load_lds_dwordx4 v[198:199], off
	v_lshl_add_u64 v[212:213], s[48:49], 0, v[0:1]
	s_mov_b32 m0, s74
	v_lshl_add_u64 v[214:215], s[84:85], 0, v[130:131]
	global_load_lds_dwordx4 v[212:213], off
	v_lshl_add_u64 v[212:213], s[48:49], 0, v[130:131]
	s_add_i32 m0, s74, 0x2000
	s_nop 0
	global_load_lds_dwordx4 v[212:213], off
	v_lshl_add_u64 v[212:213], s[84:85], 0, v[0:1]
	s_mov_b32 m0, s34
	s_nop 0
	global_load_lds_dwordx4 v[212:213], off
	s_mov_b32 m0, s36
	s_nop 0
	global_load_lds_dwordx4 v[214:215], off
	s_waitcnt vmcnt(8)
	s_waitcnt lgkmcnt(0)
	s_barrier
; #define PG8_STAGE(bufoff, gbase, voff) do { _Pragma("unroll") for (int _i = 0; _i < 2; ++_i) \
;         __builtin_amdgcn_global_load_lds((const unsigned*)((const char*)(gbase) + (voff)[_i]), (LAS unsigned*)(lds + (bufoff) + ldsw + _i * 8192), 16, 0, 0); } while (0)
; #define PG8_LDA(dst, b, h) do { _Pragma("unroll") for (int m = 0; m < 4; ++m) _Pragma("unroll") for (int k = 0; k < 2; ++k) dst[m][k] = *(const LAS bf16x8*)(lds + PG8_SA(b, h) + aoff + m * 2048 + k * 1024); } while (0)
; #define PG8_LDB(dst, b, h) do { _Pragma("unroll") for (int n = 0; n < 2; ++n) _Pragma("unroll") for (int k = 0; k < 2; ++k) dst[n][k] = *(const LAS bf16x8*)(lds + PG8_SB(b, h) + boff + n * 2048 + k * 1024); } while (0)
; #define PG8_MMA(ai, bj, At, Bt) do { __builtin_amdgcn_s_setprio(1); _Pragma("unroll") for (int m = 0; m < 4; ++m) _Pragma("unroll") for (int n = 0; n < 2; ++n) _Pragma("unroll") for (int k = 0; k < 2; ++k) \
;         acc[ai][bj][m][n] = __builtin_amdgcn_mfma_f32_16x16x32_bf16(Bt[n][k], At[m][k], acc[ai][bj][m][n], 0, 0, 0); __builtin_amdgcn_s_setprio(0); } while (0)
; #define PG8_WAIT_V(n) asm volatile("s_waitcnt vmcnt(" #n ")" ::: "memory")
; #define PG8_WAIT_L(n) asm volatile("s_waitcnt lgkmcnt(" #n ")" ::: "memory")
; #define PG8_BAR __builtin_amdgcn_s_barrier()
; #define PG8_SCHED __builtin_amdgcn_sched_barrier(0)
; template <class Epi>
; __device__ __forceinline__ void gemm_phase(LAS unsigned char* lds, const Gemm g, const StaticOrder& S, const Epi& E) {
;     ...
;             PG8_WAIT_V(8); PG8_WAIT_L(0); PG8_BAR; PG8_MMA(0, 0, At, B0); PG8_MMA(0, 1, At, B1); PG8_BAR; PG8_SCHED;
;             PG8_LDA(At, 0, 1); PG8_STAGE(PG8_SB(0, 0), b2, voffB); PG8_STAGE(PG8_SB(0, 1), b2 + hstepB, voffB); PG8_STAGE(PG8_SA(0, 0), a2, voffA);
;             PG8_WAIT_V(8); PG8_WAIT_L(0); PG8_BAR; PG8_MMA(1, 0, At, B0); PG8_MMA(1, 1, At, B1); PG8_BAR; PG8_SCHED;
;             PG8_LDB(B0, 1, 0); PG8_LDB(B1, 1, 1); PG8_SCHED; PG8_LDA(At, 1, 0); PG8_STAGE(PG8_SA(0, 1), a2 + hstepA, voffA);
;             PG8_WAIT_V(8); PG8_WAIT_L(0); PG8_BAR; PG8_MMA(0, 0, At, B0); PG8_MMA(0, 1, At, B1); PG8_BAR; PG8_SCHED;
;             PG8_LDA(At, 1, 1); PG8_STAGE(PG8_SB(1, 0), b3, voffB); PG8_STAGE(PG8_SB(1, 1), b3 + hstepB, voffB); PG8_STAGE(PG8_SA(1, 0), a3, voffA);
	s_nop 0
	s_waitcnt lgkmcnt(0)
	v_mfma_f32_16x16x32_bf16 v[62:65], v[142:145], v[174:177], v[62:65]
	v_mfma_f32_16x16x32_bf16 v[58:61], v[150:153], v[174:177], v[58:61]
	v_mfma_f32_16x16x32_bf16 v[54:57], v[142:145], v[182:185], v[54:57]
	v_mfma_f32_16x16x32_bf16 v[50:53], v[150:153], v[182:185], v[50:53]
	v_mfma_f32_16x16x32_bf16 v[42:45], v[142:145], v[190:193], v[42:45]
	v_mfma_f32_16x16x32_bf16 v[34:37], v[150:153], v[190:193], v[34:37]
	v_mfma_f32_16x16x32_bf16 v[26:29], v[142:145], v[204:207], v[26:29]
	v_mfma_f32_16x16x32_bf16 v[18:21], v[150:153], v[204:207], v[18:21]
	v_mfma_f32_16x16x32_bf16 v[62:65], v[146:149], v[178:181], v[62:65]
	v_mfma_f32_16x16x32_bf16 v[58:61], v[154:157], v[178:181], v[58:61]
	v_mfma_f32_16x16x32_bf16 v[54:57], v[146:149], v[186:189], v[54:57]
	v_mfma_f32_16x16x32_bf16 v[50:53], v[154:157], v[186:189], v[50:53]
	v_mfma_f32_16x16x32_bf16 v[42:45], v[146:149], v[200:203], v[42:45]
	v_mfma_f32_16x16x32_bf16 v[34:37], v[154:157], v[200:203], v[34:37]
	v_mfma_f32_16x16x32_bf16 v[26:29], v[146:149], v[208:211], v[26:29]
	v_mfma_f32_16x16x32_bf16 v[18:21], v[154:157], v[208:211], v[18:21]
	s_nop 0
	s_nop 0
	v_mfma_f32_16x16x32_bf16 v[46:49], v[158:161], v[174:177], v[46:49]
	v_mfma_f32_16x16x32_bf16 v[38:41], v[166:169], v[174:177], v[38:41]
	v_mfma_f32_16x16x32_bf16 v[30:33], v[158:161], v[182:185], v[30:33]
	v_mfma_f32_16x16x32_bf16 v[22:25], v[166:169], v[182:185], v[22:25]
	v_mfma_f32_16x16x32_bf16 v[14:17], v[158:161], v[190:193], v[14:17]
	v_mfma_f32_16x16x32_bf16 v[10:13], v[166:169], v[190:193], v[10:13]
	v_mfma_f32_16x16x32_bf16 v[6:9], v[158:161], v[204:207], v[6:9]
	v_mfma_f32_16x16x32_bf16 v[2:5], v[166:169], v[204:207], v[2:5]
	v_mfma_f32_16x16x32_bf16 v[46:49], v[162:165], v[178:181], v[46:49]
	v_mfma_f32_16x16x32_bf16 v[38:41], v[170:173], v[178:181], v[38:41]
	v_mfma_f32_16x16x32_bf16 v[30:33], v[162:165], v[186:189], v[30:33]
	v_mfma_f32_16x16x32_bf16 v[22:25], v[170:173], v[186:189], v[22:25]
	v_mfma_f32_16x16x32_bf16 v[14:17], v[162:165], v[200:203], v[14:17]
	v_mfma_f32_16x16x32_bf16 v[10:13], v[170:173], v[200:203], v[10:13]
	v_mfma_f32_16x16x32_bf16 v[6:9], v[162:165], v[208:211], v[6:9]
	v_mfma_f32_16x16x32_bf16 v[2:5], v[170:173], v[208:211], v[2:5]
	s_nop 0
	s_barrier
	s_add_i32 s74, 0, 0x18000
	s_add_i32 s75, 0, 0x1c000
	v_add_u32_e32 v154, s74, v140
	v_add_u32_e32 v170, s75, v140
	ds_read_b128 v[142:145], v154
	ds_read_b128 v[146:149], v154 offset:1024
	ds_read_b128 v[150:153], v154 offset:2048
	ds_read_b128 v[154:157], v154 offset:3072
	ds_read_b128 v[158:161], v170
	ds_read_b128 v[162:165], v170 offset:1024
	ds_read_b128 v[166:169], v170 offset:2048
	ds_read_b128 v[170:173], v170 offset:3072
	s_add_u32 s48, s84, 0x20000
	s_addc_u32 s49, s85, 0
	s_mov_b32 m0, s38
	v_lshl_add_u64 v[216:217], s[48:49], 0, v[0:1]
	ds_read_b128 v[174:177], v141 offset:32768
	ds_read_b128 v[178:181], v141 offset:33792
	ds_read_b128 v[182:185], v141 offset:34816
	ds_read_b128 v[186:189], v141 offset:35840
	ds_read_b128 v[190:193], v141 offset:36864
	ds_read_b128 v[200:203], v141 offset:37888
	ds_read_b128 v[204:207], v141 offset:38912
	ds_read_b128 v[208:211], v141 offset:39936
	global_load_lds_dwordx4 v[216:217], off
	v_lshl_add_u64 v[216:217], s[48:49], 0, v[130:131]
	s_mov_b32 m0, s39
	s_nop 0
	global_load_lds_dwordx4 v[216:217], off
	s_waitcnt vmcnt(8)
	s_waitcnt lgkmcnt(0)
	s_barrier
	s_nop 0
	s_waitcnt lgkmcnt(0)
	v_mfma_f32_16x16x32_bf16 v[126:129], v[142:145], v[174:177], v[126:129]
	v_mfma_f32_16x16x32_bf16 v[122:125], v[150:153], v[174:177], v[122:125]
	v_mfma_f32_16x16x32_bf16 v[118:121], v[142:145], v[182:185], v[118:121]
	v_mfma_f32_16x16x32_bf16 v[114:117], v[150:153], v[182:185], v[114:117]
	v_mfma_f32_16x16x32_bf16 v[106:109], v[142:145], v[190:193], v[106:109]
	v_mfma_f32_16x16x32_bf16 v[98:101], v[150:153], v[190:193], v[98:101]
	v_mfma_f32_16x16x32_bf16 v[90:93], v[142:145], v[204:207], v[90:93]
	v_mfma_f32_16x16x32_bf16 v[82:85], v[150:153], v[204:207], v[82:85]
	v_mfma_f32_16x16x32_bf16 v[126:129], v[146:149], v[178:181], v[126:129]
	v_mfma_f32_16x16x32_bf16 v[122:125], v[154:157], v[178:181], v[122:125]
	v_mfma_f32_16x16x32_bf16 v[118:121], v[146:149], v[186:189], v[118:121]
	v_mfma_f32_16x16x32_bf16 v[114:117], v[154:157], v[186:189], v[114:117]
	v_mfma_f32_16x16x32_bf16 v[106:109], v[146:149], v[200:203], v[106:109]
	v_mfma_f32_16x16x32_bf16 v[98:101], v[154:157], v[200:203], v[98:101]
	v_mfma_f32_16x16x32_bf16 v[90:93], v[146:149], v[208:211], v[90:93]
	v_mfma_f32_16x16x32_bf16 v[82:85], v[154:157], v[208:211], v[82:85]
	s_nop 0
	s_nop 0
	v_mfma_f32_16x16x32_bf16 v[110:113], v[158:161], v[174:177], v[110:113]
	v_mfma_f32_16x16x32_bf16 v[102:105], v[166:169], v[174:177], v[102:105]
	v_mfma_f32_16x16x32_bf16 v[94:97], v[158:161], v[182:185], v[94:97]
	v_mfma_f32_16x16x32_bf16 v[86:89], v[166:169], v[182:185], v[86:89]
	v_mfma_f32_16x16x32_bf16 v[78:81], v[158:161], v[190:193], v[78:81]
	v_mfma_f32_16x16x32_bf16 v[74:77], v[166:169], v[190:193], v[74:77]
	v_mfma_f32_16x16x32_bf16 v[70:73], v[158:161], v[204:207], v[70:73]
	v_mfma_f32_16x16x32_bf16 v[66:69], v[166:169], v[204:207], v[66:69]
	v_mfma_f32_16x16x32_bf16 v[110:113], v[162:165], v[178:181], v[110:113]
	v_mfma_f32_16x16x32_bf16 v[102:105], v[170:173], v[178:181], v[102:105]
	v_mfma_f32_16x16x32_bf16 v[94:97], v[162:165], v[186:189], v[94:97]
	v_mfma_f32_16x16x32_bf16 v[86:89], v[170:173], v[186:189], v[86:89]
	v_mfma_f32_16x16x32_bf16 v[78:81], v[162:165], v[200:203], v[78:81]
	v_mfma_f32_16x16x32_bf16 v[74:77], v[170:173], v[200:203], v[74:77]
	v_mfma_f32_16x16x32_bf16 v[70:73], v[162:165], v[208:211], v[70:73]
	v_mfma_f32_16x16x32_bf16 v[66:69], v[170:173], v[208:211], v[66:69]
	s_nop 0
	s_barrier
; #define PG8_STAGE(bufoff, gbase, voff) do { _Pragma("unroll") for (int _i = 0; _i < 2; ++_i) \
;         __builtin_amdgcn_global_load_lds((const unsigned*)((const char*)(gbase) + (voff)[_i]), (LAS unsigned*)(lds + (bufoff) + ldsw + _i * 8192), 16, 0, 0); } while (0)
; #define PG8_LDA(dst, b, h) do { _Pragma("unroll") for (int m = 0; m < 4; ++m) _Pragma("unroll") for (int k = 0; k < 2; ++k) dst[m][k] = *(const LAS bf16x8*)(lds + PG8_SA(b, h) + aoff + m * 2048 + k * 1024); } while (0)
; #define PG8_MMA(ai, bj, At, Bt) do { __builtin_amdgcn_s_setprio(1); _Pragma("unroll") for (int m = 0; m < 4; ++m) _Pragma("unroll") for (int n = 0; n < 2; ++n) _Pragma("unroll") for (int k = 0; k < 2; ++k) \
;         acc[ai][bj][m][n] = __builtin_amdgcn_mfma_f32_16x16x32_bf16(Bt[n][k], At[m][k], acc[ai][bj][m][n], 0, 0, 0); __builtin_amdgcn_s_setprio(0); } while (0)
; #define PG8_WAIT_V(n) asm volatile("s_waitcnt vmcnt(" #n ")" ::: "memory")
; #define PG8_WAIT_L(n) asm volatile("s_waitcnt lgkmcnt(" #n ")" ::: "memory")
; #define PG8_BAR __builtin_amdgcn_s_barrier()
; #define PG8_SCHED __builtin_amdgcn_sched_barrier(0)
; template <class Epi>
; __device__ __forceinline__ void gemm_phase(LAS unsigned char* lds, const Gemm g, const StaticOrder& S, const Epi& E) {
;     ...
;             PG8_WAIT_V(8); PG8_WAIT_L(0); PG8_BAR; PG8_MMA(0, 0, At, B0); PG8_MMA(0, 1, At, B1); PG8_BAR; PG8_SCHED;
;             PG8_LDA(At, 1, 1); PG8_STAGE(PG8_SB(1, 0), b3, voffB); PG8_STAGE(PG8_SB(1, 1), b3 + hstepB, voffB); PG8_STAGE(PG8_SA(1, 0), a3, voffA);
;             PG8_WAIT_V(8); PG8_WAIT_L(0); PG8_BAR; PG8_MMA(1, 0, At, B0); PG8_MMA(1, 1, At, B1); PG8_BAR; PG8_SCHED;
;         }
;         if (wr == 0) PG8_BAR;
;         E(acc, cur, wr, wc, fr, fq);
;         if (!has_next) break;
	s_add_i32 s48, s74, s29
	v_lshl_add_u64 v[196:197], v[196:197], 0, s[64:65]
	s_mov_b32 m0, s48
	ds_read_b128 v[174:177], v141 offset:49152
	ds_read_b128 v[178:181], v141 offset:50176
	ds_read_b128 v[182:185], v141 offset:51200
	ds_read_b128 v[186:189], v141 offset:52224
	ds_read_b128 v[190:193], v141 offset:53248
	ds_read_b128 v[200:203], v141 offset:54272
	ds_read_b128 v[204:207], v141 offset:55296
	ds_read_b128 v[208:211], v141 offset:56320
	global_load_lds_dwordx4 v[196:197], off
	s_add_i32 m0, s48, 0x2000
	s_add_u32 s48, s82, 0x20080
	v_lshl_add_u64 v[196:197], v[198:199], 0, s[64:65]
	s_addc_u32 s49, s83, 0
	s_add_i32 s74, s75, s29
	global_load_lds_dwordx4 v[196:197], off
	v_lshl_add_u64 v[196:197], s[48:49], 0, v[0:1]
	s_mov_b32 m0, s74
	s_nop 0
	global_load_lds_dwordx4 v[196:197], off
	v_lshl_add_u64 v[196:197], s[48:49], 0, v[130:131]
	s_add_i32 m0, s74, 0x2000
	s_nop 0
	global_load_lds_dwordx4 v[196:197], off
	v_lshl_add_u64 v[196:197], v[212:213], 0, s[64:65]
	s_mov_b32 m0, s43
	s_nop 0
	global_load_lds_dwordx4 v[196:197], off
	v_lshl_add_u64 v[196:197], v[214:215], 0, s[64:65]
	s_mov_b32 m0, s60
	s_nop 0
	global_load_lds_dwordx4 v[196:197], off
	s_waitcnt vmcnt(8)
	s_waitcnt lgkmcnt(0)
	s_barrier
	s_nop 0
	s_waitcnt lgkmcnt(0)
	v_mfma_f32_16x16x32_bf16 v[62:65], v[142:145], v[174:177], v[62:65]
	v_mfma_f32_16x16x32_bf16 v[58:61], v[150:153], v[174:177], v[58:61]
	v_mfma_f32_16x16x32_bf16 v[54:57], v[142:145], v[182:185], v[54:57]
	v_mfma_f32_16x16x32_bf16 v[50:53], v[150:153], v[182:185], v[50:53]
	v_mfma_f32_16x16x32_bf16 v[42:45], v[142:145], v[190:193], v[42:45]
	v_mfma_f32_16x16x32_bf16 v[34:37], v[150:153], v[190:193], v[34:37]
	v_mfma_f32_16x16x32_bf16 v[26:29], v[142:145], v[204:207], v[26:29]
	v_mfma_f32_16x16x32_bf16 v[18:21], v[150:153], v[204:207], v[18:21]
	v_mfma_f32_16x16x32_bf16 v[62:65], v[146:149], v[178:181], v[62:65]
	v_mfma_f32_16x16x32_bf16 v[58:61], v[154:157], v[178:181], v[58:61]
	v_mfma_f32_16x16x32_bf16 v[54:57], v[146:149], v[186:189], v[54:57]
	v_mfma_f32_16x16x32_bf16 v[50:53], v[154:157], v[186:189], v[50:53]
	v_mfma_f32_16x16x32_bf16 v[42:45], v[146:149], v[200:203], v[42:45]
	v_mfma_f32_16x16x32_bf16 v[34:37], v[154:157], v[200:203], v[34:37]
	v_mfma_f32_16x16x32_bf16 v[26:29], v[146:149], v[208:211], v[26:29]
	v_mfma_f32_16x16x32_bf16 v[18:21], v[154:157], v[208:211], v[18:21]
	s_nop 0
	s_nop 0
	v_mfma_f32_16x16x32_bf16 v[46:49], v[158:161], v[174:177], v[46:49]
	v_mfma_f32_16x16x32_bf16 v[38:41], v[166:169], v[174:177], v[38:41]
	v_mfma_f32_16x16x32_bf16 v[30:33], v[158:161], v[182:185], v[30:33]
	v_mfma_f32_16x16x32_bf16 v[22:25], v[166:169], v[182:185], v[22:25]
	v_mfma_f32_16x16x32_bf16 v[14:17], v[158:161], v[190:193], v[14:17]
	v_mfma_f32_16x16x32_bf16 v[10:13], v[166:169], v[190:193], v[10:13]
	v_mfma_f32_16x16x32_bf16 v[6:9], v[158:161], v[204:207], v[6:9]
	v_mfma_f32_16x16x32_bf16 v[2:5], v[166:169], v[204:207], v[2:5]
	v_mfma_f32_16x16x32_bf16 v[46:49], v[162:165], v[178:181], v[46:49]
	v_mfma_f32_16x16x32_bf16 v[38:41], v[170:173], v[178:181], v[38:41]
	v_mfma_f32_16x16x32_bf16 v[30:33], v[162:165], v[186:189], v[30:33]
	v_mfma_f32_16x16x32_bf16 v[22:25], v[170:173], v[186:189], v[22:25]
	v_mfma_f32_16x16x32_bf16 v[14:17], v[162:165], v[200:203], v[14:17]
	v_mfma_f32_16x16x32_bf16 v[10:13], v[170:173], v[200:203], v[10:13]
	v_mfma_f32_16x16x32_bf16 v[6:9], v[162:165], v[208:211], v[6:9]
	v_mfma_f32_16x16x32_bf16 v[2:5], v[170:173], v[208:211], v[2:5]
	s_nop 0
	s_barrier
	s_add_i32 s73, s73, 2
	s_add_u32 s80, s80, 0x100
	s_addc_u32 s81, s81, 0
	s_add_u32 s63, s63, 0x100
	s_addc_u32 s72, s72, 0
	s_cmp_gt_u32 s73, 5
	s_cbranch_scc0 .LBB0_711
	s_and_b64 vcc, exec, s[20:21]
	s_cbranch_vccz .LBB0_714
	s_barrier

; #define PG8_STAGE(bufoff, gbase, voff) do { _Pragma("unroll") for (int _i = 0; _i < 2; ++_i) \
;         __builtin_amdgcn_global_load_lds((const unsigned*)((const char*)(gbase) + (voff)[_i]), (LAS unsigned*)(lds + (bufoff) + ldsw + _i * 8192), 16, 0, 0); } while (0)
; #define PG8_LDA(dst, b, h) do { _Pragma("unroll") for (int m = 0; m < 4; ++m) _Pragma("unroll") for (int k = 0; k < 2; ++k) dst[m][k] = *(const LAS bf16x8*)(lds + PG8_SA(b, h) + aoff + m * 2048 + k * 1024); } while (0)
; #define PG8_LDB(dst, b, h) do { _Pragma("unroll") for (int n = 0; n < 2; ++n) _Pragma("unroll") for (int k = 0; k < 2; ++k) dst[n][k] = *(const LAS bf16x8*)(lds + PG8_SB(b, h) + boff + n * 2048 + k * 1024); } while (0)
; #define PG8_MMA(ai, bj, At, Bt) do { __builtin_amdgcn_s_setprio(1); _Pragma("unroll") for (int m = 0; m < 4; ++m) _Pragma("unroll") for (int n = 0; n < 2; ++n) _Pragma("unroll") for (int k = 0; k < 2; ++k) \
;         acc[ai][bj][m][n] = __builtin_amdgcn_mfma_f32_16x16x32_bf16(Bt[n][k], At[m][k], acc[ai][bj][m][n], 0, 0, 0); __builtin_amdgcn_s_setprio(0); } while (0)
; #define PG8_WAIT_V(n) asm volatile("s_waitcnt vmcnt(" #n ")" ::: "memory")
; #define PG8_WAIT_L(n) asm volatile("s_waitcnt lgkmcnt(" #n ")" ::: "memory")
; #define PG8_BAR __builtin_amdgcn_s_barrier()
; #define PG8_SCHED __builtin_amdgcn_sched_barrier(0)
; template <class Epi>
; __device__ __forceinline__ void gemm_phase(LAS unsigned char* lds, const Gemm g, const StaticOrder& S, const Epi& E) {
;     ...
;             const bool last = (t == nt - 2);
;             const char* a1 = cA + (size_t)(t + 1) * kstep;
;             const char* a2 = last ? nA : cA + (size_t)(t + 2) * kstep; const char* b2 = last ? nB : cB + (size_t)(t + 2) * kstep;
;             const char* a3 = a2 + kstep; const char* b3 = b2 + kstep;
;             PG8_LDB(B0, 0, 0); PG8_LDB(B1, 0, 1); PG8_SCHED; PG8_LDA(At, 0, 0); PG8_STAGE(PG8_SA(1, 1), a1 + hstepA, voffA);
;             PG8_WAIT_V(8); PG8_WAIT_L(0); PG8_BAR; PG8_MMA(0, 0, At, B0); PG8_MMA(0, 1, At, B1); PG8_BAR; PG8_SCHED;
;             PG8_LDA(At, 0, 1); PG8_STAGE(PG8_SB(0, 0), b2, voffB); PG8_STAGE(PG8_SB(0, 1), b2 + hstepB, voffB); PG8_STAGE(PG8_SA(0, 0), a2, voffA);
;             PG8_WAIT_V(8); PG8_WAIT_L(0); PG8_BAR; PG8_MMA(1, 0, At, B0); PG8_MMA(1, 1, At, B1); PG8_BAR; PG8_SCHED;
.LBB0_1125:
	s_add_u32 s26, s24, 0xfff80080
	s_addc_u32 s27, s25, -1
	s_add_i32 s48, 0, 0x10000
	s_cmp_eq_u32 s78, 28
	s_cselect_b32 s31, s17, s27
	s_cselect_b32 s30, s72, s26
	s_cselect_b32 s27, s15, s75
	s_cselect_b32 s26, s73, s74
	s_add_i32 s79, 0, 0x14000
	v_add_u32_e32 v142, s48, v177
	v_add_u32_e32 v170, s79, v177
	ds_read_b128 v[130:133], v142
	ds_read_b128 v[134:137], v142 offset:1024
	ds_read_b128 v[138:141], v142 offset:2048
	ds_read_b128 v[142:145], v142 offset:3072
	ds_read_b128 v[146:149], v170
	ds_read_b128 v[150:153], v170 offset:1024
	ds_read_b128 v[166:169], v170 offset:2048
	ds_read_b128 v[170:173], v170 offset:3072
	v_lshl_add_u64 v[174:175], s[24:25], 0, v[162:163]
	s_add_i32 m0, s38, 0xc000
	ds_read_b128 v[180:183], v179
	ds_read_b128 v[184:187], v179 offset:1024
	ds_read_b128 v[188:191], v179 offset:2048
	ds_read_b128 v[196:199], v179 offset:3072
	ds_read_b128 v[200:203], v179 offset:4096
	ds_read_b128 v[204:207], v179 offset:5120
	ds_read_b128 v[208:211], v179 offset:6144
	ds_read_b128 v[212:215], v179 offset:7168
	global_load_lds_dwordx4 v[174:175], off
	v_lshl_add_u64 v[174:175], s[24:25], 0, v[164:165]
	s_add_i32 m0, s38, 0xe000
	s_nop 0
	global_load_lds_dwordx4 v[174:175], off
	s_waitcnt vmcnt(8)
	s_waitcnt lgkmcnt(0)
	s_barrier
	s_nop 0
	s_waitcnt lgkmcnt(0)
	v_mfma_f32_16x16x32_bf16 v[126:129], v[130:133], v[180:183], v[126:129]
	v_mfma_f32_16x16x32_bf16 v[122:125], v[138:141], v[180:183], v[122:125]
	v_mfma_f32_16x16x32_bf16 v[110:113], v[130:133], v[188:191], v[110:113]
	v_mfma_f32_16x16x32_bf16 v[106:109], v[138:141], v[188:191], v[106:109]
	v_mfma_f32_16x16x32_bf16 v[98:101], v[130:133], v[200:203], v[98:101]
	v_mfma_f32_16x16x32_bf16 v[90:93], v[138:141], v[200:203], v[90:93]
	v_mfma_f32_16x16x32_bf16 v[82:85], v[130:133], v[208:211], v[82:85]
	v_mfma_f32_16x16x32_bf16 v[74:77], v[138:141], v[208:211], v[74:77]
	v_mfma_f32_16x16x32_bf16 v[126:129], v[134:137], v[184:187], v[126:129]
	v_mfma_f32_16x16x32_bf16 v[122:125], v[142:145], v[184:187], v[122:125]
	v_mfma_f32_16x16x32_bf16 v[110:113], v[134:137], v[196:199], v[110:113]
	v_mfma_f32_16x16x32_bf16 v[106:109], v[142:145], v[196:199], v[106:109]
	v_mfma_f32_16x16x32_bf16 v[98:101], v[134:137], v[204:207], v[98:101]
	v_mfma_f32_16x16x32_bf16 v[90:93], v[142:145], v[204:207], v[90:93]
	v_mfma_f32_16x16x32_bf16 v[82:85], v[134:137], v[212:215], v[82:85]
	v_mfma_f32_16x16x32_bf16 v[74:77], v[142:145], v[212:215], v[74:77]
	s_nop 0
	s_nop 0
	v_mfma_f32_16x16x32_bf16 v[118:121], v[146:149], v[180:183], v[118:121]
	v_mfma_f32_16x16x32_bf16 v[114:117], v[166:169], v[180:183], v[114:117]
	v_mfma_f32_16x16x32_bf16 v[102:105], v[146:149], v[188:191], v[102:105]
	v_mfma_f32_16x16x32_bf16 v[94:97], v[166:169], v[188:191], v[94:97]
	v_mfma_f32_16x16x32_bf16 v[86:89], v[146:149], v[200:203], v[86:89]
	v_mfma_f32_16x16x32_bf16 v[78:81], v[166:169], v[200:203], v[78:81]
	v_mfma_f32_16x16x32_bf16 v[70:73], v[146:149], v[208:211], v[70:73]
	v_mfma_f32_16x16x32_bf16 v[66:69], v[166:169], v[208:211], v[66:69]
	v_mfma_f32_16x16x32_bf16 v[118:121], v[150:153], v[184:187], v[118:121]
	v_mfma_f32_16x16x32_bf16 v[114:117], v[170:173], v[184:187], v[114:117]
	v_mfma_f32_16x16x32_bf16 v[102:105], v[150:153], v[196:199], v[102:105]
	v_mfma_f32_16x16x32_bf16 v[94:97], v[170:173], v[196:199], v[94:97]
	v_mfma_f32_16x16x32_bf16 v[86:89], v[150:153], v[204:207], v[86:89]
	v_mfma_f32_16x16x32_bf16 v[78:81], v[170:173], v[204:207], v[78:81]
	v_mfma_f32_16x16x32_bf16 v[70:73], v[150:153], v[212:215], v[70:73]
	v_mfma_f32_16x16x32_bf16 v[66:69], v[170:173], v[212:215], v[66:69]
	s_nop 0
	s_barrier
	s_add_i32 s48, s48, s36
	v_lshl_add_u64 v[174:175], s[26:27], 0, v[0:1]
	s_mov_b32 m0, s48
	ds_read_b128 v[180:183], v179 offset:16384
	ds_read_b128 v[184:187], v179 offset:17408
	ds_read_b128 v[188:191], v179 offset:18432
	ds_read_b128 v[196:199], v179 offset:19456
	ds_read_b128 v[200:203], v179 offset:20480
	ds_read_b128 v[204:207], v179 offset:21504
	ds_read_b128 v[208:211], v179 offset:22528
	ds_read_b128 v[212:215], v179 offset:23552
	global_load_lds_dwordx4 v[174:175], off
	s_add_i32 m0, s48, 0x2000
	s_add_u32 s48, s26, 0x80000
	v_lshl_add_u64 v[192:193], s[26:27], 0, v[158:159]
	s_addc_u32 s49, s27, 0
	s_add_i32 s79, s79, s36
	global_load_lds_dwordx4 v[192:193], off
	v_lshl_add_u64 v[216:217], s[48:49], 0, v[0:1]
	s_mov_b32 m0, s79
	v_lshl_add_u64 v[218:219], s[30:31], 0, v[156:157]
	global_load_lds_dwordx4 v[216:217], off
	v_lshl_add_u64 v[216:217], s[48:49], 0, v[158:159]
	s_add_i32 m0, s79, 0x2000
	s_nop 0
	global_load_lds_dwordx4 v[216:217], off
	v_lshl_add_u64 v[216:217], s[30:31], 0, v[154:155]
	s_mov_b32 m0, s38
	s_nop 0
	global_load_lds_dwordx4 v[216:217], off
	s_mov_b32 m0, s39
	s_nop 0
	global_load_lds_dwordx4 v[218:219], off
	s_waitcnt vmcnt(8)
	s_waitcnt lgkmcnt(0)
	s_barrier
; #define PG8_STAGE(bufoff, gbase, voff) do { _Pragma("unroll") for (int _i = 0; _i < 2; ++_i) \
;         __builtin_amdgcn_global_load_lds((const unsigned*)((const char*)(gbase) + (voff)[_i]), (LAS unsigned*)(lds + (bufoff) + ldsw + _i * 8192), 16, 0, 0); } while (0)
; #define PG8_LDA(dst, b, h) do { _Pragma("unroll") for (int m = 0; m < 4; ++m) _Pragma("unroll") for (int k = 0; k < 2; ++k) dst[m][k] = *(const LAS bf16x8*)(lds + PG8_SA(b, h) + aoff + m * 2048 + k * 1024); } while (0)
; #define PG8_LDB(dst, b, h) do { _Pragma("unroll") for (int n = 0; n < 2; ++n) _Pragma("unroll") for (int k = 0; k < 2; ++k) dst[n][k] = *(const LAS bf16x8*)(lds + PG8_SB(b, h) + boff + n * 2048 + k * 1024); } while (0)
; #define PG8_MMA(ai, bj, At, Bt) do { __builtin_amdgcn_s_setprio(1); _Pragma("unroll") for (int m = 0; m < 4; ++m) _Pragma("unroll") for (int n = 0; n < 2; ++n) _Pragma("unroll") for (int k = 0; k < 2; ++k) \
;         acc[ai][bj][m][n] = __builtin_amdgcn_mfma_f32_16x16x32_bf16(Bt[n][k], At[m][k], acc[ai][bj][m][n], 0, 0, 0); __builtin_amdgcn_s_setprio(0); } while (0)
; #define PG8_WAIT_V(n) asm volatile("s_waitcnt vmcnt(" #n ")" ::: "memory")
; #define PG8_WAIT_L(n) asm volatile("s_waitcnt lgkmcnt(" #n ")" ::: "memory")
; #define PG8_BAR __builtin_amdgcn_s_barrier()
; #define PG8_SCHED __builtin_amdgcn_sched_barrier(0)
; template <class Epi>
; __device__ __forceinline__ void gemm_phase(LAS unsigned char* lds, const Gemm g, const StaticOrder& S, const Epi& E) {
;     ...
;             PG8_WAIT_V(8); PG8_WAIT_L(0); PG8_BAR; PG8_MMA(0, 0, At, B0); PG8_MMA(0, 1, At, B1); PG8_BAR; PG8_SCHED;
;             PG8_LDA(At, 0, 1); PG8_STAGE(PG8_SB(0, 0), b2, voffB); PG8_STAGE(PG8_SB(0, 1), b2 + hstepB, voffB); PG8_STAGE(PG8_SA(0, 0), a2, voffA);
;             PG8_WAIT_V(8); PG8_WAIT_L(0); PG8_BAR; PG8_MMA(1, 0, At, B0); PG8_MMA(1, 1, At, B1); PG8_BAR; PG8_SCHED;
;             PG8_LDB(B0, 1, 0); PG8_LDB(B1, 1, 1); PG8_SCHED; PG8_LDA(At, 1, 0); PG8_STAGE(PG8_SA(0, 1), a2 + hstepA, voffA);
;             PG8_WAIT_V(8); PG8_WAIT_L(0); PG8_BAR; PG8_MMA(0, 0, At, B0); PG8_MMA(0, 1, At, B1); PG8_BAR; PG8_SCHED;
;             PG8_LDA(At, 1, 1); PG8_STAGE(PG8_SB(1, 0), b3, voffB); PG8_STAGE(PG8_SB(1, 1), b3 + hstepB, voffB); PG8_STAGE(PG8_SA(1, 0), a3, voffA);
	s_nop 0
	s_waitcnt lgkmcnt(0)
	v_mfma_f32_16x16x32_bf16 v[62:65], v[130:133], v[180:183], v[62:65]
	v_mfma_f32_16x16x32_bf16 v[58:61], v[138:141], v[180:183], v[58:61]
	v_mfma_f32_16x16x32_bf16 v[50:53], v[130:133], v[188:191], v[50:53]
	v_mfma_f32_16x16x32_bf16 v[42:45], v[138:141], v[188:191], v[42:45]
	v_mfma_f32_16x16x32_bf16 v[34:37], v[130:133], v[200:203], v[34:37]
	v_mfma_f32_16x16x32_bf16 v[26:29], v[138:141], v[200:203], v[26:29]
	v_mfma_f32_16x16x32_bf16 v[18:21], v[130:133], v[208:211], v[18:21]
	v_mfma_f32_16x16x32_bf16 v[10:13], v[138:141], v[208:211], v[10:13]
	v_mfma_f32_16x16x32_bf16 v[62:65], v[134:137], v[184:187], v[62:65]
	v_mfma_f32_16x16x32_bf16 v[58:61], v[142:145], v[184:187], v[58:61]
	v_mfma_f32_16x16x32_bf16 v[50:53], v[134:137], v[196:199], v[50:53]
	v_mfma_f32_16x16x32_bf16 v[42:45], v[142:145], v[196:199], v[42:45]
	v_mfma_f32_16x16x32_bf16 v[34:37], v[134:137], v[204:207], v[34:37]
	v_mfma_f32_16x16x32_bf16 v[26:29], v[142:145], v[204:207], v[26:29]
	v_mfma_f32_16x16x32_bf16 v[18:21], v[134:137], v[212:215], v[18:21]
	v_mfma_f32_16x16x32_bf16 v[10:13], v[142:145], v[212:215], v[10:13]
	s_nop 0
	s_nop 0
	v_mfma_f32_16x16x32_bf16 v[54:57], v[146:149], v[180:183], v[54:57]
	v_mfma_f32_16x16x32_bf16 v[46:49], v[166:169], v[180:183], v[46:49]
	v_mfma_f32_16x16x32_bf16 v[38:41], v[146:149], v[188:191], v[38:41]
	v_mfma_f32_16x16x32_bf16 v[30:33], v[166:169], v[188:191], v[30:33]
	v_mfma_f32_16x16x32_bf16 v[22:25], v[146:149], v[200:203], v[22:25]
	v_mfma_f32_16x16x32_bf16 v[14:17], v[166:169], v[200:203], v[14:17]
	v_mfma_f32_16x16x32_bf16 v[6:9], v[146:149], v[208:211], v[6:9]
	v_mfma_f32_16x16x32_bf16 v[2:5], v[166:169], v[208:211], v[2:5]
	v_mfma_f32_16x16x32_bf16 v[54:57], v[150:153], v[184:187], v[54:57]
	v_mfma_f32_16x16x32_bf16 v[46:49], v[170:173], v[184:187], v[46:49]
	v_mfma_f32_16x16x32_bf16 v[38:41], v[150:153], v[196:199], v[38:41]
	v_mfma_f32_16x16x32_bf16 v[30:33], v[170:173], v[196:199], v[30:33]
	v_mfma_f32_16x16x32_bf16 v[22:25], v[150:153], v[204:207], v[22:25]
	v_mfma_f32_16x16x32_bf16 v[14:17], v[170:173], v[204:207], v[14:17]
	v_mfma_f32_16x16x32_bf16 v[6:9], v[150:153], v[212:215], v[6:9]
	v_mfma_f32_16x16x32_bf16 v[2:5], v[170:173], v[212:215], v[2:5]
	s_nop 0
	s_barrier
	s_add_i32 s48, 0, 0x18000
	s_add_i32 s49, 0, 0x1c000
	v_add_u32_e32 v142, s48, v177
	v_add_u32_e32 v170, s49, v177
	ds_read_b128 v[130:133], v142
	ds_read_b128 v[134:137], v142 offset:1024
	ds_read_b128 v[138:141], v142 offset:2048
	ds_read_b128 v[142:145], v142 offset:3072
	ds_read_b128 v[146:149], v170
	ds_read_b128 v[150:153], v170 offset:1024
	ds_read_b128 v[166:169], v170 offset:2048
	ds_read_b128 v[170:173], v170 offset:3072
	s_add_u32 s30, s30, 0x80000
	s_addc_u32 s31, s31, 0
	s_mov_b32 m0, s43
	v_lshl_add_u64 v[220:221], s[30:31], 0, v[154:155]
	ds_read_b128 v[180:183], v179 offset:32768
	ds_read_b128 v[184:187], v179 offset:33792
	ds_read_b128 v[188:191], v179 offset:34816
	ds_read_b128 v[196:199], v179 offset:35840
	ds_read_b128 v[200:203], v179 offset:36864
	ds_read_b128 v[204:207], v179 offset:37888
	ds_read_b128 v[208:211], v179 offset:38912
	ds_read_b128 v[212:215], v179 offset:39936
	global_load_lds_dwordx4 v[220:221], off
	v_lshl_add_u64 v[220:221], s[30:31], 0, v[156:157]
	s_mov_b32 m0, s60
	s_nop 0
	global_load_lds_dwordx4 v[220:221], off
	s_waitcnt vmcnt(8)
	s_waitcnt lgkmcnt(0)
	s_barrier
	s_nop 0
	s_waitcnt lgkmcnt(0)
	v_mfma_f32_16x16x32_bf16 v[126:129], v[130:133], v[180:183], v[126:129]
	v_mfma_f32_16x16x32_bf16 v[122:125], v[138:141], v[180:183], v[122:125]
	v_mfma_f32_16x16x32_bf16 v[110:113], v[130:133], v[188:191], v[110:113]
	v_mfma_f32_16x16x32_bf16 v[106:109], v[138:141], v[188:191], v[106:109]
	v_mfma_f32_16x16x32_bf16 v[98:101], v[130:133], v[200:203], v[98:101]
	v_mfma_f32_16x16x32_bf16 v[90:93], v[138:141], v[200:203], v[90:93]
	v_mfma_f32_16x16x32_bf16 v[82:85], v[130:133], v[208:211], v[82:85]
	v_mfma_f32_16x16x32_bf16 v[74:77], v[138:141], v[208:211], v[74:77]
	v_mfma_f32_16x16x32_bf16 v[126:129], v[134:137], v[184:187], v[126:129]
	v_mfma_f32_16x16x32_bf16 v[122:125], v[142:145], v[184:187], v[122:125]
	v_mfma_f32_16x16x32_bf16 v[110:113], v[134:137], v[196:199], v[110:113]
	v_mfma_f32_16x16x32_bf16 v[106:109], v[142:145], v[196:199], v[106:109]
	v_mfma_f32_16x16x32_bf16 v[98:101], v[134:137], v[204:207], v[98:101]
	v_mfma_f32_16x16x32_bf16 v[90:93], v[142:145], v[204:207], v[90:93]
	v_mfma_f32_16x16x32_bf16 v[82:85], v[134:137], v[212:215], v[82:85]
	v_mfma_f32_16x16x32_bf16 v[74:77], v[142:145], v[212:215], v[74:77]
	s_nop 0
	s_nop 0
	v_mfma_f32_16x16x32_bf16 v[118:121], v[146:149], v[180:183], v[118:121]
	v_mfma_f32_16x16x32_bf16 v[114:117], v[166:169], v[180:183], v[114:117]
	v_mfma_f32_16x16x32_bf16 v[102:105], v[146:149], v[188:191], v[102:105]
	v_mfma_f32_16x16x32_bf16 v[94:97], v[166:169], v[188:191], v[94:97]
	v_mfma_f32_16x16x32_bf16 v[86:89], v[146:149], v[200:203], v[86:89]
	v_mfma_f32_16x16x32_bf16 v[78:81], v[166:169], v[200:203], v[78:81]
	v_mfma_f32_16x16x32_bf16 v[70:73], v[146:149], v[208:211], v[70:73]
	v_mfma_f32_16x16x32_bf16 v[66:69], v[166:169], v[208:211], v[66:69]
	v_mfma_f32_16x16x32_bf16 v[118:121], v[150:153], v[184:187], v[118:121]
	v_mfma_f32_16x16x32_bf16 v[114:117], v[170:173], v[184:187], v[114:117]
	v_mfma_f32_16x16x32_bf16 v[102:105], v[150:153], v[196:199], v[102:105]
	v_mfma_f32_16x16x32_bf16 v[94:97], v[170:173], v[196:199], v[94:97]
	v_mfma_f32_16x16x32_bf16 v[86:89], v[150:153], v[204:207], v[86:89]
	v_mfma_f32_16x16x32_bf16 v[78:81], v[170:173], v[204:207], v[78:81]
	v_mfma_f32_16x16x32_bf16 v[70:73], v[150:153], v[212:215], v[70:73]
	v_mfma_f32_16x16x32_bf16 v[66:69], v[170:173], v[212:215], v[66:69]
	s_nop 0
	s_barrier
; #define PG8_STAGE(bufoff, gbase, voff) do { _Pragma("unroll") for (int _i = 0; _i < 2; ++_i) \
;         __builtin_amdgcn_global_load_lds((const unsigned*)((const char*)(gbase) + (voff)[_i]), (LAS unsigned*)(lds + (bufoff) + ldsw + _i * 8192), 16, 0, 0); } while (0)
; #define PG8_LDA(dst, b, h) do { _Pragma("unroll") for (int m = 0; m < 4; ++m) _Pragma("unroll") for (int k = 0; k < 2; ++k) dst[m][k] = *(const LAS bf16x8*)(lds + PG8_SA(b, h) + aoff + m * 2048 + k * 1024); } while (0)
; #define PG8_MMA(ai, bj, At, Bt) do { __builtin_amdgcn_s_setprio(1); _Pragma("unroll") for (int m = 0; m < 4; ++m) _Pragma("unroll") for (int n = 0; n < 2; ++n) _Pragma("unroll") for (int k = 0; k < 2; ++k) \
;         acc[ai][bj][m][n] = __builtin_amdgcn_mfma_f32_16x16x32_bf16(Bt[n][k], At[m][k], acc[ai][bj][m][n], 0, 0, 0); __builtin_amdgcn_s_setprio(0); } while (0)
; #define PG8_WAIT_V(n) asm volatile("s_waitcnt vmcnt(" #n ")" ::: "memory")
; #define PG8_WAIT_L(n) asm volatile("s_waitcnt lgkmcnt(" #n ")" ::: "memory")
; #define PG8_BAR __builtin_amdgcn_s_barrier()
; #define PG8_SCHED __builtin_amdgcn_sched_barrier(0)
; template <class Epi>
; __device__ __forceinline__ void gemm_phase(LAS unsigned char* lds, const Gemm g, const StaticOrder& S, const Epi& E) {
;     ...
;             PG8_WAIT_V(8); PG8_WAIT_L(0); PG8_BAR; PG8_MMA(0, 0, At, B0); PG8_MMA(0, 1, At, B1); PG8_BAR; PG8_SCHED;
;             PG8_LDA(At, 1, 1); PG8_STAGE(PG8_SB(1, 0), b3, voffB); PG8_STAGE(PG8_SB(1, 1), b3 + hstepB, voffB); PG8_STAGE(PG8_SA(1, 0), a3, voffA);
;             PG8_WAIT_V(8); PG8_WAIT_L(0); PG8_BAR; PG8_MMA(1, 0, At, B0); PG8_MMA(1, 1, At, B1); PG8_BAR; PG8_SCHED;
;         }
;         if (wr == 0) PG8_BAR;
;         E(acc, cur, wr, wc, fr, fq);
;         if (!has_next) break;
	s_add_i32 s30, s48, s36
	v_lshl_add_u64 v[174:175], v[174:175], 0, s[64:65]
	s_mov_b32 m0, s30
	ds_read_b128 v[180:183], v179 offset:49152
	ds_read_b128 v[184:187], v179 offset:50176
	ds_read_b128 v[188:191], v179 offset:51200
	ds_read_b128 v[196:199], v179 offset:52224
	ds_read_b128 v[200:203], v179 offset:53248
	ds_read_b128 v[204:207], v179 offset:54272
	ds_read_b128 v[208:211], v179 offset:55296
	ds_read_b128 v[212:215], v179 offset:56320
	global_load_lds_dwordx4 v[174:175], off
	s_add_i32 m0, s30, 0x2000
	s_add_u32 s26, s26, 0x80080
	v_lshl_add_u64 v[174:175], v[192:193], 0, s[64:65]
	s_addc_u32 s27, s27, 0
	s_add_i32 s30, s49, s36
	global_load_lds_dwordx4 v[174:175], off
	v_lshl_add_u64 v[174:175], s[26:27], 0, v[0:1]
	s_mov_b32 m0, s30
	s_nop 0
	global_load_lds_dwordx4 v[174:175], off
	v_lshl_add_u64 v[174:175], s[26:27], 0, v[158:159]
	s_add_i32 m0, s30, 0x2000
	s_nop 0
	global_load_lds_dwordx4 v[174:175], off
	v_lshl_add_u64 v[174:175], v[216:217], 0, s[64:65]
	s_mov_b32 m0, s61
	s_nop 0
	global_load_lds_dwordx4 v[174:175], off
	v_lshl_add_u64 v[174:175], v[218:219], 0, s[64:65]
	s_mov_b32 m0, s62
	s_nop 0
	global_load_lds_dwordx4 v[174:175], off
	s_waitcnt vmcnt(8)
	s_waitcnt lgkmcnt(0)
	s_barrier
	s_nop 0
	s_waitcnt lgkmcnt(0)
	v_mfma_f32_16x16x32_bf16 v[62:65], v[130:133], v[180:183], v[62:65]
	v_mfma_f32_16x16x32_bf16 v[58:61], v[138:141], v[180:183], v[58:61]
	v_mfma_f32_16x16x32_bf16 v[50:53], v[130:133], v[188:191], v[50:53]
	v_mfma_f32_16x16x32_bf16 v[42:45], v[138:141], v[188:191], v[42:45]
	v_mfma_f32_16x16x32_bf16 v[34:37], v[130:133], v[200:203], v[34:37]
	v_mfma_f32_16x16x32_bf16 v[26:29], v[138:141], v[200:203], v[26:29]
	v_mfma_f32_16x16x32_bf16 v[18:21], v[130:133], v[208:211], v[18:21]
	v_mfma_f32_16x16x32_bf16 v[10:13], v[138:141], v[208:211], v[10:13]
	v_mfma_f32_16x16x32_bf16 v[62:65], v[134:137], v[184:187], v[62:65]
	v_mfma_f32_16x16x32_bf16 v[58:61], v[142:145], v[184:187], v[58:61]
	v_mfma_f32_16x16x32_bf16 v[50:53], v[134:137], v[196:199], v[50:53]
	v_mfma_f32_16x16x32_bf16 v[42:45], v[142:145], v[196:199], v[42:45]
	v_mfma_f32_16x16x32_bf16 v[34:37], v[134:137], v[204:207], v[34:37]
	v_mfma_f32_16x16x32_bf16 v[26:29], v[142:145], v[204:207], v[26:29]
	v_mfma_f32_16x16x32_bf16 v[18:21], v[134:137], v[212:215], v[18:21]
	v_mfma_f32_16x16x32_bf16 v[10:13], v[142:145], v[212:215], v[10:13]
	s_nop 0
	s_nop 0
	v_mfma_f32_16x16x32_bf16 v[54:57], v[146:149], v[180:183], v[54:57]
	v_mfma_f32_16x16x32_bf16 v[46:49], v[166:169], v[180:183], v[46:49]
	v_mfma_f32_16x16x32_bf16 v[38:41], v[146:149], v[188:191], v[38:41]
	v_mfma_f32_16x16x32_bf16 v[30:33], v[166:169], v[188:191], v[30:33]
	v_mfma_f32_16x16x32_bf16 v[22:25], v[146:149], v[200:203], v[22:25]
	v_mfma_f32_16x16x32_bf16 v[14:17], v[166:169], v[200:203], v[14:17]
	v_mfma_f32_16x16x32_bf16 v[6:9], v[146:149], v[208:211], v[6:9]
	v_mfma_f32_16x16x32_bf16 v[2:5], v[166:169], v[208:211], v[2:5]
	v_mfma_f32_16x16x32_bf16 v[54:57], v[150:153], v[184:187], v[54:57]
	v_mfma_f32_16x16x32_bf16 v[46:49], v[170:173], v[184:187], v[46:49]
	v_mfma_f32_16x16x32_bf16 v[38:41], v[150:153], v[196:199], v[38:41]
	v_mfma_f32_16x16x32_bf16 v[30:33], v[170:173], v[196:199], v[30:33]
	v_mfma_f32_16x16x32_bf16 v[22:25], v[150:153], v[204:207], v[22:25]
	v_mfma_f32_16x16x32_bf16 v[14:17], v[170:173], v[204:207], v[14:17]
	v_mfma_f32_16x16x32_bf16 v[6:9], v[150:153], v[212:215], v[6:9]
	v_mfma_f32_16x16x32_bf16 v[2:5], v[170:173], v[212:215], v[2:5]
	s_nop 0
	s_barrier
	s_add_i32 s78, s78, 2
	s_add_u32 s24, s24, 0x100
	s_addc_u32 s25, s25, 0
	s_add_u32 s74, s74, 0x100
	s_addc_u32 s75, s75, 0
	s_cmp_gt_u32 s78, 29
	s_cbranch_scc0 .LBB0_1125
	s_and_b64 vcc, exec, s[12:13]
	s_cbranch_vccz .LBB0_1128
	s_barrier

; #define PG8_STAGE(bufoff, gbase, voff) do { _Pragma("unroll") for (int _i = 0; _i < 2; ++_i) \
;         __builtin_amdgcn_global_load_lds((const unsigned*)((const char*)(gbase) + (voff)[_i]), (LAS unsigned*)(lds + (bufoff) + ldsw + _i * 8192), 16, 0, 0); } while (0)
; #define PG8_LDA(dst, b, h) do { _Pragma("unroll") for (int m = 0; m < 4; ++m) _Pragma("unroll") for (int k = 0; k < 2; ++k) dst[m][k] = *(const LAS bf16x8*)(lds + PG8_SA(b, h) + aoff + m * 2048 + k * 1024); } while (0)
; #define PG8_LDB(dst, b, h) do { _Pragma("unroll") for (int n = 0; n < 2; ++n) _Pragma("unroll") for (int k = 0; k < 2; ++k) dst[n][k] = *(const LAS bf16x8*)(lds + PG8_SB(b, h) + boff + n * 2048 + k * 1024); } while (0)
; #define PG8_MMA(ai, bj, At, Bt) do { __builtin_amdgcn_s_setprio(1); _Pragma("unroll") for (int m = 0; m < 4; ++m) _Pragma("unroll") for (int n = 0; n < 2; ++n) _Pragma("unroll") for (int k = 0; k < 2; ++k) \
;         acc[ai][bj][m][n] = __builtin_amdgcn_mfma_f32_16x16x32_bf16(Bt[n][k], At[m][k], acc[ai][bj][m][n], 0, 0, 0); __builtin_amdgcn_s_setprio(0); } while (0)
; #define PG8_WAIT_V(n) asm volatile("s_waitcnt vmcnt(" #n ")" ::: "memory")
; #define PG8_WAIT_L(n) asm volatile("s_waitcnt lgkmcnt(" #n ")" ::: "memory")
; #define PG8_BAR __builtin_amdgcn_s_barrier()
; #define PG8_SCHED __builtin_amdgcn_sched_barrier(0)
; template <class Epi>
; __device__ __forceinline__ void gemm_phase(LAS unsigned char* lds, const Gemm g, const StaticOrder& S, const Epi& E) {
;     ...
;             const bool last = (t == nt - 2);
;             const char* a1 = cA + (size_t)(t + 1) * kstep;
;             const char* a2 = last ? nA : cA + (size_t)(t + 2) * kstep; const char* b2 = last ? nB : cB + (size_t)(t + 2) * kstep;
;             const char* a3 = a2 + kstep; const char* b3 = b2 + kstep;
;             PG8_LDB(B0, 0, 0); PG8_LDB(B1, 0, 1); PG8_SCHED; PG8_LDA(At, 0, 0); PG8_STAGE(PG8_SA(1, 1), a1 + hstepA, voffA);
;             PG8_WAIT_V(8); PG8_WAIT_L(0); PG8_BAR; PG8_MMA(0, 0, At, B0); PG8_MMA(0, 1, At, B1); PG8_BAR; PG8_SCHED;
;             PG8_LDA(At, 0, 1); PG8_STAGE(PG8_SB(0, 0), b2, voffB); PG8_STAGE(PG8_SB(0, 1), b2 + hstepB, voffB); PG8_STAGE(PG8_SA(0, 0), a2, voffA);
;             PG8_WAIT_V(8); PG8_WAIT_L(0); PG8_BAR; PG8_MMA(1, 0, At, B0); PG8_MMA(1, 1, At, B1); PG8_BAR; PG8_SCHED;
.LBB0_1150:
	s_add_u32 s48, s30, 0xfff80080
	s_addc_u32 s49, s31, -1
	s_add_i32 s83, 0, 0x10000
	s_cmp_eq_u32 s82, 28
	s_cselect_b32 s81, s21, s49
	s_cselect_b32 s80, s72, s48
	s_cselect_b32 s79, s19, s75
	s_cselect_b32 s78, s73, s74
	s_add_i32 s84, 0, 0x14000
	v_add_u32_e32 v142, s83, v224
	v_add_u32_e32 v158, s84, v224
	ds_read_b128 v[130:133], v142
	ds_read_b128 v[134:137], v142 offset:1024
	ds_read_b128 v[138:141], v142 offset:2048
	ds_read_b128 v[142:145], v142 offset:3072
	ds_read_b128 v[146:149], v158
	ds_read_b128 v[150:153], v158 offset:1024
	ds_read_b128 v[154:157], v158 offset:2048
	ds_read_b128 v[158:161], v158 offset:3072
	v_lshl_add_u64 v[196:197], s[30:31], 0, v[206:207]
	s_add_i32 m0, s38, 0xc000
	ds_read_b128 v[162:165], v236
	ds_read_b128 v[166:169], v236 offset:1024
	ds_read_b128 v[170:173], v236 offset:2048
	ds_read_b128 v[174:177], v236 offset:3072
	ds_read_b128 v[178:181], v236 offset:4096
	ds_read_b128 v[182:185], v236 offset:5120
	ds_read_b128 v[186:189], v236 offset:6144
	ds_read_b128 v[190:193], v236 offset:7168
	global_load_lds_dwordx4 v[196:197], off
	v_lshl_add_u64 v[196:197], s[30:31], 0, v[208:209]
	s_add_i32 m0, s38, 0xe000
	s_nop 0
	global_load_lds_dwordx4 v[196:197], off
	s_waitcnt vmcnt(8)
	s_waitcnt lgkmcnt(0)
	s_barrier
	s_nop 0
	s_waitcnt lgkmcnt(0)
	v_mfma_f32_16x16x32_bf16 v[126:129], v[130:133], v[162:165], v[126:129]
	v_mfma_f32_16x16x32_bf16 v[122:125], v[138:141], v[162:165], v[122:125]
	v_mfma_f32_16x16x32_bf16 v[114:117], v[130:133], v[170:173], v[114:117]
	v_mfma_f32_16x16x32_bf16 v[106:109], v[138:141], v[170:173], v[106:109]
	v_mfma_f32_16x16x32_bf16 v[98:101], v[130:133], v[178:181], v[98:101]
	v_mfma_f32_16x16x32_bf16 v[90:93], v[138:141], v[178:181], v[90:93]
	v_mfma_f32_16x16x32_bf16 v[82:85], v[130:133], v[186:189], v[82:85]
	v_mfma_f32_16x16x32_bf16 v[74:77], v[138:141], v[186:189], v[74:77]
	v_mfma_f32_16x16x32_bf16 v[126:129], v[134:137], v[166:169], v[126:129]
	v_mfma_f32_16x16x32_bf16 v[122:125], v[142:145], v[166:169], v[122:125]
	v_mfma_f32_16x16x32_bf16 v[114:117], v[134:137], v[174:177], v[114:117]
	v_mfma_f32_16x16x32_bf16 v[106:109], v[142:145], v[174:177], v[106:109]
	v_mfma_f32_16x16x32_bf16 v[98:101], v[134:137], v[182:185], v[98:101]
	v_mfma_f32_16x16x32_bf16 v[90:93], v[142:145], v[182:185], v[90:93]
	v_mfma_f32_16x16x32_bf16 v[82:85], v[134:137], v[190:193], v[82:85]
	v_mfma_f32_16x16x32_bf16 v[74:77], v[142:145], v[190:193], v[74:77]
	s_nop 0
	s_nop 0
	v_mfma_f32_16x16x32_bf16 v[118:121], v[146:149], v[162:165], v[118:121]
	v_mfma_f32_16x16x32_bf16 v[110:113], v[154:157], v[162:165], v[110:113]
	v_mfma_f32_16x16x32_bf16 v[102:105], v[146:149], v[170:173], v[102:105]
	v_mfma_f32_16x16x32_bf16 v[94:97], v[154:157], v[170:173], v[94:97]
	v_mfma_f32_16x16x32_bf16 v[86:89], v[146:149], v[178:181], v[86:89]
	v_mfma_f32_16x16x32_bf16 v[78:81], v[154:157], v[178:181], v[78:81]
	v_mfma_f32_16x16x32_bf16 v[70:73], v[146:149], v[186:189], v[70:73]
	v_mfma_f32_16x16x32_bf16 v[66:69], v[154:157], v[186:189], v[66:69]
	v_mfma_f32_16x16x32_bf16 v[118:121], v[150:153], v[166:169], v[118:121]
	v_mfma_f32_16x16x32_bf16 v[110:113], v[158:161], v[166:169], v[110:113]
	v_mfma_f32_16x16x32_bf16 v[102:105], v[150:153], v[174:177], v[102:105]
	v_mfma_f32_16x16x32_bf16 v[94:97], v[158:161], v[174:177], v[94:97]
	v_mfma_f32_16x16x32_bf16 v[86:89], v[150:153], v[182:185], v[86:89]
	v_mfma_f32_16x16x32_bf16 v[78:81], v[158:161], v[182:185], v[78:81]
	v_mfma_f32_16x16x32_bf16 v[70:73], v[150:153], v[190:193], v[70:73]
	v_mfma_f32_16x16x32_bf16 v[66:69], v[158:161], v[190:193], v[66:69]
	s_nop 0
	s_barrier
	s_add_i32 s48, s83, s36
	v_lshl_add_u64 v[196:197], s[78:79], 0, v[0:1]
	s_mov_b32 m0, s48
	ds_read_b128 v[162:165], v236 offset:16384
	ds_read_b128 v[166:169], v236 offset:17408
	ds_read_b128 v[170:173], v236 offset:18432
	ds_read_b128 v[174:177], v236 offset:19456
	ds_read_b128 v[178:181], v236 offset:20480
	ds_read_b128 v[182:185], v236 offset:21504
	ds_read_b128 v[186:189], v236 offset:22528
	ds_read_b128 v[190:193], v236 offset:23552
	global_load_lds_dwordx4 v[196:197], off
	s_add_i32 m0, s48, 0x2000
	s_add_u32 s48, s78, 0x80000
	v_lshl_add_u64 v[198:199], s[78:79], 0, v[204:205]
	s_addc_u32 s49, s79, 0
	s_add_i32 s83, s84, s36
	global_load_lds_dwordx4 v[198:199], off
	v_lshl_add_u64 v[210:211], s[48:49], 0, v[0:1]
	s_mov_b32 m0, s83
	v_lshl_add_u64 v[212:213], s[80:81], 0, v[202:203]
	global_load_lds_dwordx4 v[210:211], off
	v_lshl_add_u64 v[210:211], s[48:49], 0, v[204:205]
	s_add_i32 m0, s83, 0x2000
	s_nop 0
	global_load_lds_dwordx4 v[210:211], off
	v_lshl_add_u64 v[210:211], s[80:81], 0, v[200:201]
	s_mov_b32 m0, s38
	s_nop 0
	global_load_lds_dwordx4 v[210:211], off
	s_mov_b32 m0, s39
	s_nop 0
	global_load_lds_dwordx4 v[212:213], off
	s_waitcnt vmcnt(8)
	s_waitcnt lgkmcnt(0)
	s_barrier
; #define PG8_STAGE(bufoff, gbase, voff) do { _Pragma("unroll") for (int _i = 0; _i < 2; ++_i) \
;         __builtin_amdgcn_global_load_lds((const unsigned*)((const char*)(gbase) + (voff)[_i]), (LAS unsigned*)(lds + (bufoff) + ldsw + _i * 8192), 16, 0, 0); } while (0)
; #define PG8_LDA(dst, b, h) do { _Pragma("unroll") for (int m = 0; m < 4; ++m) _Pragma("unroll") for (int k = 0; k < 2; ++k) dst[m][k] = *(const LAS bf16x8*)(lds + PG8_SA(b, h) + aoff + m * 2048 + k * 1024); } while (0)
; #define PG8_LDB(dst, b, h) do { _Pragma("unroll") for (int n = 0; n < 2; ++n) _Pragma("unroll") for (int k = 0; k < 2; ++k) dst[n][k] = *(const LAS bf16x8*)(lds + PG8_SB(b, h) + boff + n * 2048 + k * 1024); } while (0)
; #define PG8_MMA(ai, bj, At, Bt) do { __builtin_amdgcn_s_setprio(1); _Pragma("unroll") for (int m = 0; m < 4; ++m) _Pragma("unroll") for (int n = 0; n < 2; ++n) _Pragma("unroll") for (int k = 0; k < 2; ++k) \
;         acc[ai][bj][m][n] = __builtin_amdgcn_mfma_f32_16x16x32_bf16(Bt[n][k], At[m][k], acc[ai][bj][m][n], 0, 0, 0); __builtin_amdgcn_s_setprio(0); } while (0)
; #define PG8_WAIT_V(n) asm volatile("s_waitcnt vmcnt(" #n ")" ::: "memory")
; #define PG8_WAIT_L(n) asm volatile("s_waitcnt lgkmcnt(" #n ")" ::: "memory")
; #define PG8_BAR __builtin_amdgcn_s_barrier()
; #define PG8_SCHED __builtin_amdgcn_sched_barrier(0)
; template <class Epi>
; __device__ __forceinline__ void gemm_phase(LAS unsigned char* lds, const Gemm g, const StaticOrder& S, const Epi& E) {
;     ...
;             PG8_WAIT_V(8); PG8_WAIT_L(0); PG8_BAR; PG8_MMA(0, 0, At, B0); PG8_MMA(0, 1, At, B1); PG8_BAR; PG8_SCHED;
;             PG8_LDA(At, 0, 1); PG8_STAGE(PG8_SB(0, 0), b2, voffB); PG8_STAGE(PG8_SB(0, 1), b2 + hstepB, voffB); PG8_STAGE(PG8_SA(0, 0), a2, voffA);
;             PG8_WAIT_V(8); PG8_WAIT_L(0); PG8_BAR; PG8_MMA(1, 0, At, B0); PG8_MMA(1, 1, At, B1); PG8_BAR; PG8_SCHED;
;             PG8_LDB(B0, 1, 0); PG8_LDB(B1, 1, 1); PG8_SCHED; PG8_LDA(At, 1, 0); PG8_STAGE(PG8_SA(0, 1), a2 + hstepA, voffA);
;             PG8_WAIT_V(8); PG8_WAIT_L(0); PG8_BAR; PG8_MMA(0, 0, At, B0); PG8_MMA(0, 1, At, B1); PG8_BAR; PG8_SCHED;
;             PG8_LDA(At, 1, 1); PG8_STAGE(PG8_SB(1, 0), b3, voffB); PG8_STAGE(PG8_SB(1, 1), b3 + hstepB, voffB); PG8_STAGE(PG8_SA(1, 0), a3, voffA);
	s_nop 0
	s_waitcnt lgkmcnt(0)
	v_mfma_f32_16x16x32_bf16 v[62:65], v[130:133], v[162:165], v[62:65]
	v_mfma_f32_16x16x32_bf16 v[58:61], v[138:141], v[162:165], v[58:61]
	v_mfma_f32_16x16x32_bf16 v[50:53], v[130:133], v[170:173], v[50:53]
	v_mfma_f32_16x16x32_bf16 v[42:45], v[138:141], v[170:173], v[42:45]
	v_mfma_f32_16x16x32_bf16 v[34:37], v[130:133], v[178:181], v[34:37]
	v_mfma_f32_16x16x32_bf16 v[26:29], v[138:141], v[178:181], v[26:29]
	v_mfma_f32_16x16x32_bf16 v[18:21], v[130:133], v[186:189], v[18:21]
	v_mfma_f32_16x16x32_bf16 v[10:13], v[138:141], v[186:189], v[10:13]
	v_mfma_f32_16x16x32_bf16 v[62:65], v[134:137], v[166:169], v[62:65]
	v_mfma_f32_16x16x32_bf16 v[58:61], v[142:145], v[166:169], v[58:61]
	v_mfma_f32_16x16x32_bf16 v[50:53], v[134:137], v[174:177], v[50:53]
	v_mfma_f32_16x16x32_bf16 v[42:45], v[142:145], v[174:177], v[42:45]
	v_mfma_f32_16x16x32_bf16 v[34:37], v[134:137], v[182:185], v[34:37]
	v_mfma_f32_16x16x32_bf16 v[26:29], v[142:145], v[182:185], v[26:29]
	v_mfma_f32_16x16x32_bf16 v[18:21], v[134:137], v[190:193], v[18:21]
	v_mfma_f32_16x16x32_bf16 v[10:13], v[142:145], v[190:193], v[10:13]
	s_nop 0
	s_nop 0
	v_mfma_f32_16x16x32_bf16 v[54:57], v[146:149], v[162:165], v[54:57]
	v_mfma_f32_16x16x32_bf16 v[46:49], v[154:157], v[162:165], v[46:49]
	v_mfma_f32_16x16x32_bf16 v[38:41], v[146:149], v[170:173], v[38:41]
	v_mfma_f32_16x16x32_bf16 v[30:33], v[154:157], v[170:173], v[30:33]
	v_mfma_f32_16x16x32_bf16 v[22:25], v[146:149], v[178:181], v[22:25]
	v_mfma_f32_16x16x32_bf16 v[14:17], v[154:157], v[178:181], v[14:17]
	v_mfma_f32_16x16x32_bf16 v[6:9], v[146:149], v[186:189], v[6:9]
	v_mfma_f32_16x16x32_bf16 v[2:5], v[154:157], v[186:189], v[2:5]
	v_mfma_f32_16x16x32_bf16 v[54:57], v[150:153], v[166:169], v[54:57]
	v_mfma_f32_16x16x32_bf16 v[46:49], v[158:161], v[166:169], v[46:49]
	v_mfma_f32_16x16x32_bf16 v[38:41], v[150:153], v[174:177], v[38:41]
	v_mfma_f32_16x16x32_bf16 v[30:33], v[158:161], v[174:177], v[30:33]
	v_mfma_f32_16x16x32_bf16 v[22:25], v[150:153], v[182:185], v[22:25]
	v_mfma_f32_16x16x32_bf16 v[14:17], v[158:161], v[182:185], v[14:17]
	v_mfma_f32_16x16x32_bf16 v[6:9], v[150:153], v[190:193], v[6:9]
	v_mfma_f32_16x16x32_bf16 v[2:5], v[158:161], v[190:193], v[2:5]
	s_nop 0
	s_barrier
	s_add_i32 s83, 0, 0x18000
	s_add_i32 s84, 0, 0x1c000
	v_add_u32_e32 v142, s83, v224
	v_add_u32_e32 v158, s84, v224
	ds_read_b128 v[130:133], v142
	ds_read_b128 v[134:137], v142 offset:1024
	ds_read_b128 v[138:141], v142 offset:2048
	ds_read_b128 v[142:145], v142 offset:3072
	ds_read_b128 v[146:149], v158
	ds_read_b128 v[150:153], v158 offset:1024
	ds_read_b128 v[154:157], v158 offset:2048
	ds_read_b128 v[158:161], v158 offset:3072
	s_add_u32 s48, s80, 0x80000
	s_addc_u32 s49, s81, 0
	s_mov_b32 m0, s43
	v_lshl_add_u64 v[214:215], s[48:49], 0, v[200:201]
	ds_read_b128 v[162:165], v236 offset:32768
	ds_read_b128 v[166:169], v236 offset:33792
	ds_read_b128 v[170:173], v236 offset:34816
	ds_read_b128 v[174:177], v236 offset:35840
	ds_read_b128 v[178:181], v236 offset:36864
	ds_read_b128 v[182:185], v236 offset:37888
	ds_read_b128 v[186:189], v236 offset:38912
	ds_read_b128 v[190:193], v236 offset:39936
	global_load_lds_dwordx4 v[214:215], off
	v_lshl_add_u64 v[214:215], s[48:49], 0, v[202:203]
	s_mov_b32 m0, s60
	s_nop 0
	global_load_lds_dwordx4 v[214:215], off
	s_waitcnt vmcnt(8)
	s_waitcnt lgkmcnt(0)
	s_barrier
	s_nop 0
	s_waitcnt lgkmcnt(0)
	v_mfma_f32_16x16x32_bf16 v[126:129], v[130:133], v[162:165], v[126:129]
	v_mfma_f32_16x16x32_bf16 v[122:125], v[138:141], v[162:165], v[122:125]
	v_mfma_f32_16x16x32_bf16 v[114:117], v[130:133], v[170:173], v[114:117]
	v_mfma_f32_16x16x32_bf16 v[106:109], v[138:141], v[170:173], v[106:109]
	v_mfma_f32_16x16x32_bf16 v[98:101], v[130:133], v[178:181], v[98:101]
	v_mfma_f32_16x16x32_bf16 v[90:93], v[138:141], v[178:181], v[90:93]
	v_mfma_f32_16x16x32_bf16 v[82:85], v[130:133], v[186:189], v[82:85]
	v_mfma_f32_16x16x32_bf16 v[74:77], v[138:141], v[186:189], v[74:77]
	v_mfma_f32_16x16x32_bf16 v[126:129], v[134:137], v[166:169], v[126:129]
	v_mfma_f32_16x16x32_bf16 v[122:125], v[142:145], v[166:169], v[122:125]
	v_mfma_f32_16x16x32_bf16 v[114:117], v[134:137], v[174:177], v[114:117]
	v_mfma_f32_16x16x32_bf16 v[106:109], v[142:145], v[174:177], v[106:109]
	v_mfma_f32_16x16x32_bf16 v[98:101], v[134:137], v[182:185], v[98:101]
	v_mfma_f32_16x16x32_bf16 v[90:93], v[142:145], v[182:185], v[90:93]
	v_mfma_f32_16x16x32_bf16 v[82:85], v[134:137], v[190:193], v[82:85]
	v_mfma_f32_16x16x32_bf16 v[74:77], v[142:145], v[190:193], v[74:77]
	s_nop 0
	s_nop 0
	v_mfma_f32_16x16x32_bf16 v[118:121], v[146:149], v[162:165], v[118:121]
	v_mfma_f32_16x16x32_bf16 v[110:113], v[154:157], v[162:165], v[110:113]
	v_mfma_f32_16x16x32_bf16 v[102:105], v[146:149], v[170:173], v[102:105]
	v_mfma_f32_16x16x32_bf16 v[94:97], v[154:157], v[170:173], v[94:97]
	v_mfma_f32_16x16x32_bf16 v[86:89], v[146:149], v[178:181], v[86:89]
	v_mfma_f32_16x16x32_bf16 v[78:81], v[154:157], v[178:181], v[78:81]
	v_mfma_f32_16x16x32_bf16 v[70:73], v[146:149], v[186:189], v[70:73]
	v_mfma_f32_16x16x32_bf16 v[66:69], v[154:157], v[186:189], v[66:69]
	v_mfma_f32_16x16x32_bf16 v[118:121], v[150:153], v[166:169], v[118:121]
	v_mfma_f32_16x16x32_bf16 v[110:113], v[158:161], v[166:169], v[110:113]
	v_mfma_f32_16x16x32_bf16 v[102:105], v[150:153], v[174:177], v[102:105]
	v_mfma_f32_16x16x32_bf16 v[94:97], v[158:161], v[174:177], v[94:97]
	v_mfma_f32_16x16x32_bf16 v[86:89], v[150:153], v[182:185], v[86:89]
	v_mfma_f32_16x16x32_bf16 v[78:81], v[158:161], v[182:185], v[78:81]
	v_mfma_f32_16x16x32_bf16 v[70:73], v[150:153], v[190:193], v[70:73]
	v_mfma_f32_16x16x32_bf16 v[66:69], v[158:161], v[190:193], v[66:69]
	s_nop 0
	s_barrier
; #define PG8_STAGE(bufoff, gbase, voff) do { _Pragma("unroll") for (int _i = 0; _i < 2; ++_i) \
;         __builtin_amdgcn_global_load_lds((const unsigned*)((const char*)(gbase) + (voff)[_i]), (LAS unsigned*)(lds + (bufoff) + ldsw + _i * 8192), 16, 0, 0); } while (0)
; #define PG8_LDA(dst, b, h) do { _Pragma("unroll") for (int m = 0; m < 4; ++m) _Pragma("unroll") for (int k = 0; k < 2; ++k) dst[m][k] = *(const LAS bf16x8*)(lds + PG8_SA(b, h) + aoff + m * 2048 + k * 1024); } while (0)
; #define PG8_MMA(ai, bj, At, Bt) do { __builtin_amdgcn_s_setprio(1); _Pragma("unroll") for (int m = 0; m < 4; ++m) _Pragma("unroll") for (int n = 0; n < 2; ++n) _Pragma("unroll") for (int k = 0; k < 2; ++k) \
;         acc[ai][bj][m][n] = __builtin_amdgcn_mfma_f32_16x16x32_bf16(Bt[n][k], At[m][k], acc[ai][bj][m][n], 0, 0, 0); __builtin_amdgcn_s_setprio(0); } while (0)
; #define PG8_WAIT_V(n) asm volatile("s_waitcnt vmcnt(" #n ")" ::: "memory")
; #define PG8_WAIT_L(n) asm volatile("s_waitcnt lgkmcnt(" #n ")" ::: "memory")
; #define PG8_BAR __builtin_amdgcn_s_barrier()
; #define PG8_SCHED __builtin_amdgcn_sched_barrier(0)
; template <class Epi>
; __device__ __forceinline__ void gemm_phase(LAS unsigned char* lds, const Gemm g, const StaticOrder& S, const Epi& E) {
;     ...
;             PG8_WAIT_V(8); PG8_WAIT_L(0); PG8_BAR; PG8_MMA(0, 0, At, B0); PG8_MMA(0, 1, At, B1); PG8_BAR; PG8_SCHED;
;             PG8_LDA(At, 1, 1); PG8_STAGE(PG8_SB(1, 0), b3, voffB); PG8_STAGE(PG8_SB(1, 1), b3 + hstepB, voffB); PG8_STAGE(PG8_SA(1, 0), a3, voffA);
;             PG8_WAIT_V(8); PG8_WAIT_L(0); PG8_BAR; PG8_MMA(1, 0, At, B0); PG8_MMA(1, 1, At, B1); PG8_BAR; PG8_SCHED;
;         }
;         if (wr == 0) PG8_BAR;
;         E(acc, cur, wr, wc, fr, fq);
;         if (!has_next) break;
	s_add_i32 s48, s83, s36
	v_lshl_add_u64 v[196:197], v[196:197], 0, s[64:65]
	s_mov_b32 m0, s48
	ds_read_b128 v[162:165], v236 offset:49152
	ds_read_b128 v[166:169], v236 offset:50176
	ds_read_b128 v[170:173], v236 offset:51200
	ds_read_b128 v[174:177], v236 offset:52224
	ds_read_b128 v[178:181], v236 offset:53248
	ds_read_b128 v[182:185], v236 offset:54272
	ds_read_b128 v[186:189], v236 offset:55296
	ds_read_b128 v[190:193], v236 offset:56320
	global_load_lds_dwordx4 v[196:197], off
	s_add_i32 m0, s48, 0x2000
	s_add_u32 s48, s78, 0x80080
	v_lshl_add_u64 v[196:197], v[198:199], 0, s[64:65]
	s_addc_u32 s49, s79, 0
	s_add_i32 s78, s84, s36
	global_load_lds_dwordx4 v[196:197], off
	v_lshl_add_u64 v[196:197], s[48:49], 0, v[0:1]
	s_mov_b32 m0, s78
	s_nop 0
	global_load_lds_dwordx4 v[196:197], off
	v_lshl_add_u64 v[196:197], s[48:49], 0, v[204:205]
	s_add_i32 m0, s78, 0x2000
	s_nop 0
	global_load_lds_dwordx4 v[196:197], off
	v_lshl_add_u64 v[196:197], v[210:211], 0, s[64:65]
	s_mov_b32 m0, s61
	s_nop 0
	global_load_lds_dwordx4 v[196:197], off
	v_lshl_add_u64 v[196:197], v[212:213], 0, s[64:65]
	s_mov_b32 m0, s62
	s_nop 0
	global_load_lds_dwordx4 v[196:197], off
	s_waitcnt vmcnt(8)
	s_waitcnt lgkmcnt(0)
	s_barrier
	s_nop 0
	s_waitcnt lgkmcnt(0)
	v_mfma_f32_16x16x32_bf16 v[62:65], v[130:133], v[162:165], v[62:65]
	v_mfma_f32_16x16x32_bf16 v[58:61], v[138:141], v[162:165], v[58:61]
	v_mfma_f32_16x16x32_bf16 v[50:53], v[130:133], v[170:173], v[50:53]
	v_mfma_f32_16x16x32_bf16 v[42:45], v[138:141], v[170:173], v[42:45]
	v_mfma_f32_16x16x32_bf16 v[34:37], v[130:133], v[178:181], v[34:37]
	v_mfma_f32_16x16x32_bf16 v[26:29], v[138:141], v[178:181], v[26:29]
	v_mfma_f32_16x16x32_bf16 v[18:21], v[130:133], v[186:189], v[18:21]
	v_mfma_f32_16x16x32_bf16 v[10:13], v[138:141], v[186:189], v[10:13]
	v_mfma_f32_16x16x32_bf16 v[62:65], v[134:137], v[166:169], v[62:65]
	v_mfma_f32_16x16x32_bf16 v[58:61], v[142:145], v[166:169], v[58:61]
	v_mfma_f32_16x16x32_bf16 v[50:53], v[134:137], v[174:177], v[50:53]
	v_mfma_f32_16x16x32_bf16 v[42:45], v[142:145], v[174:177], v[42:45]
	v_mfma_f32_16x16x32_bf16 v[34:37], v[134:137], v[182:185], v[34:37]
	v_mfma_f32_16x16x32_bf16 v[26:29], v[142:145], v[182:185], v[26:29]
	v_mfma_f32_16x16x32_bf16 v[18:21], v[134:137], v[190:193], v[18:21]
	v_mfma_f32_16x16x32_bf16 v[10:13], v[142:145], v[190:193], v[10:13]
	s_nop 0
	s_nop 0
	v_mfma_f32_16x16x32_bf16 v[54:57], v[146:149], v[162:165], v[54:57]
	v_mfma_f32_16x16x32_bf16 v[46:49], v[154:157], v[162:165], v[46:49]
	v_mfma_f32_16x16x32_bf16 v[38:41], v[146:149], v[170:173], v[38:41]
	v_mfma_f32_16x16x32_bf16 v[30:33], v[154:157], v[170:173], v[30:33]
	v_mfma_f32_16x16x32_bf16 v[22:25], v[146:149], v[178:181], v[22:25]
	v_mfma_f32_16x16x32_bf16 v[14:17], v[154:157], v[178:181], v[14:17]
	v_mfma_f32_16x16x32_bf16 v[6:9], v[146:149], v[186:189], v[6:9]
	v_mfma_f32_16x16x32_bf16 v[2:5], v[154:157], v[186:189], v[2:5]
	v_mfma_f32_16x16x32_bf16 v[54:57], v[150:153], v[166:169], v[54:57]
	v_mfma_f32_16x16x32_bf16 v[46:49], v[158:161], v[166:169], v[46:49]
	v_mfma_f32_16x16x32_bf16 v[38:41], v[150:153], v[174:177], v[38:41]
	v_mfma_f32_16x16x32_bf16 v[30:33], v[158:161], v[174:177], v[30:33]
	v_mfma_f32_16x16x32_bf16 v[22:25], v[150:153], v[182:185], v[22:25]
	v_mfma_f32_16x16x32_bf16 v[14:17], v[158:161], v[182:185], v[14:17]
	v_mfma_f32_16x16x32_bf16 v[6:9], v[150:153], v[190:193], v[6:9]
	v_mfma_f32_16x16x32_bf16 v[2:5], v[158:161], v[190:193], v[2:5]
	s_nop 0
	s_barrier
	s_add_i32 s82, s82, 2
	s_add_u32 s30, s30, 0x100
	s_addc_u32 s31, s31, 0
	s_add_u32 s74, s74, 0x100
	s_addc_u32 s75, s75, 0
	s_cmp_gt_u32 s82, 29
	s_cbranch_scc0 .LBB0_1150
	s_and_b64 vcc, exec, s[16:17]
	s_cbranch_vccz .LBB0_1153
	s_barrier

; #define PG8_STAGE(bufoff, gbase, voff) do { _Pragma("unroll") for (int _i = 0; _i < 2; ++_i) \
;         __builtin_amdgcn_global_load_lds((const unsigned*)((const char*)(gbase) + (voff)[_i]), (LAS unsigned*)(lds + (bufoff) + ldsw + _i * 8192), 16, 0, 0); } while (0)
; #define PG8_LDA(dst, b, h) do { _Pragma("unroll") for (int m = 0; m < 4; ++m) _Pragma("unroll") for (int k = 0; k < 2; ++k) dst[m][k] = *(const LAS bf16x8*)(lds + PG8_SA(b, h) + aoff + m * 2048 + k * 1024); } while (0)
; #define PG8_LDB(dst, b, h) do { _Pragma("unroll") for (int n = 0; n < 2; ++n) _Pragma("unroll") for (int k = 0; k < 2; ++k) dst[n][k] = *(const LAS bf16x8*)(lds + PG8_SB(b, h) + boff + n * 2048 + k * 1024); } while (0)
; #define PG8_MMA(ai, bj, At, Bt) do { __builtin_amdgcn_s_setprio(1); _Pragma("unroll") for (int m = 0; m < 4; ++m) _Pragma("unroll") for (int n = 0; n < 2; ++n) _Pragma("unroll") for (int k = 0; k < 2; ++k) \
;         acc[ai][bj][m][n] = __builtin_amdgcn_mfma_f32_16x16x32_bf16(Bt[n][k], At[m][k], acc[ai][bj][m][n], 0, 0, 0); __builtin_amdgcn_s_setprio(0); } while (0)
; #define PG8_WAIT_V(n) asm volatile("s_waitcnt vmcnt(" #n ")" ::: "memory")
; #define PG8_WAIT_L(n) asm volatile("s_waitcnt lgkmcnt(" #n ")" ::: "memory")
; #define PG8_BAR __builtin_amdgcn_s_barrier()
; #define PG8_SCHED __builtin_amdgcn_sched_barrier(0)
; template <class Epi>
; __device__ __forceinline__ void gemm_phase(LAS unsigned char* lds, const Gemm g, const StaticOrder& S, const Epi& E) {
;     ...
;             const bool last = (t == nt - 2);
;             const char* a1 = cA + (size_t)(t + 1) * kstep;
;             const char* a2 = last ? nA : cA + (size_t)(t + 2) * kstep; const char* b2 = last ? nB : cB + (size_t)(t + 2) * kstep;
;             const char* a3 = a2 + kstep; const char* b3 = b2 + kstep;
;             PG8_LDB(B0, 0, 0); PG8_LDB(B1, 0, 1); PG8_SCHED; PG8_LDA(At, 0, 0); PG8_STAGE(PG8_SA(1, 1), a1 + hstepA, voffA);
;             PG8_WAIT_V(8); PG8_WAIT_L(0); PG8_BAR; PG8_MMA(0, 0, At, B0); PG8_MMA(0, 1, At, B1); PG8_BAR; PG8_SCHED;
;             PG8_LDA(At, 0, 1); PG8_STAGE(PG8_SB(0, 0), b2, voffB); PG8_STAGE(PG8_SB(0, 1), b2 + hstepB, voffB); PG8_STAGE(PG8_SA(0, 0), a2, voffA);
;             PG8_WAIT_V(8); PG8_WAIT_L(0); PG8_BAR; PG8_MMA(1, 0, At, B0); PG8_MMA(1, 1, At, B1); PG8_BAR; PG8_SCHED;
.LBB0_1240:
	s_add_u32 s48, s80, 0xfff80080
	s_addc_u32 s49, s81, -1
	s_add_i32 s79, 0, 0x10000
	s_cmp_eq_u32 s75, 28
	s_cselect_b32 s85, s23, s49
	s_cselect_b32 s84, s31, s48
	s_cselect_b32 s83, s21, s74
	s_cselect_b32 s82, s72, s73
	s_add_i32 s86, 0, 0x14000
	v_add_u32_e32 v142, s79, v222
	v_add_u32_e32 v158, s86, v222
	ds_read_b128 v[130:133], v142
	ds_read_b128 v[134:137], v142 offset:1024
	ds_read_b128 v[138:141], v142 offset:2048
	ds_read_b128 v[142:145], v142 offset:3072
	ds_read_b128 v[146:149], v158
	ds_read_b128 v[150:153], v158 offset:1024
	ds_read_b128 v[154:157], v158 offset:2048
	ds_read_b128 v[158:161], v158 offset:3072
	v_lshl_add_u64 v[208:209], s[80:81], 0, v[200:201]
	s_add_i32 m0, s38, 0xc000
	ds_read_b128 v[162:165], v224
	ds_read_b128 v[166:169], v224 offset:1024
	ds_read_b128 v[170:173], v224 offset:2048
	ds_read_b128 v[174:177], v224 offset:3072
	ds_read_b128 v[178:181], v224 offset:4096
	ds_read_b128 v[182:185], v224 offset:5120
	ds_read_b128 v[196:199], v224 offset:6144
	ds_read_b128 v[204:207], v224 offset:7168
	global_load_lds_dwordx4 v[208:209], off
	v_lshl_add_u64 v[208:209], s[80:81], 0, v[202:203]
	s_add_i32 m0, s38, 0xe000
	s_nop 0
	global_load_lds_dwordx4 v[208:209], off
	s_waitcnt vmcnt(8)
	s_waitcnt lgkmcnt(0)
	s_barrier
	s_nop 0
	s_waitcnt lgkmcnt(0)
	v_mfma_f32_16x16x32_bf16 v[126:129], v[130:133], v[162:165], v[126:129]
	v_mfma_f32_16x16x32_bf16 v[122:125], v[138:141], v[162:165], v[122:125]
	v_mfma_f32_16x16x32_bf16 v[110:113], v[130:133], v[170:173], v[110:113]
	v_mfma_f32_16x16x32_bf16 v[106:109], v[138:141], v[170:173], v[106:109]
	v_mfma_f32_16x16x32_bf16 v[94:97], v[130:133], v[178:181], v[94:97]
	v_mfma_f32_16x16x32_bf16 v[90:93], v[138:141], v[178:181], v[90:93]
	v_mfma_f32_16x16x32_bf16 v[78:81], v[130:133], v[196:199], v[78:81]
	v_mfma_f32_16x16x32_bf16 v[74:77], v[138:141], v[196:199], v[74:77]
	v_mfma_f32_16x16x32_bf16 v[126:129], v[134:137], v[166:169], v[126:129]
	v_mfma_f32_16x16x32_bf16 v[122:125], v[142:145], v[166:169], v[122:125]
	v_mfma_f32_16x16x32_bf16 v[110:113], v[134:137], v[174:177], v[110:113]
	v_mfma_f32_16x16x32_bf16 v[106:109], v[142:145], v[174:177], v[106:109]
	v_mfma_f32_16x16x32_bf16 v[94:97], v[134:137], v[182:185], v[94:97]
	v_mfma_f32_16x16x32_bf16 v[90:93], v[142:145], v[182:185], v[90:93]
	v_mfma_f32_16x16x32_bf16 v[78:81], v[134:137], v[204:207], v[78:81]
	v_mfma_f32_16x16x32_bf16 v[74:77], v[142:145], v[204:207], v[74:77]
	s_nop 0
	s_nop 0
	v_mfma_f32_16x16x32_bf16 v[118:121], v[146:149], v[162:165], v[118:121]
	v_mfma_f32_16x16x32_bf16 v[114:117], v[154:157], v[162:165], v[114:117]
	v_mfma_f32_16x16x32_bf16 v[102:105], v[146:149], v[170:173], v[102:105]
	v_mfma_f32_16x16x32_bf16 v[98:101], v[154:157], v[170:173], v[98:101]
	v_mfma_f32_16x16x32_bf16 v[86:89], v[146:149], v[178:181], v[86:89]
	v_mfma_f32_16x16x32_bf16 v[82:85], v[154:157], v[178:181], v[82:85]
	v_mfma_f32_16x16x32_bf16 v[70:73], v[146:149], v[196:199], v[70:73]
	v_mfma_f32_16x16x32_bf16 v[66:69], v[154:157], v[196:199], v[66:69]
	v_mfma_f32_16x16x32_bf16 v[118:121], v[150:153], v[166:169], v[118:121]
	v_mfma_f32_16x16x32_bf16 v[114:117], v[158:161], v[166:169], v[114:117]
	v_mfma_f32_16x16x32_bf16 v[102:105], v[150:153], v[174:177], v[102:105]
	v_mfma_f32_16x16x32_bf16 v[98:101], v[158:161], v[174:177], v[98:101]
	v_mfma_f32_16x16x32_bf16 v[86:89], v[150:153], v[182:185], v[86:89]
	v_mfma_f32_16x16x32_bf16 v[82:85], v[158:161], v[182:185], v[82:85]
	v_mfma_f32_16x16x32_bf16 v[70:73], v[150:153], v[204:207], v[70:73]
	v_mfma_f32_16x16x32_bf16 v[66:69], v[158:161], v[204:207], v[66:69]
	s_nop 0
	s_barrier
	s_add_i32 s48, s79, s34
	v_lshl_add_u64 v[208:209], s[82:83], 0, v[0:1]
	s_mov_b32 m0, s48
	ds_read_b128 v[162:165], v224 offset:16384
	ds_read_b128 v[166:169], v224 offset:17408
	ds_read_b128 v[170:173], v224 offset:18432
	ds_read_b128 v[174:177], v224 offset:19456
	ds_read_b128 v[178:181], v224 offset:20480
	ds_read_b128 v[182:185], v224 offset:21504
	ds_read_b128 v[196:199], v224 offset:22528
	ds_read_b128 v[204:207], v224 offset:23552
	global_load_lds_dwordx4 v[208:209], off
	s_add_i32 m0, s48, 0x2000
	s_add_u32 s48, s82, 0x80000
	v_lshl_add_u64 v[210:211], s[82:83], 0, v[190:191]
	s_addc_u32 s49, s83, 0
	s_add_i32 s79, s86, s34
	global_load_lds_dwordx4 v[210:211], off
	v_lshl_add_u64 v[212:213], s[48:49], 0, v[0:1]
	s_mov_b32 m0, s79
	v_lshl_add_u64 v[214:215], s[84:85], 0, v[188:189]
	global_load_lds_dwordx4 v[212:213], off
	v_lshl_add_u64 v[212:213], s[48:49], 0, v[190:191]
	s_add_i32 m0, s79, 0x2000
	s_nop 0
	global_load_lds_dwordx4 v[212:213], off
	v_lshl_add_u64 v[212:213], s[84:85], 0, v[186:187]
	s_mov_b32 m0, s38
	s_nop 0
	global_load_lds_dwordx4 v[212:213], off
	s_mov_b32 m0, s39
	s_nop 0
	global_load_lds_dwordx4 v[214:215], off
	s_waitcnt vmcnt(8)
	s_waitcnt lgkmcnt(0)
	s_barrier
; #define PG8_STAGE(bufoff, gbase, voff) do { _Pragma("unroll") for (int _i = 0; _i < 2; ++_i) \
;         __builtin_amdgcn_global_load_lds((const unsigned*)((const char*)(gbase) + (voff)[_i]), (LAS unsigned*)(lds + (bufoff) + ldsw + _i * 8192), 16, 0, 0); } while (0)
; #define PG8_LDA(dst, b, h) do { _Pragma("unroll") for (int m = 0; m < 4; ++m) _Pragma("unroll") for (int k = 0; k < 2; ++k) dst[m][k] = *(const LAS bf16x8*)(lds + PG8_SA(b, h) + aoff + m * 2048 + k * 1024); } while (0)
; #define PG8_LDB(dst, b, h) do { _Pragma("unroll") for (int n = 0; n < 2; ++n) _Pragma("unroll") for (int k = 0; k < 2; ++k) dst[n][k] = *(const LAS bf16x8*)(lds + PG8_SB(b, h) + boff + n * 2048 + k * 1024); } while (0)
; #define PG8_MMA(ai, bj, At, Bt) do { __builtin_amdgcn_s_setprio(1); _Pragma("unroll") for (int m = 0; m < 4; ++m) _Pragma("unroll") for (int n = 0; n < 2; ++n) _Pragma("unroll") for (int k = 0; k < 2; ++k) \
;         acc[ai][bj][m][n] = __builtin_amdgcn_mfma_f32_16x16x32_bf16(Bt[n][k], At[m][k], acc[ai][bj][m][n], 0, 0, 0); __builtin_amdgcn_s_setprio(0); } while (0)
; #define PG8_WAIT_V(n) asm volatile("s_waitcnt vmcnt(" #n ")" ::: "memory")
; #define PG8_WAIT_L(n) asm volatile("s_waitcnt lgkmcnt(" #n ")" ::: "memory")
; #define PG8_BAR __builtin_amdgcn_s_barrier()
; #define PG8_SCHED __builtin_amdgcn_sched_barrier(0)
; template <class Epi>
; __device__ __forceinline__ void gemm_phase(LAS unsigned char* lds, const Gemm g, const StaticOrder& S, const Epi& E) {
;     ...
;             PG8_WAIT_V(8); PG8_WAIT_L(0); PG8_BAR; PG8_MMA(0, 0, At, B0); PG8_MMA(0, 1, At, B1); PG8_BAR; PG8_SCHED;
;             PG8_LDA(At, 0, 1); PG8_STAGE(PG8_SB(0, 0), b2, voffB); PG8_STAGE(PG8_SB(0, 1), b2 + hstepB, voffB); PG8_STAGE(PG8_SA(0, 0), a2, voffA);
;             PG8_WAIT_V(8); PG8_WAIT_L(0); PG8_BAR; PG8_MMA(1, 0, At, B0); PG8_MMA(1, 1, At, B1); PG8_BAR; PG8_SCHED;
;             PG8_LDB(B0, 1, 0); PG8_LDB(B1, 1, 1); PG8_SCHED; PG8_LDA(At, 1, 0); PG8_STAGE(PG8_SA(0, 1), a2 + hstepA, voffA);
;             PG8_WAIT_V(8); PG8_WAIT_L(0); PG8_BAR; PG8_MMA(0, 0, At, B0); PG8_MMA(0, 1, At, B1); PG8_BAR; PG8_SCHED;
;             PG8_LDA(At, 1, 1); PG8_STAGE(PG8_SB(1, 0), b3, voffB); PG8_STAGE(PG8_SB(1, 1), b3 + hstepB, voffB); PG8_STAGE(PG8_SA(1, 0), a3, voffA);
	s_nop 0
	s_waitcnt lgkmcnt(0)
	v_mfma_f32_16x16x32_bf16 v[62:65], v[130:133], v[162:165], v[62:65]
	v_mfma_f32_16x16x32_bf16 v[58:61], v[138:141], v[162:165], v[58:61]
	v_mfma_f32_16x16x32_bf16 v[46:49], v[130:133], v[170:173], v[46:49]
	v_mfma_f32_16x16x32_bf16 v[42:45], v[138:141], v[170:173], v[42:45]
	v_mfma_f32_16x16x32_bf16 v[30:33], v[130:133], v[178:181], v[30:33]
	v_mfma_f32_16x16x32_bf16 v[26:29], v[138:141], v[178:181], v[26:29]
	v_mfma_f32_16x16x32_bf16 v[14:17], v[130:133], v[196:199], v[14:17]
	v_mfma_f32_16x16x32_bf16 v[10:13], v[138:141], v[196:199], v[10:13]
	v_mfma_f32_16x16x32_bf16 v[62:65], v[134:137], v[166:169], v[62:65]
	v_mfma_f32_16x16x32_bf16 v[58:61], v[142:145], v[166:169], v[58:61]
	v_mfma_f32_16x16x32_bf16 v[46:49], v[134:137], v[174:177], v[46:49]
	v_mfma_f32_16x16x32_bf16 v[42:45], v[142:145], v[174:177], v[42:45]
	v_mfma_f32_16x16x32_bf16 v[30:33], v[134:137], v[182:185], v[30:33]
	v_mfma_f32_16x16x32_bf16 v[26:29], v[142:145], v[182:185], v[26:29]
	v_mfma_f32_16x16x32_bf16 v[14:17], v[134:137], v[204:207], v[14:17]
	v_mfma_f32_16x16x32_bf16 v[10:13], v[142:145], v[204:207], v[10:13]
	s_nop 0
	s_nop 0
	v_mfma_f32_16x16x32_bf16 v[54:57], v[146:149], v[162:165], v[54:57]
	v_mfma_f32_16x16x32_bf16 v[50:53], v[154:157], v[162:165], v[50:53]
	v_mfma_f32_16x16x32_bf16 v[38:41], v[146:149], v[170:173], v[38:41]
	v_mfma_f32_16x16x32_bf16 v[34:37], v[154:157], v[170:173], v[34:37]
	v_mfma_f32_16x16x32_bf16 v[22:25], v[146:149], v[178:181], v[22:25]
	v_mfma_f32_16x16x32_bf16 v[18:21], v[154:157], v[178:181], v[18:21]
	v_mfma_f32_16x16x32_bf16 v[6:9], v[146:149], v[196:199], v[6:9]
	v_mfma_f32_16x16x32_bf16 v[2:5], v[154:157], v[196:199], v[2:5]
	v_mfma_f32_16x16x32_bf16 v[54:57], v[150:153], v[166:169], v[54:57]
	v_mfma_f32_16x16x32_bf16 v[50:53], v[158:161], v[166:169], v[50:53]
	v_mfma_f32_16x16x32_bf16 v[38:41], v[150:153], v[174:177], v[38:41]
	v_mfma_f32_16x16x32_bf16 v[34:37], v[158:161], v[174:177], v[34:37]
	v_mfma_f32_16x16x32_bf16 v[22:25], v[150:153], v[182:185], v[22:25]
	v_mfma_f32_16x16x32_bf16 v[18:21], v[158:161], v[182:185], v[18:21]
	v_mfma_f32_16x16x32_bf16 v[6:9], v[150:153], v[204:207], v[6:9]
	v_mfma_f32_16x16x32_bf16 v[2:5], v[158:161], v[204:207], v[2:5]
	s_nop 0
	s_barrier
	s_add_i32 s79, 0, 0x18000
	s_add_i32 s86, 0, 0x1c000
	v_add_u32_e32 v142, s79, v222
	v_add_u32_e32 v158, s86, v222
	ds_read_b128 v[130:133], v142
	ds_read_b128 v[134:137], v142 offset:1024
	ds_read_b128 v[138:141], v142 offset:2048
	ds_read_b128 v[142:145], v142 offset:3072
	ds_read_b128 v[146:149], v158
	ds_read_b128 v[150:153], v158 offset:1024
	ds_read_b128 v[154:157], v158 offset:2048
	ds_read_b128 v[158:161], v158 offset:3072
	s_add_u32 s48, s84, 0x80000
	s_addc_u32 s49, s85, 0
	s_mov_b32 m0, s43
	v_lshl_add_u64 v[216:217], s[48:49], 0, v[186:187]
	ds_read_b128 v[162:165], v224 offset:32768
	ds_read_b128 v[166:169], v224 offset:33792
	ds_read_b128 v[170:173], v224 offset:34816
	ds_read_b128 v[174:177], v224 offset:35840
	ds_read_b128 v[178:181], v224 offset:36864
	ds_read_b128 v[182:185], v224 offset:37888
	ds_read_b128 v[196:199], v224 offset:38912
	ds_read_b128 v[204:207], v224 offset:39936
	global_load_lds_dwordx4 v[216:217], off
	v_lshl_add_u64 v[216:217], s[48:49], 0, v[188:189]
	s_mov_b32 m0, s60
	s_nop 0
	global_load_lds_dwordx4 v[216:217], off
	s_waitcnt vmcnt(8)
	s_waitcnt lgkmcnt(0)
	s_barrier
	s_nop 0
	s_waitcnt lgkmcnt(0)
	v_mfma_f32_16x16x32_bf16 v[126:129], v[130:133], v[162:165], v[126:129]
	v_mfma_f32_16x16x32_bf16 v[122:125], v[138:141], v[162:165], v[122:125]
	v_mfma_f32_16x16x32_bf16 v[110:113], v[130:133], v[170:173], v[110:113]
	v_mfma_f32_16x16x32_bf16 v[106:109], v[138:141], v[170:173], v[106:109]
	v_mfma_f32_16x16x32_bf16 v[94:97], v[130:133], v[178:181], v[94:97]
	v_mfma_f32_16x16x32_bf16 v[90:93], v[138:141], v[178:181], v[90:93]
	v_mfma_f32_16x16x32_bf16 v[78:81], v[130:133], v[196:199], v[78:81]
	v_mfma_f32_16x16x32_bf16 v[74:77], v[138:141], v[196:199], v[74:77]
	v_mfma_f32_16x16x32_bf16 v[126:129], v[134:137], v[166:169], v[126:129]
	v_mfma_f32_16x16x32_bf16 v[122:125], v[142:145], v[166:169], v[122:125]
	v_mfma_f32_16x16x32_bf16 v[110:113], v[134:137], v[174:177], v[110:113]
	v_mfma_f32_16x16x32_bf16 v[106:109], v[142:145], v[174:177], v[106:109]
	v_mfma_f32_16x16x32_bf16 v[94:97], v[134:137], v[182:185], v[94:97]
	v_mfma_f32_16x16x32_bf16 v[90:93], v[142:145], v[182:185], v[90:93]
	v_mfma_f32_16x16x32_bf16 v[78:81], v[134:137], v[204:207], v[78:81]
	v_mfma_f32_16x16x32_bf16 v[74:77], v[142:145], v[204:207], v[74:77]
	s_nop 0
	s_nop 0
	v_mfma_f32_16x16x32_bf16 v[118:121], v[146:149], v[162:165], v[118:121]
	v_mfma_f32_16x16x32_bf16 v[114:117], v[154:157], v[162:165], v[114:117]
	v_mfma_f32_16x16x32_bf16 v[102:105], v[146:149], v[170:173], v[102:105]
	v_mfma_f32_16x16x32_bf16 v[98:101], v[154:157], v[170:173], v[98:101]
	v_mfma_f32_16x16x32_bf16 v[86:89], v[146:149], v[178:181], v[86:89]
	v_mfma_f32_16x16x32_bf16 v[82:85], v[154:157], v[178:181], v[82:85]
	v_mfma_f32_16x16x32_bf16 v[70:73], v[146:149], v[196:199], v[70:73]
	v_mfma_f32_16x16x32_bf16 v[66:69], v[154:157], v[196:199], v[66:69]
	v_mfma_f32_16x16x32_bf16 v[118:121], v[150:153], v[166:169], v[118:121]
	v_mfma_f32_16x16x32_bf16 v[114:117], v[158:161], v[166:169], v[114:117]
	v_mfma_f32_16x16x32_bf16 v[102:105], v[150:153], v[174:177], v[102:105]
	v_mfma_f32_16x16x32_bf16 v[98:101], v[158:161], v[174:177], v[98:101]
	v_mfma_f32_16x16x32_bf16 v[86:89], v[150:153], v[182:185], v[86:89]
	v_mfma_f32_16x16x32_bf16 v[82:85], v[158:161], v[182:185], v[82:85]
	v_mfma_f32_16x16x32_bf16 v[70:73], v[150:153], v[204:207], v[70:73]
	v_mfma_f32_16x16x32_bf16 v[66:69], v[158:161], v[204:207], v[66:69]
	s_nop 0
	s_barrier
; #define PG8_STAGE(bufoff, gbase, voff) do { _Pragma("unroll") for (int _i = 0; _i < 2; ++_i) \
;         __builtin_amdgcn_global_load_lds((const unsigned*)((const char*)(gbase) + (voff)[_i]), (LAS unsigned*)(lds + (bufoff) + ldsw + _i * 8192), 16, 0, 0); } while (0)
; #define PG8_LDA(dst, b, h) do { _Pragma("unroll") for (int m = 0; m < 4; ++m) _Pragma("unroll") for (int k = 0; k < 2; ++k) dst[m][k] = *(const LAS bf16x8*)(lds + PG8_SA(b, h) + aoff + m * 2048 + k * 1024); } while (0)
; #define PG8_MMA(ai, bj, At, Bt) do { __builtin_amdgcn_s_setprio(1); _Pragma("unroll") for (int m = 0; m < 4; ++m) _Pragma("unroll") for (int n = 0; n < 2; ++n) _Pragma("unroll") for (int k = 0; k < 2; ++k) \
;         acc[ai][bj][m][n] = __builtin_amdgcn_mfma_f32_16x16x32_bf16(Bt[n][k], At[m][k], acc[ai][bj][m][n], 0, 0, 0); __builtin_amdgcn_s_setprio(0); } while (0)
; #define PG8_WAIT_V(n) asm volatile("s_waitcnt vmcnt(" #n ")" ::: "memory")
; #define PG8_WAIT_L(n) asm volatile("s_waitcnt lgkmcnt(" #n ")" ::: "memory")
; #define PG8_BAR __builtin_amdgcn_s_barrier()
; #define PG8_SCHED __builtin_amdgcn_sched_barrier(0)
; template <class Epi>
; __device__ __forceinline__ void gemm_phase(LAS unsigned char* lds, const Gemm g, const StaticOrder& S, const Epi& E) {
;     ...
;             PG8_WAIT_V(8); PG8_WAIT_L(0); PG8_BAR; PG8_MMA(0, 0, At, B0); PG8_MMA(0, 1, At, B1); PG8_BAR; PG8_SCHED;
;             PG8_LDA(At, 1, 1); PG8_STAGE(PG8_SB(1, 0), b3, voffB); PG8_STAGE(PG8_SB(1, 1), b3 + hstepB, voffB); PG8_STAGE(PG8_SA(1, 0), a3, voffA);
;             PG8_WAIT_V(8); PG8_WAIT_L(0); PG8_BAR; PG8_MMA(1, 0, At, B0); PG8_MMA(1, 1, At, B1); PG8_BAR; PG8_SCHED;
;         }
;         if (wr == 0) PG8_BAR;
;         E(acc, cur, wr, wc, fr, fq);
;         if (!has_next) break;
	s_add_i32 s48, s79, s34
	v_lshl_add_u64 v[208:209], v[208:209], 0, s[64:65]
	s_mov_b32 m0, s48
	ds_read_b128 v[162:165], v224 offset:49152
	ds_read_b128 v[166:169], v224 offset:50176
	ds_read_b128 v[170:173], v224 offset:51200
	ds_read_b128 v[174:177], v224 offset:52224
	ds_read_b128 v[178:181], v224 offset:53248
	ds_read_b128 v[182:185], v224 offset:54272
	ds_read_b128 v[196:199], v224 offset:55296
	ds_read_b128 v[204:207], v224 offset:56320
	global_load_lds_dwordx4 v[208:209], off
	s_add_i32 m0, s48, 0x2000
	s_add_u32 s48, s82, 0x80080
	v_lshl_add_u64 v[208:209], v[210:211], 0, s[64:65]
	s_addc_u32 s49, s83, 0
	s_add_i32 s79, s86, s34
	global_load_lds_dwordx4 v[208:209], off
	v_lshl_add_u64 v[208:209], s[48:49], 0, v[0:1]
	s_mov_b32 m0, s79
	s_nop 0
	global_load_lds_dwordx4 v[208:209], off
	v_lshl_add_u64 v[208:209], s[48:49], 0, v[190:191]
	s_add_i32 m0, s79, 0x2000
	s_nop 0
	global_load_lds_dwordx4 v[208:209], off
	v_lshl_add_u64 v[208:209], v[212:213], 0, s[64:65]
	s_mov_b32 m0, s36
	s_nop 0
	global_load_lds_dwordx4 v[208:209], off
	v_lshl_add_u64 v[208:209], v[214:215], 0, s[64:65]
	s_mov_b32 m0, s61
	s_nop 0
	global_load_lds_dwordx4 v[208:209], off
	s_waitcnt vmcnt(8)
	s_waitcnt lgkmcnt(0)
	s_barrier
	s_nop 0
	s_waitcnt lgkmcnt(0)
	v_mfma_f32_16x16x32_bf16 v[62:65], v[130:133], v[162:165], v[62:65]
	v_mfma_f32_16x16x32_bf16 v[58:61], v[138:141], v[162:165], v[58:61]
	v_mfma_f32_16x16x32_bf16 v[46:49], v[130:133], v[170:173], v[46:49]
	v_mfma_f32_16x16x32_bf16 v[42:45], v[138:141], v[170:173], v[42:45]
	v_mfma_f32_16x16x32_bf16 v[30:33], v[130:133], v[178:181], v[30:33]
	v_mfma_f32_16x16x32_bf16 v[26:29], v[138:141], v[178:181], v[26:29]
	v_mfma_f32_16x16x32_bf16 v[14:17], v[130:133], v[196:199], v[14:17]
	v_mfma_f32_16x16x32_bf16 v[10:13], v[138:141], v[196:199], v[10:13]
	v_mfma_f32_16x16x32_bf16 v[62:65], v[134:137], v[166:169], v[62:65]
	v_mfma_f32_16x16x32_bf16 v[58:61], v[142:145], v[166:169], v[58:61]
	v_mfma_f32_16x16x32_bf16 v[46:49], v[134:137], v[174:177], v[46:49]
	v_mfma_f32_16x16x32_bf16 v[42:45], v[142:145], v[174:177], v[42:45]
	v_mfma_f32_16x16x32_bf16 v[30:33], v[134:137], v[182:185], v[30:33]
	v_mfma_f32_16x16x32_bf16 v[26:29], v[142:145], v[182:185], v[26:29]
	v_mfma_f32_16x16x32_bf16 v[14:17], v[134:137], v[204:207], v[14:17]
	v_mfma_f32_16x16x32_bf16 v[10:13], v[142:145], v[204:207], v[10:13]
	s_nop 0
	s_nop 0
	v_mfma_f32_16x16x32_bf16 v[54:57], v[146:149], v[162:165], v[54:57]
	v_mfma_f32_16x16x32_bf16 v[50:53], v[154:157], v[162:165], v[50:53]
	v_mfma_f32_16x16x32_bf16 v[38:41], v[146:149], v[170:173], v[38:41]
	v_mfma_f32_16x16x32_bf16 v[34:37], v[154:157], v[170:173], v[34:37]
	v_mfma_f32_16x16x32_bf16 v[22:25], v[146:149], v[178:181], v[22:25]
	v_mfma_f32_16x16x32_bf16 v[18:21], v[154:157], v[178:181], v[18:21]
	v_mfma_f32_16x16x32_bf16 v[6:9], v[146:149], v[196:199], v[6:9]
	v_mfma_f32_16x16x32_bf16 v[2:5], v[154:157], v[196:199], v[2:5]
	v_mfma_f32_16x16x32_bf16 v[54:57], v[150:153], v[166:169], v[54:57]
	v_mfma_f32_16x16x32_bf16 v[50:53], v[158:161], v[166:169], v[50:53]
	v_mfma_f32_16x16x32_bf16 v[38:41], v[150:153], v[174:177], v[38:41]
	v_mfma_f32_16x16x32_bf16 v[34:37], v[158:161], v[174:177], v[34:37]
	v_mfma_f32_16x16x32_bf16 v[22:25], v[150:153], v[182:185], v[22:25]
	v_mfma_f32_16x16x32_bf16 v[18:21], v[158:161], v[182:185], v[18:21]
	v_mfma_f32_16x16x32_bf16 v[6:9], v[150:153], v[204:207], v[6:9]
	v_mfma_f32_16x16x32_bf16 v[2:5], v[158:161], v[204:207], v[2:5]
	s_nop 0
	s_barrier
	s_add_i32 s75, s75, 2
	s_add_u32 s80, s80, 0x100
	s_addc_u32 s81, s81, 0
	s_add_u32 s73, s73, 0x100
	s_addc_u32 s74, s74, 0
	s_cmp_gt_u32 s75, 29
	s_cbranch_scc0 .LBB0_1240
	s_and_b64 vcc, exec, s[18:19]
	s_cbranch_vccz .LBB0_1243
	s_barrier

; #define PG8_STAGE(bufoff, gbase, voff) do { _Pragma("unroll") for (int _i = 0; _i < 2; ++_i) \
;         __builtin_amdgcn_global_load_lds((const unsigned*)((const char*)(gbase) + (voff)[_i]), (LAS unsigned*)(lds + (bufoff) + ldsw + _i * 8192), 16, 0, 0); } while (0)
; #define PG8_LDA(dst, b, h) do { _Pragma("unroll") for (int m = 0; m < 4; ++m) _Pragma("unroll") for (int k = 0; k < 2; ++k) dst[m][k] = *(const LAS bf16x8*)(lds + PG8_SA(b, h) + aoff + m * 2048 + k * 1024); } while (0)
; #define PG8_LDB(dst, b, h) do { _Pragma("unroll") for (int n = 0; n < 2; ++n) _Pragma("unroll") for (int k = 0; k < 2; ++k) dst[n][k] = *(const LAS bf16x8*)(lds + PG8_SB(b, h) + boff + n * 2048 + k * 1024); } while (0)
; #define PG8_MMA(ai, bj, At, Bt) do { __builtin_amdgcn_s_setprio(1); _Pragma("unroll") for (int m = 0; m < 4; ++m) _Pragma("unroll") for (int n = 0; n < 2; ++n) _Pragma("unroll") for (int k = 0; k < 2; ++k) \
;         acc[ai][bj][m][n] = __builtin_amdgcn_mfma_f32_16x16x32_bf16(Bt[n][k], At[m][k], acc[ai][bj][m][n], 0, 0, 0); __builtin_amdgcn_s_setprio(0); } while (0)
; #define PG8_WAIT_V(n) asm volatile("s_waitcnt vmcnt(" #n ")" ::: "memory")
; #define PG8_WAIT_L(n) asm volatile("s_waitcnt lgkmcnt(" #n ")" ::: "memory")
; #define PG8_BAR __builtin_amdgcn_s_barrier()
; #define PG8_SCHED __builtin_amdgcn_sched_barrier(0)
; template <class Epi>
; __device__ __forceinline__ void gemm_phase(LAS unsigned char* lds, const Gemm g, const StaticOrder& S, const Epi& E) {
;     ...
;             const bool last = (t == nt - 2);
;             const char* a1 = cA + (size_t)(t + 1) * kstep;
;             const char* a2 = last ? nA : cA + (size_t)(t + 2) * kstep; const char* b2 = last ? nB : cB + (size_t)(t + 2) * kstep;
;             const char* a3 = a2 + kstep; const char* b3 = b2 + kstep;
;             PG8_LDB(B0, 0, 0); PG8_LDB(B1, 0, 1); PG8_SCHED; PG8_LDA(At, 0, 0); PG8_STAGE(PG8_SA(1, 1), a1 + hstepA, voffA);
;             PG8_WAIT_V(8); PG8_WAIT_L(0); PG8_BAR; PG8_MMA(0, 0, At, B0); PG8_MMA(0, 1, At, B1); PG8_BAR; PG8_SCHED;
;             PG8_LDA(At, 0, 1); PG8_STAGE(PG8_SB(0, 0), b2, voffB); PG8_STAGE(PG8_SB(0, 1), b2 + hstepB, voffB); PG8_STAGE(PG8_SA(0, 0), a2, voffA);
;             PG8_WAIT_V(8); PG8_WAIT_L(0); PG8_BAR; PG8_MMA(1, 0, At, B0); PG8_MMA(1, 1, At, B1); PG8_BAR; PG8_SCHED;
.LBB0_1344:
	s_add_u32 s30, s26, 0xfff80080
	s_addc_u32 s31, s27, -1
	s_add_i32 s48, 0, 0x10000
	s_cmp_eq_u32 s81, 28
	s_cselect_b32 s79, s19, s31
	s_cselect_b32 s78, s73, s30
	v_add_u32_e32 v142, s48, v147
	s_cselect_b32 s31, s17, s80
	s_cselect_b32 s30, s74, s75
	s_add_i32 s82, 0, 0x14000
	ds_read_b128 v[150:153], v142
	ds_read_b128 v[154:157], v142 offset:1024
	ds_read_b128 v[158:161], v142 offset:2048
	ds_read_b128 v[162:165], v142 offset:3072
	v_add_u32_e32 v142, s82, v147
	ds_read_b128 v[166:169], v142
	ds_read_b128 v[170:173], v142 offset:1024
	ds_read_b128 v[174:177], v142 offset:2048
	ds_read_b128 v[178:181], v142 offset:3072
	v_lshl_add_u64 v[142:143], s[26:27], 0, v[138:139]
	s_add_i32 m0, s39, 0xc000
	ds_read_b128 v[182:185], v149
	ds_read_b128 v[186:189], v149 offset:1024
	ds_read_b128 v[190:193], v149 offset:2048
	ds_read_b128 v[196:199], v149 offset:3072
	ds_read_b128 v[200:203], v149 offset:4096
	ds_read_b128 v[204:207], v149 offset:5120
	ds_read_b128 v[208:211], v149 offset:6144
	ds_read_b128 v[212:215], v149 offset:7168
	global_load_lds_dwordx4 v[142:143], off
	v_lshl_add_u64 v[142:143], s[26:27], 0, v[140:141]
	s_add_i32 m0, s39, 0xe000
	s_nop 0
	global_load_lds_dwordx4 v[142:143], off
	s_waitcnt vmcnt(8)
	s_waitcnt lgkmcnt(0)
	s_barrier
	s_nop 0
	s_waitcnt lgkmcnt(0)
	v_mfma_f32_16x16x32_bf16 v[126:129], v[150:153], v[182:185], v[126:129]
	v_mfma_f32_16x16x32_bf16 v[122:125], v[158:161], v[182:185], v[122:125]
	v_mfma_f32_16x16x32_bf16 v[110:113], v[150:153], v[190:193], v[110:113]
	v_mfma_f32_16x16x32_bf16 v[106:109], v[158:161], v[190:193], v[106:109]
	v_mfma_f32_16x16x32_bf16 v[94:97], v[150:153], v[200:203], v[94:97]
	v_mfma_f32_16x16x32_bf16 v[90:93], v[158:161], v[200:203], v[90:93]
	v_mfma_f32_16x16x32_bf16 v[78:81], v[150:153], v[208:211], v[78:81]
	v_mfma_f32_16x16x32_bf16 v[74:77], v[158:161], v[208:211], v[74:77]
	v_mfma_f32_16x16x32_bf16 v[126:129], v[154:157], v[186:189], v[126:129]
	v_mfma_f32_16x16x32_bf16 v[122:125], v[162:165], v[186:189], v[122:125]
	v_mfma_f32_16x16x32_bf16 v[110:113], v[154:157], v[196:199], v[110:113]
	v_mfma_f32_16x16x32_bf16 v[106:109], v[162:165], v[196:199], v[106:109]
	v_mfma_f32_16x16x32_bf16 v[94:97], v[154:157], v[204:207], v[94:97]
	v_mfma_f32_16x16x32_bf16 v[90:93], v[162:165], v[204:207], v[90:93]
	v_mfma_f32_16x16x32_bf16 v[78:81], v[154:157], v[212:215], v[78:81]
	v_mfma_f32_16x16x32_bf16 v[74:77], v[162:165], v[212:215], v[74:77]
	s_nop 0
	s_nop 0
	v_mfma_f32_16x16x32_bf16 v[118:121], v[166:169], v[182:185], v[118:121]
	v_mfma_f32_16x16x32_bf16 v[114:117], v[174:177], v[182:185], v[114:117]
	v_mfma_f32_16x16x32_bf16 v[102:105], v[166:169], v[190:193], v[102:105]
	v_mfma_f32_16x16x32_bf16 v[98:101], v[174:177], v[190:193], v[98:101]
	v_mfma_f32_16x16x32_bf16 v[86:89], v[166:169], v[200:203], v[86:89]
	v_mfma_f32_16x16x32_bf16 v[82:85], v[174:177], v[200:203], v[82:85]
	v_mfma_f32_16x16x32_bf16 v[70:73], v[166:169], v[208:211], v[70:73]
	v_mfma_f32_16x16x32_bf16 v[66:69], v[174:177], v[208:211], v[66:69]
	v_mfma_f32_16x16x32_bf16 v[118:121], v[170:173], v[186:189], v[118:121]
	v_mfma_f32_16x16x32_bf16 v[114:117], v[178:181], v[186:189], v[114:117]
	v_mfma_f32_16x16x32_bf16 v[102:105], v[170:173], v[196:199], v[102:105]
	v_mfma_f32_16x16x32_bf16 v[98:101], v[178:181], v[196:199], v[98:101]
	v_mfma_f32_16x16x32_bf16 v[86:89], v[170:173], v[204:207], v[86:89]
	v_mfma_f32_16x16x32_bf16 v[82:85], v[178:181], v[204:207], v[82:85]
	v_mfma_f32_16x16x32_bf16 v[70:73], v[170:173], v[212:215], v[70:73]
	v_mfma_f32_16x16x32_bf16 v[66:69], v[178:181], v[212:215], v[66:69]
	s_nop 0
	s_barrier
	s_add_i32 s48, s48, s38
	v_lshl_add_u64 v[142:143], s[30:31], 0, v[132:133]
	s_mov_b32 m0, s48
	ds_read_b128 v[182:185], v149 offset:16384
	ds_read_b128 v[186:189], v149 offset:17408
	ds_read_b128 v[190:193], v149 offset:18432
	ds_read_b128 v[196:199], v149 offset:19456
	ds_read_b128 v[200:203], v149 offset:20480
	ds_read_b128 v[204:207], v149 offset:21504
	ds_read_b128 v[208:211], v149 offset:22528
	ds_read_b128 v[212:215], v149 offset:23552
	global_load_lds_dwordx4 v[142:143], off
	s_add_i32 m0, s48, 0x2000
	s_add_u32 s48, s30, 0x80000
	v_lshl_add_u64 v[216:217], s[30:31], 0, v[136:137]
	s_addc_u32 s49, s31, 0
	s_add_i32 s82, s82, s38
	global_load_lds_dwordx4 v[216:217], off
	v_lshl_add_u64 v[218:219], s[48:49], 0, v[132:133]
	s_mov_b32 m0, s82
	v_lshl_add_u64 v[220:221], s[78:79], 0, v[134:135]
	global_load_lds_dwordx4 v[218:219], off
	v_lshl_add_u64 v[218:219], s[48:49], 0, v[136:137]
	s_add_i32 m0, s82, 0x2000
	s_nop 0
	global_load_lds_dwordx4 v[218:219], off
	v_lshl_add_u64 v[218:219], s[78:79], 0, v[130:131]
	s_mov_b32 m0, s39
	s_nop 0
	global_load_lds_dwordx4 v[218:219], off
	s_mov_b32 m0, s43
	s_nop 0
	global_load_lds_dwordx4 v[220:221], off
	s_waitcnt vmcnt(8)
	s_waitcnt lgkmcnt(0)
	s_barrier
; #define PG8_STAGE(bufoff, gbase, voff) do { _Pragma("unroll") for (int _i = 0; _i < 2; ++_i) \
;         __builtin_amdgcn_global_load_lds((const unsigned*)((const char*)(gbase) + (voff)[_i]), (LAS unsigned*)(lds + (bufoff) + ldsw + _i * 8192), 16, 0, 0); } while (0)
; #define PG8_LDA(dst, b, h) do { _Pragma("unroll") for (int m = 0; m < 4; ++m) _Pragma("unroll") for (int k = 0; k < 2; ++k) dst[m][k] = *(const LAS bf16x8*)(lds + PG8_SA(b, h) + aoff + m * 2048 + k * 1024); } while (0)
; #define PG8_LDB(dst, b, h) do { _Pragma("unroll") for (int n = 0; n < 2; ++n) _Pragma("unroll") for (int k = 0; k < 2; ++k) dst[n][k] = *(const LAS bf16x8*)(lds + PG8_SB(b, h) + boff + n * 2048 + k * 1024); } while (0)
; #define PG8_MMA(ai, bj, At, Bt) do { __builtin_amdgcn_s_setprio(1); _Pragma("unroll") for (int m = 0; m < 4; ++m) _Pragma("unroll") for (int n = 0; n < 2; ++n) _Pragma("unroll") for (int k = 0; k < 2; ++k) \
;         acc[ai][bj][m][n] = __builtin_amdgcn_mfma_f32_16x16x32_bf16(Bt[n][k], At[m][k], acc[ai][bj][m][n], 0, 0, 0); __builtin_amdgcn_s_setprio(0); } while (0)
; #define PG8_WAIT_V(n) asm volatile("s_waitcnt vmcnt(" #n ")" ::: "memory")
; #define PG8_WAIT_L(n) asm volatile("s_waitcnt lgkmcnt(" #n ")" ::: "memory")
; #define PG8_BAR __builtin_amdgcn_s_barrier()
; #define PG8_SCHED __builtin_amdgcn_sched_barrier(0)
; template <class Epi>
; __device__ __forceinline__ void gemm_phase(LAS unsigned char* lds, const Gemm g, const StaticOrder& S, const Epi& E) {
;     ...
;             PG8_WAIT_V(8); PG8_WAIT_L(0); PG8_BAR; PG8_MMA(1, 0, At, B0); PG8_MMA(1, 1, At, B1); PG8_BAR; PG8_SCHED;
;             PG8_LDB(B0, 1, 0); PG8_LDB(B1, 1, 1); PG8_SCHED; PG8_LDA(At, 1, 0); PG8_STAGE(PG8_SA(0, 1), a2 + hstepA, voffA);
;             PG8_WAIT_V(8); PG8_WAIT_L(0); PG8_BAR; PG8_MMA(0, 0, At, B0); PG8_MMA(0, 1, At, B1); PG8_BAR; PG8_SCHED;
	s_nop 0
	s_waitcnt lgkmcnt(0)
	v_mfma_f32_16x16x32_bf16 v[62:65], v[150:153], v[182:185], v[62:65]
	v_mfma_f32_16x16x32_bf16 v[58:61], v[158:161], v[182:185], v[58:61]
	v_mfma_f32_16x16x32_bf16 v[46:49], v[150:153], v[190:193], v[46:49]
	v_mfma_f32_16x16x32_bf16 v[42:45], v[158:161], v[190:193], v[42:45]
	v_mfma_f32_16x16x32_bf16 v[30:33], v[150:153], v[200:203], v[30:33]
	v_mfma_f32_16x16x32_bf16 v[26:29], v[158:161], v[200:203], v[26:29]
	v_mfma_f32_16x16x32_bf16 v[14:17], v[150:153], v[208:211], v[14:17]
	v_mfma_f32_16x16x32_bf16 v[10:13], v[158:161], v[208:211], v[10:13]
	v_mfma_f32_16x16x32_bf16 v[62:65], v[154:157], v[186:189], v[62:65]
	v_mfma_f32_16x16x32_bf16 v[58:61], v[162:165], v[186:189], v[58:61]
	v_mfma_f32_16x16x32_bf16 v[46:49], v[154:157], v[196:199], v[46:49]
	v_mfma_f32_16x16x32_bf16 v[42:45], v[162:165], v[196:199], v[42:45]
	v_mfma_f32_16x16x32_bf16 v[30:33], v[154:157], v[204:207], v[30:33]
	v_mfma_f32_16x16x32_bf16 v[26:29], v[162:165], v[204:207], v[26:29]
	v_mfma_f32_16x16x32_bf16 v[14:17], v[154:157], v[212:215], v[14:17]
	v_mfma_f32_16x16x32_bf16 v[10:13], v[162:165], v[212:215], v[10:13]
	s_nop 0
	s_nop 0
	v_mfma_f32_16x16x32_bf16 v[54:57], v[166:169], v[182:185], v[54:57]
	v_mfma_f32_16x16x32_bf16 v[50:53], v[174:177], v[182:185], v[50:53]
	v_mfma_f32_16x16x32_bf16 v[38:41], v[166:169], v[190:193], v[38:41]
	v_mfma_f32_16x16x32_bf16 v[34:37], v[174:177], v[190:193], v[34:37]
	v_mfma_f32_16x16x32_bf16 v[22:25], v[166:169], v[200:203], v[22:25]
	v_mfma_f32_16x16x32_bf16 v[18:21], v[174:177], v[200:203], v[18:21]
	v_mfma_f32_16x16x32_bf16 v[6:9], v[166:169], v[208:211], v[6:9]
	v_mfma_f32_16x16x32_bf16 v[2:5], v[174:177], v[208:211], v[2:5]
	v_mfma_f32_16x16x32_bf16 v[54:57], v[170:173], v[186:189], v[54:57]
	v_mfma_f32_16x16x32_bf16 v[50:53], v[178:181], v[186:189], v[50:53]
	v_mfma_f32_16x16x32_bf16 v[38:41], v[170:173], v[196:199], v[38:41]
	v_mfma_f32_16x16x32_bf16 v[34:37], v[178:181], v[196:199], v[34:37]
	v_mfma_f32_16x16x32_bf16 v[22:25], v[170:173], v[204:207], v[22:25]
	v_mfma_f32_16x16x32_bf16 v[18:21], v[178:181], v[204:207], v[18:21]
	v_mfma_f32_16x16x32_bf16 v[6:9], v[170:173], v[212:215], v[6:9]
	v_mfma_f32_16x16x32_bf16 v[2:5], v[178:181], v[212:215], v[2:5]
	s_nop 0
	s_barrier
	s_add_i32 s82, 0, 0x18000
	v_add_u32_e32 v144, s82, v147
	s_add_i32 s83, 0, 0x1c000
	ds_read_b128 v[150:153], v144
	ds_read_b128 v[154:157], v144 offset:1024
	ds_read_b128 v[158:161], v144 offset:2048
	ds_read_b128 v[162:165], v144 offset:3072
	v_add_u32_e32 v144, s83, v147
	ds_read_b128 v[166:169], v144
	ds_read_b128 v[170:173], v144 offset:1024
	ds_read_b128 v[174:177], v144 offset:2048
	ds_read_b128 v[178:181], v144 offset:3072
	s_add_u32 s48, s78, 0x80000
	s_addc_u32 s49, s79, 0
	s_mov_b32 m0, s60
	v_lshl_add_u64 v[222:223], s[48:49], 0, v[130:131]
	ds_read_b128 v[182:185], v149 offset:32768
	ds_read_b128 v[186:189], v149 offset:33792
	ds_read_b128 v[190:193], v149 offset:34816
	ds_read_b128 v[196:199], v149 offset:35840
	ds_read_b128 v[200:203], v149 offset:36864
	ds_read_b128 v[204:207], v149 offset:37888
	ds_read_b128 v[208:211], v149 offset:38912
	ds_read_b128 v[212:215], v149 offset:39936
	global_load_lds_dwordx4 v[222:223], off
	v_lshl_add_u64 v[222:223], s[48:49], 0, v[134:135]
	s_mov_b32 m0, s61
	s_nop 0
	global_load_lds_dwordx4 v[222:223], off
	s_waitcnt vmcnt(8)
	s_waitcnt lgkmcnt(0)
	s_barrier
	s_nop 0
	s_waitcnt lgkmcnt(0)
	v_mfma_f32_16x16x32_bf16 v[126:129], v[150:153], v[182:185], v[126:129]
	v_mfma_f32_16x16x32_bf16 v[122:125], v[158:161], v[182:185], v[122:125]
	v_mfma_f32_16x16x32_bf16 v[110:113], v[150:153], v[190:193], v[110:113]
	v_mfma_f32_16x16x32_bf16 v[106:109], v[158:161], v[190:193], v[106:109]
	v_mfma_f32_16x16x32_bf16 v[94:97], v[150:153], v[200:203], v[94:97]
	v_mfma_f32_16x16x32_bf16 v[90:93], v[158:161], v[200:203], v[90:93]
	v_mfma_f32_16x16x32_bf16 v[78:81], v[150:153], v[208:211], v[78:81]
	v_mfma_f32_16x16x32_bf16 v[74:77], v[158:161], v[208:211], v[74:77]
	v_mfma_f32_16x16x32_bf16 v[126:129], v[154:157], v[186:189], v[126:129]
	v_mfma_f32_16x16x32_bf16 v[122:125], v[162:165], v[186:189], v[122:125]
	v_mfma_f32_16x16x32_bf16 v[110:113], v[154:157], v[196:199], v[110:113]
	v_mfma_f32_16x16x32_bf16 v[106:109], v[162:165], v[196:199], v[106:109]
	v_mfma_f32_16x16x32_bf16 v[94:97], v[154:157], v[204:207], v[94:97]
	v_mfma_f32_16x16x32_bf16 v[90:93], v[162:165], v[204:207], v[90:93]
	v_mfma_f32_16x16x32_bf16 v[78:81], v[154:157], v[212:215], v[78:81]
	v_mfma_f32_16x16x32_bf16 v[74:77], v[162:165], v[212:215], v[74:77]
	s_nop 0
	s_nop 0
	v_mfma_f32_16x16x32_bf16 v[118:121], v[166:169], v[182:185], v[118:121]
	v_mfma_f32_16x16x32_bf16 v[114:117], v[174:177], v[182:185], v[114:117]
	v_mfma_f32_16x16x32_bf16 v[102:105], v[166:169], v[190:193], v[102:105]
	v_mfma_f32_16x16x32_bf16 v[98:101], v[174:177], v[190:193], v[98:101]
	v_mfma_f32_16x16x32_bf16 v[86:89], v[166:169], v[200:203], v[86:89]
	v_mfma_f32_16x16x32_bf16 v[82:85], v[174:177], v[200:203], v[82:85]
	v_mfma_f32_16x16x32_bf16 v[70:73], v[166:169], v[208:211], v[70:73]
	v_mfma_f32_16x16x32_bf16 v[66:69], v[174:177], v[208:211], v[66:69]
	v_mfma_f32_16x16x32_bf16 v[118:121], v[170:173], v[186:189], v[118:121]
	v_mfma_f32_16x16x32_bf16 v[114:117], v[178:181], v[186:189], v[114:117]
	v_mfma_f32_16x16x32_bf16 v[102:105], v[170:173], v[196:199], v[102:105]
	v_mfma_f32_16x16x32_bf16 v[98:101], v[178:181], v[196:199], v[98:101]
	v_mfma_f32_16x16x32_bf16 v[86:89], v[170:173], v[204:207], v[86:89]
	v_mfma_f32_16x16x32_bf16 v[82:85], v[178:181], v[204:207], v[82:85]
	v_mfma_f32_16x16x32_bf16 v[70:73], v[170:173], v[212:215], v[70:73]
	v_mfma_f32_16x16x32_bf16 v[66:69], v[178:181], v[212:215], v[66:69]
	s_nop 0
	s_barrier
; #define PG8_STAGE(bufoff, gbase, voff) do { _Pragma("unroll") for (int _i = 0; _i < 2; ++_i) \
;         __builtin_amdgcn_global_load_lds((const unsigned*)((const char*)(gbase) + (voff)[_i]), (LAS unsigned*)(lds + (bufoff) + ldsw + _i * 8192), 16, 0, 0); } while (0)
; #define PG8_LDA(dst, b, h) do { _Pragma("unroll") for (int m = 0; m < 4; ++m) _Pragma("unroll") for (int k = 0; k < 2; ++k) dst[m][k] = *(const LAS bf16x8*)(lds + PG8_SA(b, h) + aoff + m * 2048 + k * 1024); } while (0)
; #define PG8_MMA(ai, bj, At, Bt) do { __builtin_amdgcn_s_setprio(1); _Pragma("unroll") for (int m = 0; m < 4; ++m) _Pragma("unroll") for (int n = 0; n < 2; ++n) _Pragma("unroll") for (int k = 0; k < 2; ++k) \
;         acc[ai][bj][m][n] = __builtin_amdgcn_mfma_f32_16x16x32_bf16(Bt[n][k], At[m][k], acc[ai][bj][m][n], 0, 0, 0); __builtin_amdgcn_s_setprio(0); } while (0)
; #define PG8_WAIT_V(n) asm volatile("s_waitcnt vmcnt(" #n ")" ::: "memory")
; #define PG8_WAIT_L(n) asm volatile("s_waitcnt lgkmcnt(" #n ")" ::: "memory")
; #define PG8_BAR __builtin_amdgcn_s_barrier()
; #define PG8_SCHED __builtin_amdgcn_sched_barrier(0)
; template <class Epi>
; __device__ __forceinline__ void gemm_phase(LAS unsigned char* lds, const Gemm g, const StaticOrder& S, const Epi& E) {
;     ...
;             PG8_LDA(At, 1, 1); PG8_STAGE(PG8_SB(1, 0), b3, voffB); PG8_STAGE(PG8_SB(1, 1), b3 + hstepB, voffB); PG8_STAGE(PG8_SA(1, 0), a3, voffA);
;             PG8_WAIT_V(8); PG8_WAIT_L(0); PG8_BAR; PG8_MMA(1, 0, At, B0); PG8_MMA(1, 1, At, B1); PG8_BAR; PG8_SCHED;
;         }
;         if (wr == 0) PG8_BAR;
	s_add_i32 s48, s82, s38
	v_lshl_add_u64 v[142:143], v[142:143], 0, s[64:65]
	s_mov_b32 m0, s48
	ds_read_b128 v[182:185], v149 offset:49152
	ds_read_b128 v[186:189], v149 offset:50176
	ds_read_b128 v[190:193], v149 offset:51200
	ds_read_b128 v[196:199], v149 offset:52224
	ds_read_b128 v[200:203], v149 offset:53248
	ds_read_b128 v[204:207], v149 offset:54272
	ds_read_b128 v[208:211], v149 offset:55296
	ds_read_b128 v[212:215], v149 offset:56320
	global_load_lds_dwordx4 v[142:143], off
	s_add_i32 m0, s48, 0x2000
	s_add_u32 s30, s30, 0x80080
	v_lshl_add_u64 v[142:143], v[216:217], 0, s[64:65]
	s_addc_u32 s31, s31, 0
	s_add_i32 s48, s83, s38
	global_load_lds_dwordx4 v[142:143], off
	v_lshl_add_u64 v[142:143], s[30:31], 0, v[132:133]
	s_mov_b32 m0, s48
	s_nop 0
	global_load_lds_dwordx4 v[142:143], off
	v_lshl_add_u64 v[142:143], s[30:31], 0, v[136:137]
	s_add_i32 m0, s48, 0x2000
	s_nop 0
	global_load_lds_dwordx4 v[142:143], off
	v_lshl_add_u64 v[142:143], v[218:219], 0, s[64:65]
	s_mov_b32 m0, s62
	s_nop 0
	global_load_lds_dwordx4 v[142:143], off
	v_lshl_add_u64 v[142:143], v[220:221], 0, s[64:65]
	s_mov_b32 m0, s63
	s_nop 0
	global_load_lds_dwordx4 v[142:143], off
	s_waitcnt vmcnt(8)
	s_waitcnt lgkmcnt(0)
	s_barrier
	s_nop 0
	s_waitcnt lgkmcnt(0)
	v_mfma_f32_16x16x32_bf16 v[62:65], v[150:153], v[182:185], v[62:65]
	v_mfma_f32_16x16x32_bf16 v[58:61], v[158:161], v[182:185], v[58:61]
	v_mfma_f32_16x16x32_bf16 v[46:49], v[150:153], v[190:193], v[46:49]
	v_mfma_f32_16x16x32_bf16 v[42:45], v[158:161], v[190:193], v[42:45]
	v_mfma_f32_16x16x32_bf16 v[30:33], v[150:153], v[200:203], v[30:33]
	v_mfma_f32_16x16x32_bf16 v[26:29], v[158:161], v[200:203], v[26:29]
	v_mfma_f32_16x16x32_bf16 v[14:17], v[150:153], v[208:211], v[14:17]
	v_mfma_f32_16x16x32_bf16 v[10:13], v[158:161], v[208:211], v[10:13]
	v_mfma_f32_16x16x32_bf16 v[62:65], v[154:157], v[186:189], v[62:65]
	v_mfma_f32_16x16x32_bf16 v[58:61], v[162:165], v[186:189], v[58:61]
	v_mfma_f32_16x16x32_bf16 v[46:49], v[154:157], v[196:199], v[46:49]
	v_mfma_f32_16x16x32_bf16 v[42:45], v[162:165], v[196:199], v[42:45]
	v_mfma_f32_16x16x32_bf16 v[30:33], v[154:157], v[204:207], v[30:33]
	v_mfma_f32_16x16x32_bf16 v[26:29], v[162:165], v[204:207], v[26:29]
	v_mfma_f32_16x16x32_bf16 v[14:17], v[154:157], v[212:215], v[14:17]
	v_mfma_f32_16x16x32_bf16 v[10:13], v[162:165], v[212:215], v[10:13]
	s_nop 0
	s_nop 0
	v_mfma_f32_16x16x32_bf16 v[54:57], v[166:169], v[182:185], v[54:57]
	v_mfma_f32_16x16x32_bf16 v[50:53], v[174:177], v[182:185], v[50:53]
	v_mfma_f32_16x16x32_bf16 v[38:41], v[166:169], v[190:193], v[38:41]
	v_mfma_f32_16x16x32_bf16 v[34:37], v[174:177], v[190:193], v[34:37]
	v_mfma_f32_16x16x32_bf16 v[22:25], v[166:169], v[200:203], v[22:25]
	v_mfma_f32_16x16x32_bf16 v[18:21], v[174:177], v[200:203], v[18:21]
	v_mfma_f32_16x16x32_bf16 v[6:9], v[166:169], v[208:211], v[6:9]
	v_mfma_f32_16x16x32_bf16 v[2:5], v[174:177], v[208:211], v[2:5]
	v_mfma_f32_16x16x32_bf16 v[54:57], v[170:173], v[186:189], v[54:57]
	v_mfma_f32_16x16x32_bf16 v[50:53], v[178:181], v[186:189], v[50:53]
	v_mfma_f32_16x16x32_bf16 v[38:41], v[170:173], v[196:199], v[38:41]
	v_mfma_f32_16x16x32_bf16 v[34:37], v[178:181], v[196:199], v[34:37]
	v_mfma_f32_16x16x32_bf16 v[22:25], v[170:173], v[204:207], v[22:25]
	v_mfma_f32_16x16x32_bf16 v[18:21], v[178:181], v[204:207], v[18:21]
	v_mfma_f32_16x16x32_bf16 v[6:9], v[170:173], v[212:215], v[6:9]
	v_mfma_f32_16x16x32_bf16 v[2:5], v[178:181], v[212:215], v[2:5]
	s_nop 0
	s_barrier
	s_add_i32 s81, s81, 2
	s_add_u32 s26, s26, 0x100
	s_addc_u32 s27, s27, 0
	s_add_u32 s75, s75, 0x100
	s_addc_u32 s80, s80, 0
	s_cmp_gt_u32 s81, 29
	s_cbranch_scc0 .LBB0_1344
	s_and_b64 vcc, exec, s[14:15]
	s_cbranch_vccz .LBB0_1347
	s_barrier

; #define PG8_STAGE(bufoff, gbase, voff) do { _Pragma("unroll") for (int _i = 0; _i < 2; ++_i) \
;         __builtin_amdgcn_global_load_lds((const unsigned*)((const char*)(gbase) + (voff)[_i]), (LAS unsigned*)(lds + (bufoff) + ldsw + _i * 8192), 16, 0, 0); } while (0)
; #define PG8_LDA(dst, b, h) do { _Pragma("unroll") for (int m = 0; m < 4; ++m) _Pragma("unroll") for (int k = 0; k < 2; ++k) dst[m][k] = *(const LAS bf16x8*)(lds + PG8_SA(b, h) + aoff + m * 2048 + k * 1024); } while (0)
; #define PG8_LDB(dst, b, h) do { _Pragma("unroll") for (int n = 0; n < 2; ++n) _Pragma("unroll") for (int k = 0; k < 2; ++k) dst[n][k] = *(const LAS bf16x8*)(lds + PG8_SB(b, h) + boff + n * 2048 + k * 1024); } while (0)
; #define PG8_MMA(ai, bj, At, Bt) do { __builtin_amdgcn_s_setprio(1); _Pragma("unroll") for (int m = 0; m < 4; ++m) _Pragma("unroll") for (int n = 0; n < 2; ++n) _Pragma("unroll") for (int k = 0; k < 2; ++k) \
;         acc[ai][bj][m][n] = __builtin_amdgcn_mfma_f32_16x16x32_bf16(Bt[n][k], At[m][k], acc[ai][bj][m][n], 0, 0, 0); __builtin_amdgcn_s_setprio(0); } while (0)
; #define PG8_WAIT_V(n) asm volatile("s_waitcnt vmcnt(" #n ")" ::: "memory")
; #define PG8_WAIT_L(n) asm volatile("s_waitcnt lgkmcnt(" #n ")" ::: "memory")
; #define PG8_BAR __builtin_amdgcn_s_barrier()
; #define PG8_SCHED __builtin_amdgcn_sched_barrier(0)
; template <class Epi>
; __device__ __forceinline__ void gemm_phase(LAS unsigned char* lds, const Gemm g, const StaticOrder& S, const Epi& E) {
;     ...
;             const bool last = (t == nt - 2);
;             const char* a1 = cA + (size_t)(t + 1) * kstep;
;             const char* a2 = last ? nA : cA + (size_t)(t + 2) * kstep; const char* b2 = last ? nB : cB + (size_t)(t + 2) * kstep;
;             const char* a3 = a2 + kstep; const char* b3 = b2 + kstep;
;             PG8_LDB(B0, 0, 0); PG8_LDB(B1, 0, 1); PG8_SCHED; PG8_LDA(At, 0, 0); PG8_STAGE(PG8_SA(1, 1), a1 + hstepA, voffA);
;             PG8_WAIT_V(8); PG8_WAIT_L(0); PG8_BAR; PG8_MMA(0, 0, At, B0); PG8_MMA(0, 1, At, B1); PG8_BAR; PG8_SCHED;
;             PG8_LDA(At, 0, 1); PG8_STAGE(PG8_SB(0, 0), b2, voffB); PG8_STAGE(PG8_SB(0, 1), b2 + hstepB, voffB); PG8_STAGE(PG8_SA(0, 0), a2, voffA);
.LBB0_1434:
	s_add_u32 s48, s74, 0xffe00080
	s_addc_u32 s49, s75, -1
	s_add_i32 s87, 0, 0x10000
	s_cmpk_eq_i32 s86, 0x7c
	s_cselect_b32 s85, s27, s49
	s_cselect_b32 s84, s62, s48
	s_cselect_b32 s83, s25, s81
	s_cselect_b32 s82, s63, s79
	s_add_i32 s88, 0, 0x14000
	v_add_u32_e32 v134, s87, v236
	v_add_u32_e32 v158, s88, v236
	ds_read_b128 v[122:125], v134
	ds_read_b128 v[126:129], v134 offset:1024
	ds_read_b128 v[130:133], v134 offset:2048
	ds_read_b128 v[134:137], v134 offset:3072
	ds_read_b128 v[146:149], v158
	ds_read_b128 v[150:153], v158 offset:1024
	ds_read_b128 v[154:157], v158 offset:2048
	ds_read_b128 v[158:161], v158 offset:3072
	v_lshl_add_u64 v[208:209], s[74:75], 0, v[200:201]
	s_add_i32 m0, s29, 0xc000
	ds_read_b128 v[162:165], v238
	ds_read_b128 v[166:169], v238 offset:1024
	ds_read_b128 v[170:173], v238 offset:2048
	ds_read_b128 v[174:177], v238 offset:3072
	ds_read_b128 v[178:181], v238 offset:4096
	ds_read_b128 v[182:185], v238 offset:5120
	ds_read_b128 v[196:199], v238 offset:6144
	ds_read_b128 v[204:207], v238 offset:7168
	global_load_lds_dwordx4 v[208:209], off
	v_lshl_add_u64 v[208:209], s[74:75], 0, v[202:203]
	s_add_i32 m0, s29, 0xe000
	s_nop 0
	global_load_lds_dwordx4 v[208:209], off
	s_waitcnt vmcnt(8)
	s_waitcnt lgkmcnt(0)
	s_barrier
	s_nop 0
	s_waitcnt lgkmcnt(0)
	v_mfma_f32_16x16x32_bf16 v[142:145], v[122:125], v[162:165], v[142:145]
	v_mfma_f32_16x16x32_bf16 v[138:141], v[130:133], v[162:165], v[138:141]
	v_mfma_f32_16x16x32_bf16 v[110:113], v[122:125], v[170:173], v[110:113]
	v_mfma_f32_16x16x32_bf16 v[106:109], v[130:133], v[170:173], v[106:109]
	v_mfma_f32_16x16x32_bf16 v[94:97], v[122:125], v[178:181], v[94:97]
	v_mfma_f32_16x16x32_bf16 v[90:93], v[130:133], v[178:181], v[90:93]
	v_mfma_f32_16x16x32_bf16 v[78:81], v[122:125], v[196:199], v[78:81]
	v_mfma_f32_16x16x32_bf16 v[74:77], v[130:133], v[196:199], v[74:77]
	v_mfma_f32_16x16x32_bf16 v[142:145], v[126:129], v[166:169], v[142:145]
	v_mfma_f32_16x16x32_bf16 v[138:141], v[134:137], v[166:169], v[138:141]
	v_mfma_f32_16x16x32_bf16 v[110:113], v[126:129], v[174:177], v[110:113]
	v_mfma_f32_16x16x32_bf16 v[106:109], v[134:137], v[174:177], v[106:109]
	v_mfma_f32_16x16x32_bf16 v[94:97], v[126:129], v[182:185], v[94:97]
	v_mfma_f32_16x16x32_bf16 v[90:93], v[134:137], v[182:185], v[90:93]
	v_mfma_f32_16x16x32_bf16 v[78:81], v[126:129], v[204:207], v[78:81]
	v_mfma_f32_16x16x32_bf16 v[74:77], v[134:137], v[204:207], v[74:77]
	s_nop 0
	s_nop 0
	v_mfma_f32_16x16x32_bf16 v[118:121], v[146:149], v[162:165], v[118:121]
	v_mfma_f32_16x16x32_bf16 v[114:117], v[154:157], v[162:165], v[114:117]
	v_mfma_f32_16x16x32_bf16 v[102:105], v[146:149], v[170:173], v[102:105]
	v_mfma_f32_16x16x32_bf16 v[98:101], v[154:157], v[170:173], v[98:101]
	v_mfma_f32_16x16x32_bf16 v[86:89], v[146:149], v[178:181], v[86:89]
	v_mfma_f32_16x16x32_bf16 v[82:85], v[154:157], v[178:181], v[82:85]
	v_mfma_f32_16x16x32_bf16 v[70:73], v[146:149], v[196:199], v[70:73]
	v_mfma_f32_16x16x32_bf16 v[66:69], v[154:157], v[196:199], v[66:69]
	v_mfma_f32_16x16x32_bf16 v[118:121], v[150:153], v[166:169], v[118:121]
	v_mfma_f32_16x16x32_bf16 v[114:117], v[158:161], v[166:169], v[114:117]
	v_mfma_f32_16x16x32_bf16 v[102:105], v[150:153], v[174:177], v[102:105]
	v_mfma_f32_16x16x32_bf16 v[98:101], v[158:161], v[174:177], v[98:101]
	v_mfma_f32_16x16x32_bf16 v[86:89], v[150:153], v[182:185], v[86:89]
	v_mfma_f32_16x16x32_bf16 v[82:85], v[158:161], v[182:185], v[82:85]
	v_mfma_f32_16x16x32_bf16 v[70:73], v[150:153], v[204:207], v[70:73]
	v_mfma_f32_16x16x32_bf16 v[66:69], v[158:161], v[204:207], v[66:69]
	s_nop 0
	s_barrier
	s_add_i32 s48, s87, s28
	v_lshl_add_u64 v[208:209], s[82:83], 0, v[0:1]
	s_mov_b32 m0, s48
	ds_read_b128 v[162:165], v238 offset:16384
	ds_read_b128 v[166:169], v238 offset:17408
	ds_read_b128 v[170:173], v238 offset:18432
	ds_read_b128 v[174:177], v238 offset:19456
	ds_read_b128 v[178:181], v238 offset:20480
	ds_read_b128 v[182:185], v238 offset:21504
	ds_read_b128 v[196:199], v238 offset:22528
	ds_read_b128 v[204:207], v238 offset:23552
	global_load_lds_dwordx4 v[208:209], off
	s_add_i32 m0, s48, 0x2000
	s_add_u32 s48, s82, 0x200000
	v_lshl_add_u64 v[210:211], s[82:83], 0, v[190:191]
	s_addc_u32 s49, s83, 0
	s_add_i32 s87, s88, s28
	global_load_lds_dwordx4 v[210:211], off
	v_lshl_add_u64 v[212:213], s[48:49], 0, v[0:1]
	s_mov_b32 m0, s87
	v_lshl_add_u64 v[214:215], s[84:85], 0, v[188:189]
	global_load_lds_dwordx4 v[212:213], off
	v_lshl_add_u64 v[212:213], s[48:49], 0, v[190:191]
	s_add_i32 m0, s87, 0x2000
	s_nop 0
	global_load_lds_dwordx4 v[212:213], off
	v_lshl_add_u64 v[212:213], s[84:85], 0, v[186:187]
	s_mov_b32 m0, s29
	s_nop 0
	global_load_lds_dwordx4 v[212:213], off
	s_mov_b32 m0, s34
	s_nop 0
	global_load_lds_dwordx4 v[214:215], off
	s_waitcnt vmcnt(8)
	s_waitcnt lgkmcnt(0)
	s_barrier
; #define PG8_STAGE(bufoff, gbase, voff) do { _Pragma("unroll") for (int _i = 0; _i < 2; ++_i) \
;         __builtin_amdgcn_global_load_lds((const unsigned*)((const char*)(gbase) + (voff)[_i]), (LAS unsigned*)(lds + (bufoff) + ldsw + _i * 8192), 16, 0, 0); } while (0)
; #define PG8_LDA(dst, b, h) do { _Pragma("unroll") for (int m = 0; m < 4; ++m) _Pragma("unroll") for (int k = 0; k < 2; ++k) dst[m][k] = *(const LAS bf16x8*)(lds + PG8_SA(b, h) + aoff + m * 2048 + k * 1024); } while (0)
; #define PG8_LDB(dst, b, h) do { _Pragma("unroll") for (int n = 0; n < 2; ++n) _Pragma("unroll") for (int k = 0; k < 2; ++k) dst[n][k] = *(const LAS bf16x8*)(lds + PG8_SB(b, h) + boff + n * 2048 + k * 1024); } while (0)
; #define PG8_MMA(ai, bj, At, Bt) do { __builtin_amdgcn_s_setprio(1); _Pragma("unroll") for (int m = 0; m < 4; ++m) _Pragma("unroll") for (int n = 0; n < 2; ++n) _Pragma("unroll") for (int k = 0; k < 2; ++k) \
;         acc[ai][bj][m][n] = __builtin_amdgcn_mfma_f32_16x16x32_bf16(Bt[n][k], At[m][k], acc[ai][bj][m][n], 0, 0, 0); __builtin_amdgcn_s_setprio(0); } while (0)
; #define PG8_WAIT_V(n) asm volatile("s_waitcnt vmcnt(" #n ")" ::: "memory")
; #define PG8_WAIT_L(n) asm volatile("s_waitcnt lgkmcnt(" #n ")" ::: "memory")
; #define PG8_BAR __builtin_amdgcn_s_barrier()
; #define PG8_SCHED __builtin_amdgcn_sched_barrier(0)
; template <class Epi>
; __device__ __forceinline__ void gemm_phase(LAS unsigned char* lds, const Gemm g, const StaticOrder& S, const Epi& E) {
;     ...
;             PG8_WAIT_V(8); PG8_WAIT_L(0); PG8_BAR; PG8_MMA(1, 0, At, B0); PG8_MMA(1, 1, At, B1); PG8_BAR; PG8_SCHED;
;             PG8_LDB(B0, 1, 0); PG8_LDB(B1, 1, 1); PG8_SCHED; PG8_LDA(At, 1, 0); PG8_STAGE(PG8_SA(0, 1), a2 + hstepA, voffA);
;             PG8_WAIT_V(8); PG8_WAIT_L(0); PG8_BAR; PG8_MMA(0, 0, At, B0); PG8_MMA(0, 1, At, B1); PG8_BAR; PG8_SCHED;
	s_nop 0
	s_waitcnt lgkmcnt(0)
	v_mfma_f32_16x16x32_bf16 v[62:65], v[122:125], v[162:165], v[62:65]
	v_mfma_f32_16x16x32_bf16 v[58:61], v[130:133], v[162:165], v[58:61]
	v_mfma_f32_16x16x32_bf16 v[46:49], v[122:125], v[170:173], v[46:49]
	v_mfma_f32_16x16x32_bf16 v[42:45], v[130:133], v[170:173], v[42:45]
	v_mfma_f32_16x16x32_bf16 v[30:33], v[122:125], v[178:181], v[30:33]
	v_mfma_f32_16x16x32_bf16 v[26:29], v[130:133], v[178:181], v[26:29]
	v_mfma_f32_16x16x32_bf16 v[14:17], v[122:125], v[196:199], v[14:17]
	v_mfma_f32_16x16x32_bf16 v[10:13], v[130:133], v[196:199], v[10:13]
	v_mfma_f32_16x16x32_bf16 v[62:65], v[126:129], v[166:169], v[62:65]
	v_mfma_f32_16x16x32_bf16 v[58:61], v[134:137], v[166:169], v[58:61]
	v_mfma_f32_16x16x32_bf16 v[46:49], v[126:129], v[174:177], v[46:49]
	v_mfma_f32_16x16x32_bf16 v[42:45], v[134:137], v[174:177], v[42:45]
	v_mfma_f32_16x16x32_bf16 v[30:33], v[126:129], v[182:185], v[30:33]
	v_mfma_f32_16x16x32_bf16 v[26:29], v[134:137], v[182:185], v[26:29]
	v_mfma_f32_16x16x32_bf16 v[14:17], v[126:129], v[204:207], v[14:17]
	v_mfma_f32_16x16x32_bf16 v[10:13], v[134:137], v[204:207], v[10:13]
	s_nop 0
	s_nop 0
	v_mfma_f32_16x16x32_bf16 v[54:57], v[146:149], v[162:165], v[54:57]
	v_mfma_f32_16x16x32_bf16 v[50:53], v[154:157], v[162:165], v[50:53]
	v_mfma_f32_16x16x32_bf16 v[38:41], v[146:149], v[170:173], v[38:41]
	v_mfma_f32_16x16x32_bf16 v[34:37], v[154:157], v[170:173], v[34:37]
	v_mfma_f32_16x16x32_bf16 v[22:25], v[146:149], v[178:181], v[22:25]
	v_mfma_f32_16x16x32_bf16 v[18:21], v[154:157], v[178:181], v[18:21]
	v_mfma_f32_16x16x32_bf16 v[6:9], v[146:149], v[196:199], v[6:9]
	v_mfma_f32_16x16x32_bf16 v[2:5], v[154:157], v[196:199], v[2:5]
	v_mfma_f32_16x16x32_bf16 v[54:57], v[150:153], v[166:169], v[54:57]
	v_mfma_f32_16x16x32_bf16 v[50:53], v[158:161], v[166:169], v[50:53]
	v_mfma_f32_16x16x32_bf16 v[38:41], v[150:153], v[174:177], v[38:41]
	v_mfma_f32_16x16x32_bf16 v[34:37], v[158:161], v[174:177], v[34:37]
	v_mfma_f32_16x16x32_bf16 v[22:25], v[150:153], v[182:185], v[22:25]
	v_mfma_f32_16x16x32_bf16 v[18:21], v[158:161], v[182:185], v[18:21]
	v_mfma_f32_16x16x32_bf16 v[6:9], v[150:153], v[204:207], v[6:9]
	v_mfma_f32_16x16x32_bf16 v[2:5], v[158:161], v[204:207], v[2:5]
	s_nop 0
	s_barrier
	s_add_i32 s87, 0, 0x18000
	s_add_i32 s88, 0, 0x1c000
	v_add_u32_e32 v134, s87, v236
	v_add_u32_e32 v158, s88, v236
	ds_read_b128 v[122:125], v134
	ds_read_b128 v[126:129], v134 offset:1024
	ds_read_b128 v[130:133], v134 offset:2048
	ds_read_b128 v[134:137], v134 offset:3072
	ds_read_b128 v[146:149], v158
	ds_read_b128 v[150:153], v158 offset:1024
	ds_read_b128 v[154:157], v158 offset:2048
	ds_read_b128 v[158:161], v158 offset:3072
	s_add_u32 s48, s84, 0x200000
	s_addc_u32 s49, s85, 0
	s_mov_b32 m0, s38
	v_lshl_add_u64 v[216:217], s[48:49], 0, v[186:187]
	ds_read_b128 v[162:165], v238 offset:32768
	ds_read_b128 v[166:169], v238 offset:33792
	ds_read_b128 v[170:173], v238 offset:34816
	ds_read_b128 v[174:177], v238 offset:35840
	ds_read_b128 v[178:181], v238 offset:36864
	ds_read_b128 v[182:185], v238 offset:37888
	ds_read_b128 v[196:199], v238 offset:38912
	ds_read_b128 v[204:207], v238 offset:39936
	global_load_lds_dwordx4 v[216:217], off
	v_lshl_add_u64 v[216:217], s[48:49], 0, v[188:189]
	s_mov_b32 m0, s39
	s_nop 0
	global_load_lds_dwordx4 v[216:217], off
	s_waitcnt vmcnt(8)
	s_waitcnt lgkmcnt(0)
	s_barrier
	s_nop 0
	s_waitcnt lgkmcnt(0)
	v_mfma_f32_16x16x32_bf16 v[142:145], v[122:125], v[162:165], v[142:145]
	v_mfma_f32_16x16x32_bf16 v[138:141], v[130:133], v[162:165], v[138:141]
	v_mfma_f32_16x16x32_bf16 v[110:113], v[122:125], v[170:173], v[110:113]
	v_mfma_f32_16x16x32_bf16 v[106:109], v[130:133], v[170:173], v[106:109]
	v_mfma_f32_16x16x32_bf16 v[94:97], v[122:125], v[178:181], v[94:97]
	v_mfma_f32_16x16x32_bf16 v[90:93], v[130:133], v[178:181], v[90:93]
	v_mfma_f32_16x16x32_bf16 v[78:81], v[122:125], v[196:199], v[78:81]
	v_mfma_f32_16x16x32_bf16 v[74:77], v[130:133], v[196:199], v[74:77]
	v_mfma_f32_16x16x32_bf16 v[142:145], v[126:129], v[166:169], v[142:145]
	v_mfma_f32_16x16x32_bf16 v[138:141], v[134:137], v[166:169], v[138:141]
	v_mfma_f32_16x16x32_bf16 v[110:113], v[126:129], v[174:177], v[110:113]
	v_mfma_f32_16x16x32_bf16 v[106:109], v[134:137], v[174:177], v[106:109]
	v_mfma_f32_16x16x32_bf16 v[94:97], v[126:129], v[182:185], v[94:97]
	v_mfma_f32_16x16x32_bf16 v[90:93], v[134:137], v[182:185], v[90:93]
	v_mfma_f32_16x16x32_bf16 v[78:81], v[126:129], v[204:207], v[78:81]
	v_mfma_f32_16x16x32_bf16 v[74:77], v[134:137], v[204:207], v[74:77]
	s_nop 0
	s_nop 0
	v_mfma_f32_16x16x32_bf16 v[118:121], v[146:149], v[162:165], v[118:121]
	v_mfma_f32_16x16x32_bf16 v[114:117], v[154:157], v[162:165], v[114:117]
	v_mfma_f32_16x16x32_bf16 v[102:105], v[146:149], v[170:173], v[102:105]
	v_mfma_f32_16x16x32_bf16 v[98:101], v[154:157], v[170:173], v[98:101]
	v_mfma_f32_16x16x32_bf16 v[86:89], v[146:149], v[178:181], v[86:89]
	v_mfma_f32_16x16x32_bf16 v[82:85], v[154:157], v[178:181], v[82:85]
	v_mfma_f32_16x16x32_bf16 v[70:73], v[146:149], v[196:199], v[70:73]
	v_mfma_f32_16x16x32_bf16 v[66:69], v[154:157], v[196:199], v[66:69]
	v_mfma_f32_16x16x32_bf16 v[118:121], v[150:153], v[166:169], v[118:121]
	v_mfma_f32_16x16x32_bf16 v[114:117], v[158:161], v[166:169], v[114:117]
	v_mfma_f32_16x16x32_bf16 v[102:105], v[150:153], v[174:177], v[102:105]
	v_mfma_f32_16x16x32_bf16 v[98:101], v[158:161], v[174:177], v[98:101]
	v_mfma_f32_16x16x32_bf16 v[86:89], v[150:153], v[182:185], v[86:89]
	v_mfma_f32_16x16x32_bf16 v[82:85], v[158:161], v[182:185], v[82:85]
	v_mfma_f32_16x16x32_bf16 v[70:73], v[150:153], v[204:207], v[70:73]
	v_mfma_f32_16x16x32_bf16 v[66:69], v[158:161], v[204:207], v[66:69]
	s_nop 0
	s_barrier
; #define PG8_STAGE(bufoff, gbase, voff) do { _Pragma("unroll") for (int _i = 0; _i < 2; ++_i) \
;         __builtin_amdgcn_global_load_lds((const unsigned*)((const char*)(gbase) + (voff)[_i]), (LAS unsigned*)(lds + (bufoff) + ldsw + _i * 8192), 16, 0, 0); } while (0)
; #define PG8_LDA(dst, b, h) do { _Pragma("unroll") for (int m = 0; m < 4; ++m) _Pragma("unroll") for (int k = 0; k < 2; ++k) dst[m][k] = *(const LAS bf16x8*)(lds + PG8_SA(b, h) + aoff + m * 2048 + k * 1024); } while (0)
; #define PG8_MMA(ai, bj, At, Bt) do { __builtin_amdgcn_s_setprio(1); _Pragma("unroll") for (int m = 0; m < 4; ++m) _Pragma("unroll") for (int n = 0; n < 2; ++n) _Pragma("unroll") for (int k = 0; k < 2; ++k) \
;         acc[ai][bj][m][n] = __builtin_amdgcn_mfma_f32_16x16x32_bf16(Bt[n][k], At[m][k], acc[ai][bj][m][n], 0, 0, 0); __builtin_amdgcn_s_setprio(0); } while (0)
; #define PG8_WAIT_V(n) asm volatile("s_waitcnt vmcnt(" #n ")" ::: "memory")
; #define PG8_WAIT_L(n) asm volatile("s_waitcnt lgkmcnt(" #n ")" ::: "memory")
; #define PG8_BAR __builtin_amdgcn_s_barrier()
; #define PG8_SCHED __builtin_amdgcn_sched_barrier(0)
; template <class Epi>
; __device__ __forceinline__ void gemm_phase(LAS unsigned char* lds, const Gemm g, const StaticOrder& S, const Epi& E) {
;     ...
;             PG8_LDA(At, 1, 1); PG8_STAGE(PG8_SB(1, 0), b3, voffB); PG8_STAGE(PG8_SB(1, 1), b3 + hstepB, voffB); PG8_STAGE(PG8_SA(1, 0), a3, voffA);
;             PG8_WAIT_V(8); PG8_WAIT_L(0); PG8_BAR; PG8_MMA(1, 0, At, B0); PG8_MMA(1, 1, At, B1); PG8_BAR; PG8_SCHED;
;         }
;         if (wr == 0) PG8_BAR;
	s_add_i32 s48, s87, s28
	v_lshl_add_u64 v[208:209], v[208:209], 0, s[64:65]
	s_mov_b32 m0, s48
	ds_read_b128 v[162:165], v238 offset:49152
	ds_read_b128 v[166:169], v238 offset:50176
	ds_read_b128 v[170:173], v238 offset:51200
	ds_read_b128 v[174:177], v238 offset:52224
	ds_read_b128 v[178:181], v238 offset:53248
	ds_read_b128 v[182:185], v238 offset:54272
	ds_read_b128 v[196:199], v238 offset:55296
	ds_read_b128 v[204:207], v238 offset:56320
	global_load_lds_dwordx4 v[208:209], off
	s_add_i32 m0, s48, 0x2000
	s_add_u32 s48, s82, 0x200080
	v_lshl_add_u64 v[208:209], v[210:211], 0, s[64:65]
	s_addc_u32 s49, s83, 0
	s_add_i32 s82, s88, s28
	global_load_lds_dwordx4 v[208:209], off
	v_lshl_add_u64 v[208:209], s[48:49], 0, v[0:1]
	s_mov_b32 m0, s82
	s_nop 0
	global_load_lds_dwordx4 v[208:209], off
	v_lshl_add_u64 v[208:209], s[48:49], 0, v[190:191]
	s_add_i32 m0, s82, 0x2000
	s_nop 0
	global_load_lds_dwordx4 v[208:209], off
	v_lshl_add_u64 v[208:209], v[212:213], 0, s[64:65]
	s_mov_b32 m0, s36
	s_nop 0
	global_load_lds_dwordx4 v[208:209], off
	v_lshl_add_u64 v[208:209], v[214:215], 0, s[64:65]
	s_mov_b32 m0, s43
	s_nop 0
	global_load_lds_dwordx4 v[208:209], off
	s_waitcnt vmcnt(8)
	s_waitcnt lgkmcnt(0)
	s_barrier
	s_nop 0
	s_waitcnt lgkmcnt(0)
	v_mfma_f32_16x16x32_bf16 v[62:65], v[122:125], v[162:165], v[62:65]
	v_mfma_f32_16x16x32_bf16 v[58:61], v[130:133], v[162:165], v[58:61]
	v_mfma_f32_16x16x32_bf16 v[46:49], v[122:125], v[170:173], v[46:49]
	v_mfma_f32_16x16x32_bf16 v[42:45], v[130:133], v[170:173], v[42:45]
	v_mfma_f32_16x16x32_bf16 v[30:33], v[122:125], v[178:181], v[30:33]
	v_mfma_f32_16x16x32_bf16 v[26:29], v[130:133], v[178:181], v[26:29]
	v_mfma_f32_16x16x32_bf16 v[14:17], v[122:125], v[196:199], v[14:17]
	v_mfma_f32_16x16x32_bf16 v[10:13], v[130:133], v[196:199], v[10:13]
	v_mfma_f32_16x16x32_bf16 v[62:65], v[126:129], v[166:169], v[62:65]
	v_mfma_f32_16x16x32_bf16 v[58:61], v[134:137], v[166:169], v[58:61]
	v_mfma_f32_16x16x32_bf16 v[46:49], v[126:129], v[174:177], v[46:49]
	v_mfma_f32_16x16x32_bf16 v[42:45], v[134:137], v[174:177], v[42:45]
	v_mfma_f32_16x16x32_bf16 v[30:33], v[126:129], v[182:185], v[30:33]
	v_mfma_f32_16x16x32_bf16 v[26:29], v[134:137], v[182:185], v[26:29]
	v_mfma_f32_16x16x32_bf16 v[14:17], v[126:129], v[204:207], v[14:17]
	v_mfma_f32_16x16x32_bf16 v[10:13], v[134:137], v[204:207], v[10:13]
	s_nop 0
	s_nop 0
	v_mfma_f32_16x16x32_bf16 v[54:57], v[146:149], v[162:165], v[54:57]
	v_mfma_f32_16x16x32_bf16 v[50:53], v[154:157], v[162:165], v[50:53]
	v_mfma_f32_16x16x32_bf16 v[38:41], v[146:149], v[170:173], v[38:41]
	v_mfma_f32_16x16x32_bf16 v[34:37], v[154:157], v[170:173], v[34:37]
	v_mfma_f32_16x16x32_bf16 v[22:25], v[146:149], v[178:181], v[22:25]
	v_mfma_f32_16x16x32_bf16 v[18:21], v[154:157], v[178:181], v[18:21]
	v_mfma_f32_16x16x32_bf16 v[6:9], v[146:149], v[196:199], v[6:9]
	v_mfma_f32_16x16x32_bf16 v[2:5], v[154:157], v[196:199], v[2:5]
	v_mfma_f32_16x16x32_bf16 v[54:57], v[150:153], v[166:169], v[54:57]
	v_mfma_f32_16x16x32_bf16 v[50:53], v[158:161], v[166:169], v[50:53]
	v_mfma_f32_16x16x32_bf16 v[38:41], v[150:153], v[174:177], v[38:41]
	v_mfma_f32_16x16x32_bf16 v[34:37], v[158:161], v[174:177], v[34:37]
	v_mfma_f32_16x16x32_bf16 v[22:25], v[150:153], v[182:185], v[22:25]
	v_mfma_f32_16x16x32_bf16 v[18:21], v[158:161], v[182:185], v[18:21]
	v_mfma_f32_16x16x32_bf16 v[6:9], v[150:153], v[204:207], v[6:9]
	v_mfma_f32_16x16x32_bf16 v[2:5], v[158:161], v[204:207], v[2:5]
	s_nop 0
	s_barrier
	s_add_i32 s86, s86, 2
	s_add_u32 s74, s74, 0x100
	s_addc_u32 s75, s75, 0
	s_add_u32 s79, s79, 0x100
	s_addc_u32 s81, s81, 0
	s_cmpk_gt_u32 s86, 0x7d
	s_cbranch_scc0 .LBB0_1434
	s_and_b64 vcc, exec, s[22:23]
	s_cbranch_vccz .LBB0_1437
	s_barrier
